# nt hint on weight-conversion f32 loads; removed redundant mid-block setprio pair and post-barrier lgkmcnt wait in the six GEMM K-loops
# speedup vs baseline: 1.0037x; 1.0037x over previous
.LBB0_43:
	s_lshr_b32 s6, s2, 1
	s_and_b32 s12, s3, 0xfe0
	s_and_b32 s6, s6, 0x7c0
	v_or_b32_e32 v2, s12, v8
	v_add_u32_e32 v23, s6, v9
	v_lshlrev_b32_e32 v2, 2, v2
	v_lshl_add_u64 v[24:25], s[4:5], 0, v[2:3]
	v_add_u32_e32 v2, 2, v23
	v_mad_i64_i32 v[28:29], s[14:15], v2, s11, v[24:25]
	v_add_u32_e32 v2, 4, v23
	v_mad_i64_i32 v[30:31], s[14:15], v2, s11, v[24:25]
	v_add_u32_e32 v2, 6, v23
	v_mad_i64_i32 v[32:33], s[14:15], v2, s11, v[24:25]
	v_add_u32_e32 v2, 8, v23
	v_mad_i64_i32 v[34:35], s[14:15], v2, s11, v[24:25]
	v_add_u32_e32 v2, 10, v23
	v_mad_i64_i32 v[36:37], s[14:15], v2, s11, v[24:25]
	v_add_u32_e32 v2, 12, v23
	v_mad_i64_i32 v[26:27], s[14:15], v23, s11, v[24:25]
	v_mad_i64_i32 v[38:39], s[14:15], v2, s11, v[24:25]
	v_add_u32_e32 v2, 14, v23
	v_mad_i64_i32 v[40:41], s[14:15], v2, s11, v[24:25]
	global_load_dword v2, v[26:27], off nt
	global_load_dword v42, v[28:29], off nt
	global_load_dword v43, v[30:31], off nt
	global_load_dword v44, v[32:33], off nt
	global_load_dword v45, v[34:35], off nt
	global_load_dword v46, v[36:37], off nt
	global_load_dword v47, v[38:39], off nt
	global_load_dword v48, v[40:41], off nt
	v_add_u32_e32 v26, 16, v23
	v_mad_i64_i32 v[26:27], s[14:15], v26, s11, v[24:25]
	v_add_u32_e32 v28, 18, v23
	v_add_u32_e32 v30, 20, v23
	v_add_u32_e32 v32, 22, v23
	v_add_u32_e32 v34, 24, v23
	v_add_u32_e32 v36, 26, v23
	v_add_u32_e32 v38, 28, v23
	v_add_u32_e32 v40, 30, v23
	v_mad_i64_i32 v[28:29], s[14:15], v28, s11, v[24:25]
	v_mad_i64_i32 v[30:31], s[14:15], v30, s11, v[24:25]
	v_mad_i64_i32 v[32:33], s[14:15], v32, s11, v[24:25]
	v_mad_i64_i32 v[34:35], s[14:15], v34, s11, v[24:25]
	v_mad_i64_i32 v[36:37], s[14:15], v36, s11, v[24:25]
	v_mad_i64_i32 v[38:39], s[14:15], v38, s11, v[24:25]
	v_mad_i64_i32 v[40:41], s[14:15], v40, s11, v[24:25]
	global_load_dword v49, v[26:27], off nt
	global_load_dword v50, v[28:29], off nt
	global_load_dword v51, v[30:31], off nt
	global_load_dword v52, v[32:33], off nt
	global_load_dword v53, v[34:35], off nt
	global_load_dword v54, v[36:37], off nt
	global_load_dword v55, v[38:39], off nt
	global_load_dword v56, v[40:41], off nt
	v_add_u32_e32 v26, 32, v23
	v_mad_i64_i32 v[26:27], s[14:15], v26, s11, v[24:25]
	v_add_u32_e32 v28, 34, v23
	v_add_u32_e32 v30, 36, v23
	v_add_u32_e32 v32, 38, v23
	v_add_u32_e32 v34, 40, v23
	v_add_u32_e32 v36, 42, v23
	v_add_u32_e32 v38, 44, v23
	v_add_u32_e32 v40, 46, v23
	v_mad_i64_i32 v[28:29], s[14:15], v28, s11, v[24:25]
	v_mad_i64_i32 v[30:31], s[14:15], v30, s11, v[24:25]
	v_mad_i64_i32 v[32:33], s[14:15], v32, s11, v[24:25]
	v_mad_i64_i32 v[34:35], s[14:15], v34, s11, v[24:25]
	v_mad_i64_i32 v[36:37], s[14:15], v36, s11, v[24:25]
	v_mad_i64_i32 v[38:39], s[14:15], v38, s11, v[24:25]
	v_mad_i64_i32 v[40:41], s[14:15], v40, s11, v[24:25]
	global_load_dword v57, v[26:27], off nt
	global_load_dword v58, v[28:29], off nt
	global_load_dword v59, v[30:31], off nt
	global_load_dword v60, v[32:33], off nt
	global_load_dword v61, v[34:35], off nt
	global_load_dword v62, v[36:37], off nt
	global_load_dword v63, v[38:39], off nt
	global_load_dword v64, v[40:41], off nt
	v_add_u32_e32 v26, 48, v23
	v_mad_i64_i32 v[26:27], s[14:15], v26, s11, v[24:25]
	v_add_u32_e32 v28, 50, v23
	v_add_u32_e32 v30, 52, v23
	v_add_u32_e32 v32, 54, v23
	v_add_u32_e32 v34, 56, v23
	v_add_u32_e32 v36, 58, v23
	v_add_u32_e32 v38, 60, v23
	v_add_u32_e32 v23, 62, v23
	v_mad_i64_i32 v[28:29], s[14:15], v28, s11, v[24:25]
	v_mad_i64_i32 v[30:31], s[14:15], v30, s11, v[24:25]
	v_mad_i64_i32 v[32:33], s[14:15], v32, s11, v[24:25]
	v_mad_i64_i32 v[34:35], s[14:15], v34, s11, v[24:25]
	v_mad_i64_i32 v[36:37], s[14:15], v36, s11, v[24:25]
	v_mad_i64_i32 v[38:39], s[14:15], v38, s11, v[24:25]
	v_mad_i64_i32 v[24:25], s[14:15], v23, s11, v[24:25]
	global_load_dword v23, v[26:27], off nt
	global_load_dword v40, v[28:29], off nt
	global_load_dword v41, v[30:31], off nt
	global_load_dword v65, v[32:33], off nt
	global_load_dword v66, v[34:35], off nt
	global_load_dword v67, v[36:37], off nt
	global_load_dword v68, v[38:39], off nt
	global_load_dword v69, v[24:25], off nt
	s_waitcnt vmcnt(30)
	ds_write2_b32 v15, v2, v42 offset1:66
	s_waitcnt vmcnt(28)
	ds_write2_b32 v15, v43, v44 offset0:132 offset1:198
	s_waitcnt vmcnt(26)
	ds_write2_b32 v16, v45, v46 offset0:8 offset1:74
	s_waitcnt vmcnt(24)
	ds_write2_b32 v16, v47, v48 offset0:140 offset1:206
	s_waitcnt vmcnt(22)
	ds_write2_b32 v17, v49, v50 offset0:16 offset1:82
	s_waitcnt vmcnt(20)
	ds_write2_b32 v17, v51, v52 offset0:148 offset1:214
	s_waitcnt vmcnt(18)
	ds_write2_b32 v18, v53, v54 offset0:24 offset1:90
	s_waitcnt vmcnt(16)
	ds_write2_b32 v18, v55, v56 offset0:156 offset1:222
	s_waitcnt vmcnt(14)
	ds_write2_b32 v19, v57, v58 offset0:32 offset1:98
	s_waitcnt vmcnt(12)
	ds_write2_b32 v19, v59, v60 offset0:164 offset1:230
	s_waitcnt vmcnt(10)
	ds_write2_b32 v20, v61, v62 offset0:40 offset1:106
	s_waitcnt vmcnt(8)
	ds_write2_b32 v20, v63, v64 offset0:172 offset1:238
	s_waitcnt vmcnt(6)
	ds_write2_b32 v21, v23, v40 offset0:48 offset1:114
	s_waitcnt vmcnt(4)
	ds_write2_b32 v21, v41, v65 offset0:180 offset1:246
	s_waitcnt vmcnt(2)
	ds_write2_b32 v22, v66, v67 offset0:56 offset1:122
	s_waitcnt vmcnt(0)
	ds_write2_b32 v22, v68, v69 offset0:188 offset1:254
	s_waitcnt lgkmcnt(0)
	v_mov_b32 v2, 0
	ds_read2_b32 v[28:29], v11 offset0:33 offset1:41
	ds_read2_b32 v[30:31], v11 offset1:8
	ds_read2_b32 v[32:33], v11 offset0:66 offset1:74
	ds_read2_b32 v[34:35], v11 offset0:99 offset1:107
	ds_read2_b32 v[36:37], v11 offset0:132 offset1:140
	ds_read2_b32 v[38:39], v11 offset0:165 offset1:173
	ds_read2_b32 v[40:41], v11 offset0:198 offset1:206
	ds_read2_b32 v[42:43], v11 offset0:231 offset1:239
	v_add_u32_e32 v46, s12, v10
	s_lshl_b32 s6, s6, 1
	v_ashrrev_i32_e32 v47, 31, v46
	v_lshl_add_u64 v[44:45], v[4:5], 0, s[6:7]
	v_lshlrev_b64 v[46:47], 12, v[46:47]
	s_waitcnt lgkmcnt(6)
	v_cvt_pk_bf16_f32 v24, v30, v28
	v_lshl_add_u64 v[46:47], v[44:45], 0, v[46:47]
	v_add_u32_e32 v28, s12, v12
	s_waitcnt lgkmcnt(4)
	v_cvt_pk_bf16_f32 v25, v32, v34
	s_waitcnt lgkmcnt(2)
	v_cvt_pk_bf16_f32 v26, v36, v38
	s_waitcnt lgkmcnt(0)
	v_cvt_pk_bf16_f32 v27, v40, v42
	global_store_dwordx4 v[46:47], v[24:27], off
	s_nop 1
	v_cvt_pk_bf16_f32 v24, v31, v29
	v_ashrrev_i32_e32 v29, 31, v28
	v_lshlrev_b64 v[28:29], 12, v[28:29]
	v_cvt_pk_bf16_f32 v25, v33, v35
	v_cvt_pk_bf16_f32 v26, v37, v39
	v_cvt_pk_bf16_f32 v27, v41, v43
	v_lshl_add_u64 v[28:29], v[44:45], 0, v[28:29]
	ds_read2_b32 v[30:31], v11 offset0:16 offset1:24
	ds_read2_b32 v[32:33], v11 offset0:49 offset1:57
	ds_read2_b32 v[34:35], v11 offset0:82 offset1:90
	ds_read2_b32 v[36:37], v11 offset0:115 offset1:123
	ds_read2_b32 v[38:39], v11 offset0:148 offset1:156
	ds_read2_b32 v[40:41], v11 offset0:181 offset1:189
	ds_read2_b32 v[42:43], v11 offset0:214 offset1:222
	ds_read2_b32 v[46:47], v11 offset0:247 offset1:255
	global_store_dwordx4 v[28:29], v[24:27], off
	v_add_u32_e32 v28, s12, v13
	v_ashrrev_i32_e32 v29, 31, v28
	v_lshlrev_b64 v[28:29], 12, v[28:29]
	v_lshl_add_u64 v[28:29], v[44:45], 0, v[28:29]
	s_waitcnt lgkmcnt(6)
	v_cvt_pk_bf16_f32 v24, v30, v32
	s_waitcnt lgkmcnt(4)
	v_cvt_pk_bf16_f32 v25, v34, v36
	s_waitcnt lgkmcnt(2)
	v_cvt_pk_bf16_f32 v26, v38, v40
	s_waitcnt lgkmcnt(0)
	v_cvt_pk_bf16_f32 v27, v42, v46
	global_store_dwordx4 v[28:29], v[24:27], off
	v_add_u32_e32 v28, s12, v14
	v_ashrrev_i32_e32 v29, 31, v28
	v_lshlrev_b64 v[28:29], 12, v[28:29]
	v_lshl_add_u64 v[28:29], v[44:45], 0, v[28:29]
	v_cvt_pk_bf16_f32 v24, v31, v33
	v_cvt_pk_bf16_f32 v25, v35, v37
	v_cvt_pk_bf16_f32 v26, v39, v41
	v_cvt_pk_bf16_f32 v27, v43, v47
	global_store_dwordx4 v[28:29], v[24:27], off
	s_waitcnt lgkmcnt(0)
	s_cmpk_lt_i32 s2, 0x1000
	s_cbranch_scc1 .LBB0_40
.LBB0_44:
	s_add_i32 s12, s3, 0xfffe0000
	s_and_b32 s12, s12, 0x7e0
	s_add_i32 s6, s2, 0xfffff000
	v_or_b32_e32 v2, s12, v8
	s_andn2_b32 s6, s6, 63
	v_lshlrev_b32_e32 v2, 2, v2
	v_add_u32_e32 v23, s6, v9
	v_lshl_add_u64 v[24:25], s[4:5], 0, v[2:3]
	v_lshl_add_u64 v[24:25], v[24:25], 0, s[8:9]
	v_add_u32_e32 v2, 2, v23
	v_mad_i64_i32 v[28:29], s[14:15], v2, s11, v[24:25]
	v_add_u32_e32 v2, 4, v23
	v_mad_i64_i32 v[30:31], s[14:15], v2, s11, v[24:25]
	v_add_u32_e32 v2, 6, v23
	v_mad_i64_i32 v[32:33], s[14:15], v2, s11, v[24:25]
	v_add_u32_e32 v2, 8, v23
	v_mad_i64_i32 v[34:35], s[14:15], v2, s11, v[24:25]
	v_add_u32_e32 v2, 10, v23
	v_mad_i64_i32 v[36:37], s[14:15], v2, s11, v[24:25]
	v_add_u32_e32 v2, 12, v23
	v_mad_i64_i32 v[26:27], s[14:15], v23, s11, v[24:25]
	v_mad_i64_i32 v[38:39], s[14:15], v2, s11, v[24:25]
	v_add_u32_e32 v2, 14, v23
	v_mad_i64_i32 v[40:41], s[14:15], v2, s11, v[24:25]
	global_load_dword v2, v[26:27], off nt
	global_load_dword v42, v[28:29], off nt
	global_load_dword v43, v[30:31], off nt
	global_load_dword v44, v[32:33], off nt
	global_load_dword v45, v[34:35], off nt
	global_load_dword v46, v[36:37], off nt
	global_load_dword v47, v[38:39], off nt
	global_load_dword v48, v[40:41], off nt
	v_add_u32_e32 v26, 16, v23
	v_mad_i64_i32 v[26:27], s[14:15], v26, s11, v[24:25]
	v_add_u32_e32 v28, 18, v23
	v_add_u32_e32 v30, 20, v23
	v_add_u32_e32 v32, 22, v23
	v_add_u32_e32 v34, 24, v23
	v_add_u32_e32 v36, 26, v23
	v_add_u32_e32 v38, 28, v23
	v_add_u32_e32 v40, 30, v23
	v_mad_i64_i32 v[28:29], s[14:15], v28, s11, v[24:25]
	v_mad_i64_i32 v[30:31], s[14:15], v30, s11, v[24:25]
	v_mad_i64_i32 v[32:33], s[14:15], v32, s11, v[24:25]
	v_mad_i64_i32 v[34:35], s[14:15], v34, s11, v[24:25]
	v_mad_i64_i32 v[36:37], s[14:15], v36, s11, v[24:25]
	v_mad_i64_i32 v[38:39], s[14:15], v38, s11, v[24:25]
	v_mad_i64_i32 v[40:41], s[14:15], v40, s11, v[24:25]
	global_load_dword v49, v[26:27], off nt
	global_load_dword v50, v[28:29], off nt
	global_load_dword v51, v[30:31], off nt
	global_load_dword v52, v[32:33], off nt
	global_load_dword v53, v[34:35], off nt
	global_load_dword v54, v[36:37], off nt
	global_load_dword v55, v[38:39], off nt
	global_load_dword v56, v[40:41], off nt
	v_add_u32_e32 v26, 32, v23
	v_mad_i64_i32 v[26:27], s[14:15], v26, s11, v[24:25]
	v_add_u32_e32 v28, 34, v23
	v_add_u32_e32 v30, 36, v23
	v_add_u32_e32 v32, 38, v23
	v_add_u32_e32 v34, 40, v23
	v_add_u32_e32 v36, 42, v23
	v_add_u32_e32 v38, 44, v23
	v_add_u32_e32 v40, 46, v23
	v_mad_i64_i32 v[28:29], s[14:15], v28, s11, v[24:25]
	v_mad_i64_i32 v[30:31], s[14:15], v30, s11, v[24:25]
	v_mad_i64_i32 v[32:33], s[14:15], v32, s11, v[24:25]
	v_mad_i64_i32 v[34:35], s[14:15], v34, s11, v[24:25]
	v_mad_i64_i32 v[36:37], s[14:15], v36, s11, v[24:25]
	v_mad_i64_i32 v[38:39], s[14:15], v38, s11, v[24:25]
	v_mad_i64_i32 v[40:41], s[14:15], v40, s11, v[24:25]
	global_load_dword v57, v[26:27], off nt
	global_load_dword v58, v[28:29], off nt
	global_load_dword v59, v[30:31], off nt
	global_load_dword v60, v[32:33], off nt
	global_load_dword v61, v[34:35], off nt
	global_load_dword v62, v[36:37], off nt
	global_load_dword v63, v[38:39], off nt
	global_load_dword v64, v[40:41], off nt
	v_add_u32_e32 v26, 48, v23
	v_mad_i64_i32 v[26:27], s[14:15], v26, s11, v[24:25]
	v_add_u32_e32 v28, 50, v23
	v_add_u32_e32 v30, 52, v23
	v_add_u32_e32 v32, 54, v23
	v_add_u32_e32 v34, 56, v23
	v_add_u32_e32 v36, 58, v23
	v_add_u32_e32 v38, 60, v23
	v_add_u32_e32 v23, 62, v23
	v_mad_i64_i32 v[28:29], s[14:15], v28, s11, v[24:25]
	v_mad_i64_i32 v[30:31], s[14:15], v30, s11, v[24:25]
	v_mad_i64_i32 v[32:33], s[14:15], v32, s11, v[24:25]
	v_mad_i64_i32 v[34:35], s[14:15], v34, s11, v[24:25]
	v_mad_i64_i32 v[36:37], s[14:15], v36, s11, v[24:25]
	v_mad_i64_i32 v[38:39], s[14:15], v38, s11, v[24:25]
	v_mad_i64_i32 v[24:25], s[14:15], v23, s11, v[24:25]
	global_load_dword v23, v[26:27], off nt
	global_load_dword v40, v[28:29], off nt
	global_load_dword v41, v[30:31], off nt
	global_load_dword v65, v[32:33], off nt
	global_load_dword v66, v[34:35], off nt
	global_load_dword v67, v[36:37], off nt
	global_load_dword v68, v[38:39], off nt
	global_load_dword v69, v[24:25], off nt
	s_waitcnt vmcnt(30)
	ds_write2_b32 v15, v2, v42 offset1:66
	s_waitcnt vmcnt(28)
	ds_write2_b32 v15, v43, v44 offset0:132 offset1:198
	s_waitcnt vmcnt(26)
	ds_write2_b32 v16, v45, v46 offset0:8 offset1:74
	s_waitcnt vmcnt(24)
	ds_write2_b32 v16, v47, v48 offset0:140 offset1:206
	s_waitcnt vmcnt(22)
	ds_write2_b32 v17, v49, v50 offset0:16 offset1:82
	s_waitcnt vmcnt(20)
	ds_write2_b32 v17, v51, v52 offset0:148 offset1:214
	s_waitcnt vmcnt(18)
	ds_write2_b32 v18, v53, v54 offset0:24 offset1:90
	s_waitcnt vmcnt(16)
	ds_write2_b32 v18, v55, v56 offset0:156 offset1:222
	s_waitcnt vmcnt(14)
	ds_write2_b32 v19, v57, v58 offset0:32 offset1:98
	s_waitcnt vmcnt(12)
	ds_write2_b32 v19, v59, v60 offset0:164 offset1:230
	s_waitcnt vmcnt(10)
	ds_write2_b32 v20, v61, v62 offset0:40 offset1:106
	s_waitcnt vmcnt(8)
	ds_write2_b32 v20, v63, v64 offset0:172 offset1:238
	s_waitcnt vmcnt(6)
	ds_write2_b32 v21, v23, v40 offset0:48 offset1:114
	s_waitcnt vmcnt(4)
	ds_write2_b32 v21, v41, v65 offset0:180 offset1:246
	s_waitcnt vmcnt(2)
	ds_write2_b32 v22, v66, v67 offset0:56 offset1:122
	s_waitcnt vmcnt(0)
	ds_write2_b32 v22, v68, v69 offset0:188 offset1:254
	s_waitcnt lgkmcnt(0)
	v_mov_b32 v2, 0
	ds_read2_b32 v[28:29], v11 offset0:33 offset1:41
	ds_read2_b32 v[30:31], v11 offset1:8
	ds_read2_b32 v[32:33], v11 offset0:66 offset1:74
	ds_read2_b32 v[34:35], v11 offset0:99 offset1:107
	ds_read2_b32 v[36:37], v11 offset0:132 offset1:140
	ds_read2_b32 v[38:39], v11 offset0:165 offset1:173
	ds_read2_b32 v[40:41], v11 offset0:198 offset1:206
	ds_read2_b32 v[42:43], v11 offset0:231 offset1:239
	v_add_u32_e32 v46, s12, v10
	v_ashrrev_i32_e32 v47, 31, v46
	v_lshl_add_u64 v[44:45], s[6:7], 1, v[6:7]
	v_lshlrev_b64 v[46:47], 12, v[46:47]
	s_waitcnt lgkmcnt(6)
	v_cvt_pk_bf16_f32 v24, v30, v28
	v_lshl_add_u64 v[46:47], v[44:45], 0, v[46:47]
	v_add_u32_e32 v28, s12, v12
	s_waitcnt lgkmcnt(4)
	v_cvt_pk_bf16_f32 v25, v32, v34
	s_waitcnt lgkmcnt(2)
	v_cvt_pk_bf16_f32 v26, v36, v38
	s_waitcnt lgkmcnt(0)
	v_cvt_pk_bf16_f32 v27, v40, v42
	global_store_dwordx4 v[46:47], v[24:27], off
	s_nop 1
	v_cvt_pk_bf16_f32 v24, v31, v29
	v_ashrrev_i32_e32 v29, 31, v28
	v_lshlrev_b64 v[28:29], 12, v[28:29]
	v_cvt_pk_bf16_f32 v25, v33, v35
	v_cvt_pk_bf16_f32 v26, v37, v39
	v_cvt_pk_bf16_f32 v27, v41, v43
	v_lshl_add_u64 v[28:29], v[44:45], 0, v[28:29]
	ds_read2_b32 v[30:31], v11 offset0:16 offset1:24
	ds_read2_b32 v[32:33], v11 offset0:49 offset1:57
	ds_read2_b32 v[34:35], v11 offset0:82 offset1:90
	ds_read2_b32 v[36:37], v11 offset0:115 offset1:123
	ds_read2_b32 v[38:39], v11 offset0:148 offset1:156
	ds_read2_b32 v[40:41], v11 offset0:181 offset1:189
	ds_read2_b32 v[42:43], v11 offset0:214 offset1:222
	ds_read2_b32 v[46:47], v11 offset0:247 offset1:255
	global_store_dwordx4 v[28:29], v[24:27], off
	v_add_u32_e32 v28, s12, v13
	v_ashrrev_i32_e32 v29, 31, v28
	v_lshlrev_b64 v[28:29], 12, v[28:29]
	v_lshl_add_u64 v[28:29], v[44:45], 0, v[28:29]
	s_waitcnt lgkmcnt(6)
	v_cvt_pk_bf16_f32 v24, v30, v32
	s_waitcnt lgkmcnt(4)
	v_cvt_pk_bf16_f32 v25, v34, v36
	s_waitcnt lgkmcnt(2)
	v_cvt_pk_bf16_f32 v26, v38, v40
	s_waitcnt lgkmcnt(0)
	v_cvt_pk_bf16_f32 v27, v42, v46
	global_store_dwordx4 v[28:29], v[24:27], off
	v_add_u32_e32 v28, s12, v14
	v_ashrrev_i32_e32 v29, 31, v28
	v_lshlrev_b64 v[28:29], 12, v[28:29]
	v_lshl_add_u64 v[28:29], v[44:45], 0, v[28:29]
	v_cvt_pk_bf16_f32 v24, v31, v33
	v_cvt_pk_bf16_f32 v25, v35, v37
	v_cvt_pk_bf16_f32 v26, v39, v41
	v_cvt_pk_bf16_f32 v27, v43, v47
	global_store_dwordx4 v[28:29], v[24:27], off
	s_waitcnt lgkmcnt(0)
	s_branch .LBB0_40

.LBB0_67:
	s_add_u32 s34, s6, 0xfff80080
	s_addc_u32 s35, s7, -1
	s_add_i32 s53, 0, 0x10000
	s_cmp_eq_u32 s52, 28
	s_cselect_b32 s37, s25, s35
	s_cselect_b32 s36, s29, s34
	s_cselect_b32 s35, s23, s51
	s_cselect_b32 s34, s49, s50
	s_add_i32 s56, 0, 0x14000
	v_add_u32_e32 v142, s53, v187
	v_add_u32_e32 v158, s56, v187
	ds_read_b128 v[130:133], v142
	ds_read_b128 v[134:137], v142 offset:1024
	ds_read_b128 v[138:141], v142 offset:2048
	ds_read_b128 v[142:145], v142 offset:3072
	ds_read_b128 v[146:149], v158
	ds_read_b128 v[150:153], v158 offset:1024
	ds_read_b128 v[154:157], v158 offset:2048
	ds_read_b128 v[158:161], v158 offset:3072
	v_lshl_add_u64 v[184:185], s[6:7], 0, v[168:169]
	s_add_i32 m0, s43, 0xc000
	ds_read_b128 v[172:175], v199
	ds_read_b128 v[178:181], v199 offset:1024
	ds_read_b128 v[188:191], v199 offset:2048
	ds_read_b128 v[200:203], v199 offset:3072
	ds_read_b128 v[204:207], v199 offset:4096
	ds_read_b128 v[216:219], v199 offset:5120
	ds_read_b128 v[220:223], v199 offset:6144
	ds_read_b128 v[224:227], v199 offset:7168
	global_load_lds_dwordx4 v[184:185], off
	v_lshl_add_u64 v[184:185], s[6:7], 0, v[170:171]
	s_add_i32 m0, s43, 0xe000
	s_nop 0
	global_load_lds_dwordx4 v[184:185], off
	s_waitcnt vmcnt(8)
	s_waitcnt lgkmcnt(0)
	s_barrier
	s_setprio 1
	v_mfma_f32_16x16x32_bf16 v[126:129], v[130:133], v[172:175], v[126:129]
	v_mfma_f32_16x16x32_bf16 v[122:125], v[138:141], v[172:175], v[122:125]
	v_mfma_f32_16x16x32_bf16 v[110:113], v[130:133], v[188:191], v[110:113]
	v_mfma_f32_16x16x32_bf16 v[106:109], v[138:141], v[188:191], v[106:109]
	v_mfma_f32_16x16x32_bf16 v[98:101], v[130:133], v[204:207], v[98:101]
	v_mfma_f32_16x16x32_bf16 v[90:93], v[138:141], v[204:207], v[90:93]
	v_mfma_f32_16x16x32_bf16 v[82:85], v[130:133], v[220:223], v[82:85]
	v_mfma_f32_16x16x32_bf16 v[74:77], v[138:141], v[220:223], v[74:77]
	v_mfma_f32_16x16x32_bf16 v[126:129], v[134:137], v[178:181], v[126:129]
	v_mfma_f32_16x16x32_bf16 v[122:125], v[142:145], v[178:181], v[122:125]
	v_mfma_f32_16x16x32_bf16 v[110:113], v[134:137], v[200:203], v[110:113]
	v_mfma_f32_16x16x32_bf16 v[106:109], v[142:145], v[200:203], v[106:109]
	v_mfma_f32_16x16x32_bf16 v[98:101], v[134:137], v[216:219], v[98:101]
	v_mfma_f32_16x16x32_bf16 v[90:93], v[142:145], v[216:219], v[90:93]
	v_mfma_f32_16x16x32_bf16 v[82:85], v[134:137], v[224:227], v[82:85]
	v_mfma_f32_16x16x32_bf16 v[74:77], v[142:145], v[224:227], v[74:77]
	v_mfma_f32_16x16x32_bf16 v[118:121], v[146:149], v[172:175], v[118:121]
	v_mfma_f32_16x16x32_bf16 v[114:117], v[154:157], v[172:175], v[114:117]
	v_mfma_f32_16x16x32_bf16 v[102:105], v[146:149], v[188:191], v[102:105]
	v_mfma_f32_16x16x32_bf16 v[94:97], v[154:157], v[188:191], v[94:97]
	v_mfma_f32_16x16x32_bf16 v[86:89], v[146:149], v[204:207], v[86:89]
	v_mfma_f32_16x16x32_bf16 v[78:81], v[154:157], v[204:207], v[78:81]
	v_mfma_f32_16x16x32_bf16 v[70:73], v[146:149], v[220:223], v[70:73]
	v_mfma_f32_16x16x32_bf16 v[66:69], v[154:157], v[220:223], v[66:69]
	v_mfma_f32_16x16x32_bf16 v[118:121], v[150:153], v[178:181], v[118:121]
	v_mfma_f32_16x16x32_bf16 v[114:117], v[158:161], v[178:181], v[114:117]
	v_mfma_f32_16x16x32_bf16 v[102:105], v[150:153], v[200:203], v[102:105]
	v_mfma_f32_16x16x32_bf16 v[94:97], v[158:161], v[200:203], v[94:97]
	v_mfma_f32_16x16x32_bf16 v[86:89], v[150:153], v[216:219], v[86:89]
	v_mfma_f32_16x16x32_bf16 v[78:81], v[158:161], v[216:219], v[78:81]
	v_mfma_f32_16x16x32_bf16 v[70:73], v[150:153], v[224:227], v[70:73]
	v_mfma_f32_16x16x32_bf16 v[66:69], v[158:161], v[224:227], v[66:69]
	s_setprio 0
	s_barrier
	s_add_i32 s53, s53, s42
	v_lshl_add_u64 v[184:185], s[34:35], 0, v[210:211]
	s_mov_b32 m0, s53
	ds_read_b128 v[172:175], v199 offset:16384
	ds_read_b128 v[178:181], v199 offset:17408
	ds_read_b128 v[188:191], v199 offset:18432
	ds_read_b128 v[200:203], v199 offset:19456
	ds_read_b128 v[204:207], v199 offset:20480
	ds_read_b128 v[216:219], v199 offset:21504
	ds_read_b128 v[220:223], v199 offset:22528
	ds_read_b128 v[224:227], v199 offset:23552
	global_load_lds_dwordx4 v[184:185], off
	s_add_i32 m0, s53, 0x2000
	s_add_u32 s54, s34, 0x80000
	v_lshl_add_u64 v[192:193], s[34:35], 0, v[162:163]
	s_addc_u32 s55, s35, 0
	s_add_i32 s53, s56, s42
	global_load_lds_dwordx4 v[192:193], off
	v_lshl_add_u64 v[196:197], s[54:55], 0, v[210:211]
	s_mov_b32 m0, s53
	v_lshl_add_u64 v[208:209], s[36:37], 0, v[164:165]
	global_load_lds_dwordx4 v[196:197], off
	v_lshl_add_u64 v[196:197], s[54:55], 0, v[162:163]
	s_add_i32 m0, s53, 0x2000
	s_nop 0
	global_load_lds_dwordx4 v[196:197], off
	v_lshl_add_u64 v[196:197], s[36:37], 0, v[166:167]
	s_mov_b32 m0, s43
	s_nop 0
	global_load_lds_dwordx4 v[196:197], off
	s_mov_b32 m0, s44
	s_nop 0
	global_load_lds_dwordx4 v[208:209], off
	s_waitcnt vmcnt(8)
	s_waitcnt lgkmcnt(0)
	s_barrier
	s_setprio 1
	v_mfma_f32_16x16x32_bf16 v[62:65], v[130:133], v[172:175], v[62:65]
	v_mfma_f32_16x16x32_bf16 v[58:61], v[138:141], v[172:175], v[58:61]
	v_mfma_f32_16x16x32_bf16 v[50:53], v[130:133], v[188:191], v[50:53]
	v_mfma_f32_16x16x32_bf16 v[42:45], v[138:141], v[188:191], v[42:45]
	v_mfma_f32_16x16x32_bf16 v[34:37], v[130:133], v[204:207], v[34:37]
	v_mfma_f32_16x16x32_bf16 v[26:29], v[138:141], v[204:207], v[26:29]
	v_mfma_f32_16x16x32_bf16 v[14:17], v[130:133], v[220:223], v[14:17]
	v_mfma_f32_16x16x32_bf16 v[10:13], v[138:141], v[220:223], v[10:13]
	v_mfma_f32_16x16x32_bf16 v[62:65], v[134:137], v[178:181], v[62:65]
	v_mfma_f32_16x16x32_bf16 v[58:61], v[142:145], v[178:181], v[58:61]
	v_mfma_f32_16x16x32_bf16 v[50:53], v[134:137], v[200:203], v[50:53]
	v_mfma_f32_16x16x32_bf16 v[42:45], v[142:145], v[200:203], v[42:45]
	v_mfma_f32_16x16x32_bf16 v[34:37], v[134:137], v[216:219], v[34:37]
	v_mfma_f32_16x16x32_bf16 v[26:29], v[142:145], v[216:219], v[26:29]
	v_mfma_f32_16x16x32_bf16 v[14:17], v[134:137], v[224:227], v[14:17]
	v_mfma_f32_16x16x32_bf16 v[10:13], v[142:145], v[224:227], v[10:13]
	v_mfma_f32_16x16x32_bf16 v[54:57], v[146:149], v[172:175], v[54:57]
	v_mfma_f32_16x16x32_bf16 v[46:49], v[154:157], v[172:175], v[46:49]
	v_mfma_f32_16x16x32_bf16 v[38:41], v[146:149], v[188:191], v[38:41]
	v_mfma_f32_16x16x32_bf16 v[30:33], v[154:157], v[188:191], v[30:33]
	v_mfma_f32_16x16x32_bf16 v[22:25], v[146:149], v[204:207], v[22:25]
	v_mfma_f32_16x16x32_bf16 v[18:21], v[154:157], v[204:207], v[18:21]
	v_mfma_f32_16x16x32_bf16 v[6:9], v[146:149], v[220:223], v[6:9]
	v_mfma_f32_16x16x32_bf16 v[2:5], v[154:157], v[220:223], v[2:5]
	v_mfma_f32_16x16x32_bf16 v[54:57], v[150:153], v[178:181], v[54:57]
	v_mfma_f32_16x16x32_bf16 v[46:49], v[158:161], v[178:181], v[46:49]
	v_mfma_f32_16x16x32_bf16 v[38:41], v[150:153], v[200:203], v[38:41]
	v_mfma_f32_16x16x32_bf16 v[30:33], v[158:161], v[200:203], v[30:33]
	v_mfma_f32_16x16x32_bf16 v[22:25], v[150:153], v[216:219], v[22:25]
	v_mfma_f32_16x16x32_bf16 v[18:21], v[158:161], v[216:219], v[18:21]
	v_mfma_f32_16x16x32_bf16 v[6:9], v[150:153], v[224:227], v[6:9]
	v_mfma_f32_16x16x32_bf16 v[2:5], v[158:161], v[224:227], v[2:5]
	s_setprio 0
	s_barrier
	s_add_i32 s53, 0, 0x18000
	s_add_i32 s54, 0, 0x1c000
	v_add_u32_e32 v142, s53, v187
	v_add_u32_e32 v158, s54, v187
	ds_read_b128 v[130:133], v142
	ds_read_b128 v[134:137], v142 offset:1024
	ds_read_b128 v[138:141], v142 offset:2048
	ds_read_b128 v[142:145], v142 offset:3072
	ds_read_b128 v[146:149], v158
	ds_read_b128 v[150:153], v158 offset:1024
	ds_read_b128 v[154:157], v158 offset:2048
	ds_read_b128 v[158:161], v158 offset:3072
	s_add_u32 s36, s36, 0x80000
	s_addc_u32 s37, s37, 0
	s_mov_b32 m0, s45
	v_lshl_add_u64 v[212:213], s[36:37], 0, v[166:167]
	ds_read_b128 v[172:175], v199 offset:32768
	ds_read_b128 v[178:181], v199 offset:33792
	ds_read_b128 v[188:191], v199 offset:34816
	ds_read_b128 v[200:203], v199 offset:35840
	ds_read_b128 v[204:207], v199 offset:36864
	ds_read_b128 v[216:219], v199 offset:37888
	ds_read_b128 v[220:223], v199 offset:38912
	ds_read_b128 v[224:227], v199 offset:39936
	global_load_lds_dwordx4 v[212:213], off
	v_lshl_add_u64 v[212:213], s[36:37], 0, v[164:165]
	s_mov_b32 m0, s46
	s_nop 0
	global_load_lds_dwordx4 v[212:213], off
	s_waitcnt vmcnt(8)
	s_waitcnt lgkmcnt(0)
	s_barrier
	s_setprio 1
	v_mfma_f32_16x16x32_bf16 v[126:129], v[130:133], v[172:175], v[126:129]
	v_mfma_f32_16x16x32_bf16 v[122:125], v[138:141], v[172:175], v[122:125]
	v_mfma_f32_16x16x32_bf16 v[110:113], v[130:133], v[188:191], v[110:113]
	v_mfma_f32_16x16x32_bf16 v[106:109], v[138:141], v[188:191], v[106:109]
	v_mfma_f32_16x16x32_bf16 v[98:101], v[130:133], v[204:207], v[98:101]
	v_mfma_f32_16x16x32_bf16 v[90:93], v[138:141], v[204:207], v[90:93]
	v_mfma_f32_16x16x32_bf16 v[82:85], v[130:133], v[220:223], v[82:85]
	v_mfma_f32_16x16x32_bf16 v[74:77], v[138:141], v[220:223], v[74:77]
	v_mfma_f32_16x16x32_bf16 v[126:129], v[134:137], v[178:181], v[126:129]
	v_mfma_f32_16x16x32_bf16 v[122:125], v[142:145], v[178:181], v[122:125]
	v_mfma_f32_16x16x32_bf16 v[110:113], v[134:137], v[200:203], v[110:113]
	v_mfma_f32_16x16x32_bf16 v[106:109], v[142:145], v[200:203], v[106:109]
	v_mfma_f32_16x16x32_bf16 v[98:101], v[134:137], v[216:219], v[98:101]
	v_mfma_f32_16x16x32_bf16 v[90:93], v[142:145], v[216:219], v[90:93]
	v_mfma_f32_16x16x32_bf16 v[82:85], v[134:137], v[224:227], v[82:85]
	v_mfma_f32_16x16x32_bf16 v[74:77], v[142:145], v[224:227], v[74:77]
	v_mfma_f32_16x16x32_bf16 v[118:121], v[146:149], v[172:175], v[118:121]
	v_mfma_f32_16x16x32_bf16 v[114:117], v[154:157], v[172:175], v[114:117]
	v_mfma_f32_16x16x32_bf16 v[102:105], v[146:149], v[188:191], v[102:105]
	v_mfma_f32_16x16x32_bf16 v[94:97], v[154:157], v[188:191], v[94:97]
	v_mfma_f32_16x16x32_bf16 v[86:89], v[146:149], v[204:207], v[86:89]
	v_mfma_f32_16x16x32_bf16 v[78:81], v[154:157], v[204:207], v[78:81]
	v_mfma_f32_16x16x32_bf16 v[70:73], v[146:149], v[220:223], v[70:73]
	v_mfma_f32_16x16x32_bf16 v[66:69], v[154:157], v[220:223], v[66:69]
	v_mfma_f32_16x16x32_bf16 v[118:121], v[150:153], v[178:181], v[118:121]
	v_mfma_f32_16x16x32_bf16 v[114:117], v[158:161], v[178:181], v[114:117]
	v_mfma_f32_16x16x32_bf16 v[102:105], v[150:153], v[200:203], v[102:105]
	v_mfma_f32_16x16x32_bf16 v[94:97], v[158:161], v[200:203], v[94:97]
	v_mfma_f32_16x16x32_bf16 v[86:89], v[150:153], v[216:219], v[86:89]
	v_mfma_f32_16x16x32_bf16 v[78:81], v[158:161], v[216:219], v[78:81]
	v_mfma_f32_16x16x32_bf16 v[70:73], v[150:153], v[224:227], v[70:73]
	v_mfma_f32_16x16x32_bf16 v[66:69], v[158:161], v[224:227], v[66:69]
	s_setprio 0
	s_barrier
	s_add_i32 s36, s53, s42
	v_lshl_add_u64 v[184:185], v[184:185], 0, s[64:65]
	s_mov_b32 m0, s36
	ds_read_b128 v[172:175], v199 offset:49152
	ds_read_b128 v[178:181], v199 offset:50176
	ds_read_b128 v[188:191], v199 offset:51200
	ds_read_b128 v[200:203], v199 offset:52224
	ds_read_b128 v[204:207], v199 offset:53248
	ds_read_b128 v[216:219], v199 offset:54272
	ds_read_b128 v[220:223], v199 offset:55296
	ds_read_b128 v[224:227], v199 offset:56320
	global_load_lds_dwordx4 v[184:185], off
	s_add_i32 m0, s36, 0x2000
	s_add_u32 s34, s34, 0x80080
	v_lshl_add_u64 v[184:185], v[192:193], 0, s[64:65]
	s_addc_u32 s35, s35, 0
	s_add_i32 s36, s54, s42
	global_load_lds_dwordx4 v[184:185], off
	v_lshl_add_u64 v[184:185], s[34:35], 0, v[210:211]
	s_mov_b32 m0, s36
	s_nop 0
	global_load_lds_dwordx4 v[184:185], off
	v_lshl_add_u64 v[184:185], s[34:35], 0, v[162:163]
	s_add_i32 m0, s36, 0x2000
	s_nop 0
	global_load_lds_dwordx4 v[184:185], off
	v_lshl_add_u64 v[184:185], v[196:197], 0, s[64:65]
	s_mov_b32 m0, s47
	s_nop 0
	global_load_lds_dwordx4 v[184:185], off
	v_lshl_add_u64 v[184:185], v[208:209], 0, s[64:65]
	s_mov_b32 m0, s48
	s_nop 0
	global_load_lds_dwordx4 v[184:185], off
	s_waitcnt vmcnt(8)
	s_waitcnt lgkmcnt(0)
	s_barrier
	s_setprio 1
	v_mfma_f32_16x16x32_bf16 v[62:65], v[130:133], v[172:175], v[62:65]
	v_mfma_f32_16x16x32_bf16 v[58:61], v[138:141], v[172:175], v[58:61]
	v_mfma_f32_16x16x32_bf16 v[50:53], v[130:133], v[188:191], v[50:53]
	v_mfma_f32_16x16x32_bf16 v[42:45], v[138:141], v[188:191], v[42:45]
	v_mfma_f32_16x16x32_bf16 v[34:37], v[130:133], v[204:207], v[34:37]
	v_mfma_f32_16x16x32_bf16 v[26:29], v[138:141], v[204:207], v[26:29]
	v_mfma_f32_16x16x32_bf16 v[14:17], v[130:133], v[220:223], v[14:17]
	v_mfma_f32_16x16x32_bf16 v[10:13], v[138:141], v[220:223], v[10:13]
	v_mfma_f32_16x16x32_bf16 v[62:65], v[134:137], v[178:181], v[62:65]
	v_mfma_f32_16x16x32_bf16 v[58:61], v[142:145], v[178:181], v[58:61]
	v_mfma_f32_16x16x32_bf16 v[50:53], v[134:137], v[200:203], v[50:53]
	v_mfma_f32_16x16x32_bf16 v[42:45], v[142:145], v[200:203], v[42:45]
	v_mfma_f32_16x16x32_bf16 v[34:37], v[134:137], v[216:219], v[34:37]
	v_mfma_f32_16x16x32_bf16 v[26:29], v[142:145], v[216:219], v[26:29]
	v_mfma_f32_16x16x32_bf16 v[14:17], v[134:137], v[224:227], v[14:17]
	v_mfma_f32_16x16x32_bf16 v[10:13], v[142:145], v[224:227], v[10:13]
	v_mfma_f32_16x16x32_bf16 v[54:57], v[146:149], v[172:175], v[54:57]
	v_mfma_f32_16x16x32_bf16 v[46:49], v[154:157], v[172:175], v[46:49]
	v_mfma_f32_16x16x32_bf16 v[38:41], v[146:149], v[188:191], v[38:41]
	v_mfma_f32_16x16x32_bf16 v[30:33], v[154:157], v[188:191], v[30:33]
	v_mfma_f32_16x16x32_bf16 v[22:25], v[146:149], v[204:207], v[22:25]
	v_mfma_f32_16x16x32_bf16 v[18:21], v[154:157], v[204:207], v[18:21]
	v_mfma_f32_16x16x32_bf16 v[6:9], v[146:149], v[220:223], v[6:9]
	v_mfma_f32_16x16x32_bf16 v[2:5], v[154:157], v[220:223], v[2:5]
	v_mfma_f32_16x16x32_bf16 v[54:57], v[150:153], v[178:181], v[54:57]
	v_mfma_f32_16x16x32_bf16 v[46:49], v[158:161], v[178:181], v[46:49]
	v_mfma_f32_16x16x32_bf16 v[38:41], v[150:153], v[200:203], v[38:41]
	v_mfma_f32_16x16x32_bf16 v[30:33], v[158:161], v[200:203], v[30:33]
	v_mfma_f32_16x16x32_bf16 v[22:25], v[150:153], v[216:219], v[22:25]
	v_mfma_f32_16x16x32_bf16 v[18:21], v[158:161], v[216:219], v[18:21]
	v_mfma_f32_16x16x32_bf16 v[6:9], v[150:153], v[224:227], v[6:9]
	v_mfma_f32_16x16x32_bf16 v[2:5], v[158:161], v[224:227], v[2:5]
	s_setprio 0
	s_barrier
	s_add_i32 s52, s52, 2
	s_add_u32 s6, s6, 0x100
	s_addc_u32 s7, s7, 0
	s_add_u32 s50, s50, 0x100
	s_addc_u32 s51, s51, 0
	s_cmp_gt_u32 s52, 29
	s_cbranch_scc0 .LBB0_67
	s_and_b64 vcc, exec, s[18:19]
	s_cbranch_vccz .LBB0_70
	s_barrier

.LBB0_116:
	s_add_u32 s30, s6, 0xfff80080
	s_addc_u32 s31, s7, -1
	s_add_i32 s52, 0, 0x10000
	s_cmp_eq_u32 s51, 28
	s_cselect_b32 s35, s23, s31
	s_cselect_b32 s34, s28, s30
	s_cselect_b32 s31, s21, s50
	s_cselect_b32 s30, s29, s49
	s_add_i32 s54, 0, 0x14000
	v_add_u32_e32 v78, s52, v240
	v_add_u32_e32 v98, s54, v240
	ds_read_b128 v[66:69], v78
	ds_read_b128 v[70:73], v78 offset:1024
	ds_read_b128 v[74:77], v78 offset:2048
	ds_read_b128 v[78:81], v78 offset:3072
	ds_read_b128 v[82:85], v98
	ds_read_b128 v[86:89], v98 offset:1024
	ds_read_b128 v[90:93], v98 offset:2048
	ds_read_b128 v[98:101], v98 offset:3072
	v_lshl_add_u64 v[212:213], s[6:7], 0, v[182:183]
	s_add_i32 m0, s37, 0xc000
	ds_read_b128 v[186:189], v241
	ds_read_b128 v[190:193], v241 offset:1024
	ds_read_b128 v[194:197], v241 offset:2048
	ds_read_b128 v[198:201], v241 offset:3072
	ds_read_b128 v[202:205], v241 offset:4096
	ds_read_b128 v[206:209], v241 offset:5120
	ds_read_b128 v[216:219], v241 offset:6144
	ds_read_b128 v[220:223], v241 offset:7168
	global_load_lds_dwordx4 v[212:213], off
	v_lshl_add_u64 v[212:213], s[6:7], 0, v[184:185]
	s_add_i32 m0, s37, 0xe000
	s_nop 0
	global_load_lds_dwordx4 v[212:213], off
	s_waitcnt vmcnt(8)
	s_waitcnt lgkmcnt(0)
	s_barrier
	s_setprio 1
	v_mfma_f32_16x16x32_bf16 v[158:161], v[66:69], v[186:189], v[158:161]
	v_mfma_f32_16x16x32_bf16 v[154:157], v[74:77], v[186:189], v[154:157]
	v_mfma_f32_16x16x32_bf16 v[142:145], v[66:69], v[194:197], v[142:145]
	v_mfma_f32_16x16x32_bf16 v[138:141], v[74:77], v[194:197], v[138:141]
	v_mfma_f32_16x16x32_bf16 v[126:129], v[66:69], v[202:205], v[126:129]
	v_mfma_f32_16x16x32_bf16 v[122:125], v[74:77], v[202:205], v[122:125]
	v_mfma_f32_16x16x32_bf16 v[110:113], v[66:69], v[216:219], v[110:113]
	v_mfma_f32_16x16x32_bf16 v[106:109], v[74:77], v[216:219], v[106:109]
	v_mfma_f32_16x16x32_bf16 v[158:161], v[70:73], v[190:193], v[158:161]
	v_mfma_f32_16x16x32_bf16 v[154:157], v[78:81], v[190:193], v[154:157]
	v_mfma_f32_16x16x32_bf16 v[142:145], v[70:73], v[198:201], v[142:145]
	v_mfma_f32_16x16x32_bf16 v[138:141], v[78:81], v[198:201], v[138:141]
	v_mfma_f32_16x16x32_bf16 v[126:129], v[70:73], v[206:209], v[126:129]
	v_mfma_f32_16x16x32_bf16 v[122:125], v[78:81], v[206:209], v[122:125]
	v_mfma_f32_16x16x32_bf16 v[110:113], v[70:73], v[220:223], v[110:113]
	v_mfma_f32_16x16x32_bf16 v[106:109], v[78:81], v[220:223], v[106:109]
	v_mfma_f32_16x16x32_bf16 v[150:153], v[82:85], v[186:189], v[150:153]
	v_mfma_f32_16x16x32_bf16 v[146:149], v[90:93], v[186:189], v[146:149]
	v_mfma_f32_16x16x32_bf16 v[134:137], v[82:85], v[194:197], v[134:137]
	v_mfma_f32_16x16x32_bf16 v[130:133], v[90:93], v[194:197], v[130:133]
	v_mfma_f32_16x16x32_bf16 v[118:121], v[82:85], v[202:205], v[118:121]
	v_mfma_f32_16x16x32_bf16 v[114:117], v[90:93], v[202:205], v[114:117]
	v_mfma_f32_16x16x32_bf16 v[102:105], v[82:85], v[216:219], v[102:105]
	v_mfma_f32_16x16x32_bf16 v[94:97], v[90:93], v[216:219], v[94:97]
	v_mfma_f32_16x16x32_bf16 v[150:153], v[86:89], v[190:193], v[150:153]
	v_mfma_f32_16x16x32_bf16 v[146:149], v[98:101], v[190:193], v[146:149]
	v_mfma_f32_16x16x32_bf16 v[134:137], v[86:89], v[198:201], v[134:137]
	v_mfma_f32_16x16x32_bf16 v[130:133], v[98:101], v[198:201], v[130:133]
	v_mfma_f32_16x16x32_bf16 v[118:121], v[86:89], v[206:209], v[118:121]
	v_mfma_f32_16x16x32_bf16 v[114:117], v[98:101], v[206:209], v[114:117]
	v_mfma_f32_16x16x32_bf16 v[102:105], v[86:89], v[220:223], v[102:105]
	v_mfma_f32_16x16x32_bf16 v[94:97], v[98:101], v[220:223], v[94:97]
	s_setprio 0
	s_barrier
	s_add_i32 s52, s52, s36
	v_lshl_add_u64 v[212:213], s[30:31], 0, v[166:167]
	s_mov_b32 m0, s52
	ds_read_b128 v[186:189], v241 offset:16384
	ds_read_b128 v[190:193], v241 offset:17408
	ds_read_b128 v[194:197], v241 offset:18432
	ds_read_b128 v[198:201], v241 offset:19456
	ds_read_b128 v[202:205], v241 offset:20480
	ds_read_b128 v[206:209], v241 offset:21504
	ds_read_b128 v[216:219], v241 offset:22528
	ds_read_b128 v[220:223], v241 offset:23552
	global_load_lds_dwordx4 v[212:213], off
	s_add_i32 m0, s52, 0x2000
	s_add_u32 s52, s30, 0x80000
	v_lshl_add_u64 v[214:215], s[30:31], 0, v[162:163]
	s_addc_u32 s53, s31, 0
	s_add_i32 s54, s54, s36
	global_load_lds_dwordx4 v[214:215], off
	v_lshl_add_u64 v[224:225], s[52:53], 0, v[166:167]
	s_mov_b32 m0, s54
	v_lshl_add_u64 v[226:227], s[34:35], 0, v[164:165]
	global_load_lds_dwordx4 v[224:225], off
	v_lshl_add_u64 v[224:225], s[52:53], 0, v[162:163]
	s_add_i32 m0, s54, 0x2000
	s_nop 0
	global_load_lds_dwordx4 v[224:225], off
	v_lshl_add_u64 v[224:225], s[34:35], 0, v[168:169]
	s_mov_b32 m0, s37
	s_nop 0
	global_load_lds_dwordx4 v[224:225], off
	s_mov_b32 m0, s42
	s_nop 0
	global_load_lds_dwordx4 v[226:227], off
	s_waitcnt vmcnt(8)
	s_waitcnt lgkmcnt(0)
	s_barrier
	s_setprio 1
	v_mfma_f32_16x16x32_bf16 v[62:65], v[66:69], v[186:189], v[62:65]
	v_mfma_f32_16x16x32_bf16 v[58:61], v[74:77], v[186:189], v[58:61]
	v_mfma_f32_16x16x32_bf16 v[46:49], v[66:69], v[194:197], v[46:49]
	v_mfma_f32_16x16x32_bf16 v[42:45], v[74:77], v[194:197], v[42:45]
	v_mfma_f32_16x16x32_bf16 v[30:33], v[66:69], v[202:205], v[30:33]
	v_mfma_f32_16x16x32_bf16 v[26:29], v[74:77], v[202:205], v[26:29]
	v_mfma_f32_16x16x32_bf16 v[14:17], v[66:69], v[216:219], v[14:17]
	v_mfma_f32_16x16x32_bf16 v[10:13], v[74:77], v[216:219], v[10:13]
	v_mfma_f32_16x16x32_bf16 v[62:65], v[70:73], v[190:193], v[62:65]
	v_mfma_f32_16x16x32_bf16 v[58:61], v[78:81], v[190:193], v[58:61]
	v_mfma_f32_16x16x32_bf16 v[46:49], v[70:73], v[198:201], v[46:49]
	v_mfma_f32_16x16x32_bf16 v[42:45], v[78:81], v[198:201], v[42:45]
	v_mfma_f32_16x16x32_bf16 v[30:33], v[70:73], v[206:209], v[30:33]
	v_mfma_f32_16x16x32_bf16 v[26:29], v[78:81], v[206:209], v[26:29]
	v_mfma_f32_16x16x32_bf16 v[14:17], v[70:73], v[220:223], v[14:17]
	v_mfma_f32_16x16x32_bf16 v[10:13], v[78:81], v[220:223], v[10:13]
	v_mfma_f32_16x16x32_bf16 v[54:57], v[82:85], v[186:189], v[54:57]
	v_mfma_f32_16x16x32_bf16 v[50:53], v[90:93], v[186:189], v[50:53]
	v_mfma_f32_16x16x32_bf16 v[38:41], v[82:85], v[194:197], v[38:41]
	v_mfma_f32_16x16x32_bf16 v[34:37], v[90:93], v[194:197], v[34:37]
	v_mfma_f32_16x16x32_bf16 v[22:25], v[82:85], v[202:205], v[22:25]
	v_mfma_f32_16x16x32_bf16 v[18:21], v[90:93], v[202:205], v[18:21]
	v_mfma_f32_16x16x32_bf16 v[6:9], v[82:85], v[216:219], v[6:9]
	v_mfma_f32_16x16x32_bf16 v[2:5], v[90:93], v[216:219], v[2:5]
	v_mfma_f32_16x16x32_bf16 v[54:57], v[86:89], v[190:193], v[54:57]
	v_mfma_f32_16x16x32_bf16 v[50:53], v[98:101], v[190:193], v[50:53]
	v_mfma_f32_16x16x32_bf16 v[38:41], v[86:89], v[198:201], v[38:41]
	v_mfma_f32_16x16x32_bf16 v[34:37], v[98:101], v[198:201], v[34:37]
	v_mfma_f32_16x16x32_bf16 v[22:25], v[86:89], v[206:209], v[22:25]
	v_mfma_f32_16x16x32_bf16 v[18:21], v[98:101], v[206:209], v[18:21]
	v_mfma_f32_16x16x32_bf16 v[6:9], v[86:89], v[220:223], v[6:9]
	v_mfma_f32_16x16x32_bf16 v[2:5], v[98:101], v[220:223], v[2:5]
	s_setprio 0
	s_barrier
	s_add_i32 s52, 0, 0x18000
	s_add_i32 s53, 0, 0x1c000
	v_add_u32_e32 v78, s52, v240
	v_add_u32_e32 v98, s53, v240
	ds_read_b128 v[66:69], v78
	ds_read_b128 v[70:73], v78 offset:1024
	ds_read_b128 v[74:77], v78 offset:2048
	ds_read_b128 v[78:81], v78 offset:3072
	ds_read_b128 v[82:85], v98
	ds_read_b128 v[86:89], v98 offset:1024
	ds_read_b128 v[90:93], v98 offset:2048
	ds_read_b128 v[98:101], v98 offset:3072
	s_add_u32 s34, s34, 0x80000
	s_addc_u32 s35, s35, 0
	s_mov_b32 m0, s43
	v_lshl_add_u64 v[228:229], s[34:35], 0, v[168:169]
	ds_read_b128 v[186:189], v241 offset:32768
	ds_read_b128 v[190:193], v241 offset:33792
	ds_read_b128 v[194:197], v241 offset:34816
	ds_read_b128 v[198:201], v241 offset:35840
	ds_read_b128 v[202:205], v241 offset:36864
	ds_read_b128 v[206:209], v241 offset:37888
	ds_read_b128 v[216:219], v241 offset:38912
	ds_read_b128 v[220:223], v241 offset:39936
	global_load_lds_dwordx4 v[228:229], off
	v_lshl_add_u64 v[228:229], s[34:35], 0, v[164:165]
	s_mov_b32 m0, s44
	s_nop 0
	global_load_lds_dwordx4 v[228:229], off
	s_waitcnt vmcnt(8)
	s_waitcnt lgkmcnt(0)
	s_barrier
	s_setprio 1
	v_mfma_f32_16x16x32_bf16 v[158:161], v[66:69], v[186:189], v[158:161]
	v_mfma_f32_16x16x32_bf16 v[154:157], v[74:77], v[186:189], v[154:157]
	v_mfma_f32_16x16x32_bf16 v[142:145], v[66:69], v[194:197], v[142:145]
	v_mfma_f32_16x16x32_bf16 v[138:141], v[74:77], v[194:197], v[138:141]
	v_mfma_f32_16x16x32_bf16 v[126:129], v[66:69], v[202:205], v[126:129]
	v_mfma_f32_16x16x32_bf16 v[122:125], v[74:77], v[202:205], v[122:125]
	v_mfma_f32_16x16x32_bf16 v[110:113], v[66:69], v[216:219], v[110:113]
	v_mfma_f32_16x16x32_bf16 v[106:109], v[74:77], v[216:219], v[106:109]
	v_mfma_f32_16x16x32_bf16 v[158:161], v[70:73], v[190:193], v[158:161]
	v_mfma_f32_16x16x32_bf16 v[154:157], v[78:81], v[190:193], v[154:157]
	v_mfma_f32_16x16x32_bf16 v[142:145], v[70:73], v[198:201], v[142:145]
	v_mfma_f32_16x16x32_bf16 v[138:141], v[78:81], v[198:201], v[138:141]
	v_mfma_f32_16x16x32_bf16 v[126:129], v[70:73], v[206:209], v[126:129]
	v_mfma_f32_16x16x32_bf16 v[122:125], v[78:81], v[206:209], v[122:125]
	v_mfma_f32_16x16x32_bf16 v[110:113], v[70:73], v[220:223], v[110:113]
	v_mfma_f32_16x16x32_bf16 v[106:109], v[78:81], v[220:223], v[106:109]
	v_mfma_f32_16x16x32_bf16 v[150:153], v[82:85], v[186:189], v[150:153]
	v_mfma_f32_16x16x32_bf16 v[146:149], v[90:93], v[186:189], v[146:149]
	v_mfma_f32_16x16x32_bf16 v[134:137], v[82:85], v[194:197], v[134:137]
	v_mfma_f32_16x16x32_bf16 v[130:133], v[90:93], v[194:197], v[130:133]
	v_mfma_f32_16x16x32_bf16 v[118:121], v[82:85], v[202:205], v[118:121]
	v_mfma_f32_16x16x32_bf16 v[114:117], v[90:93], v[202:205], v[114:117]
	v_mfma_f32_16x16x32_bf16 v[102:105], v[82:85], v[216:219], v[102:105]
	v_mfma_f32_16x16x32_bf16 v[94:97], v[90:93], v[216:219], v[94:97]
	v_mfma_f32_16x16x32_bf16 v[150:153], v[86:89], v[190:193], v[150:153]
	v_mfma_f32_16x16x32_bf16 v[146:149], v[98:101], v[190:193], v[146:149]
	v_mfma_f32_16x16x32_bf16 v[134:137], v[86:89], v[198:201], v[134:137]
	v_mfma_f32_16x16x32_bf16 v[130:133], v[98:101], v[198:201], v[130:133]
	v_mfma_f32_16x16x32_bf16 v[118:121], v[86:89], v[206:209], v[118:121]
	v_mfma_f32_16x16x32_bf16 v[114:117], v[98:101], v[206:209], v[114:117]
	v_mfma_f32_16x16x32_bf16 v[102:105], v[86:89], v[220:223], v[102:105]
	v_mfma_f32_16x16x32_bf16 v[94:97], v[98:101], v[220:223], v[94:97]
	s_setprio 0
	s_barrier
	s_add_i32 s34, s52, s36
	v_lshl_add_u64 v[212:213], v[212:213], 0, s[64:65]
	s_mov_b32 m0, s34
	ds_read_b128 v[186:189], v241 offset:49152
	ds_read_b128 v[190:193], v241 offset:50176
	ds_read_b128 v[194:197], v241 offset:51200
	ds_read_b128 v[198:201], v241 offset:52224
	ds_read_b128 v[202:205], v241 offset:53248
	ds_read_b128 v[206:209], v241 offset:54272
	ds_read_b128 v[216:219], v241 offset:55296
	ds_read_b128 v[220:223], v241 offset:56320
	global_load_lds_dwordx4 v[212:213], off
	s_add_i32 m0, s34, 0x2000
	s_add_u32 s30, s30, 0x80080
	v_lshl_add_u64 v[212:213], v[214:215], 0, s[64:65]
	s_addc_u32 s31, s31, 0
	s_add_i32 s34, s53, s36
	global_load_lds_dwordx4 v[212:213], off
	v_lshl_add_u64 v[212:213], s[30:31], 0, v[166:167]
	s_mov_b32 m0, s34
	s_nop 0
	global_load_lds_dwordx4 v[212:213], off
	v_lshl_add_u64 v[212:213], s[30:31], 0, v[162:163]
	s_add_i32 m0, s34, 0x2000
	s_nop 0
	global_load_lds_dwordx4 v[212:213], off
	v_lshl_add_u64 v[212:213], v[224:225], 0, s[64:65]
	s_mov_b32 m0, s46
	s_nop 0
	global_load_lds_dwordx4 v[212:213], off
	v_lshl_add_u64 v[212:213], v[226:227], 0, s[64:65]
	s_mov_b32 m0, s47
	s_nop 0
	global_load_lds_dwordx4 v[212:213], off
	s_waitcnt vmcnt(8)
	s_waitcnt lgkmcnt(0)
	s_barrier
	s_setprio 1
	v_mfma_f32_16x16x32_bf16 v[62:65], v[66:69], v[186:189], v[62:65]
	v_mfma_f32_16x16x32_bf16 v[58:61], v[74:77], v[186:189], v[58:61]
	v_mfma_f32_16x16x32_bf16 v[46:49], v[66:69], v[194:197], v[46:49]
	v_mfma_f32_16x16x32_bf16 v[42:45], v[74:77], v[194:197], v[42:45]
	v_mfma_f32_16x16x32_bf16 v[30:33], v[66:69], v[202:205], v[30:33]
	v_mfma_f32_16x16x32_bf16 v[26:29], v[74:77], v[202:205], v[26:29]
	v_mfma_f32_16x16x32_bf16 v[14:17], v[66:69], v[216:219], v[14:17]
	v_mfma_f32_16x16x32_bf16 v[10:13], v[74:77], v[216:219], v[10:13]
	v_mfma_f32_16x16x32_bf16 v[62:65], v[70:73], v[190:193], v[62:65]
	v_mfma_f32_16x16x32_bf16 v[58:61], v[78:81], v[190:193], v[58:61]
	v_mfma_f32_16x16x32_bf16 v[46:49], v[70:73], v[198:201], v[46:49]
	v_mfma_f32_16x16x32_bf16 v[42:45], v[78:81], v[198:201], v[42:45]
	v_mfma_f32_16x16x32_bf16 v[30:33], v[70:73], v[206:209], v[30:33]
	v_mfma_f32_16x16x32_bf16 v[26:29], v[78:81], v[206:209], v[26:29]
	v_mfma_f32_16x16x32_bf16 v[14:17], v[70:73], v[220:223], v[14:17]
	v_mfma_f32_16x16x32_bf16 v[10:13], v[78:81], v[220:223], v[10:13]
	v_mfma_f32_16x16x32_bf16 v[54:57], v[82:85], v[186:189], v[54:57]
	v_mfma_f32_16x16x32_bf16 v[50:53], v[90:93], v[186:189], v[50:53]
	v_mfma_f32_16x16x32_bf16 v[38:41], v[82:85], v[194:197], v[38:41]
	v_mfma_f32_16x16x32_bf16 v[34:37], v[90:93], v[194:197], v[34:37]
	v_mfma_f32_16x16x32_bf16 v[22:25], v[82:85], v[202:205], v[22:25]
	v_mfma_f32_16x16x32_bf16 v[18:21], v[90:93], v[202:205], v[18:21]
	v_mfma_f32_16x16x32_bf16 v[6:9], v[82:85], v[216:219], v[6:9]
	v_mfma_f32_16x16x32_bf16 v[2:5], v[90:93], v[216:219], v[2:5]
	v_mfma_f32_16x16x32_bf16 v[54:57], v[86:89], v[190:193], v[54:57]
	v_mfma_f32_16x16x32_bf16 v[50:53], v[98:101], v[190:193], v[50:53]
	v_mfma_f32_16x16x32_bf16 v[38:41], v[86:89], v[198:201], v[38:41]
	v_mfma_f32_16x16x32_bf16 v[34:37], v[98:101], v[198:201], v[34:37]
	v_mfma_f32_16x16x32_bf16 v[22:25], v[86:89], v[206:209], v[22:25]
	v_mfma_f32_16x16x32_bf16 v[18:21], v[98:101], v[206:209], v[18:21]
	v_mfma_f32_16x16x32_bf16 v[6:9], v[86:89], v[220:223], v[6:9]
	v_mfma_f32_16x16x32_bf16 v[2:5], v[98:101], v[220:223], v[2:5]
	s_setprio 0
	s_barrier
	s_add_i32 s51, s51, 2
	s_add_u32 s6, s6, 0x100
	s_addc_u32 s7, s7, 0
	s_add_u32 s49, s49, 0x100
	s_addc_u32 s50, s50, 0
	s_cmp_gt_u32 s51, 29
	s_cbranch_scc0 .LBB0_116
	s_and_b64 vcc, exec, s[18:19]
	s_cbranch_vccz .LBB0_119
	s_barrier

.LBB0_226:
	s_add_u32 s30, s8, 0xfff80080
	s_addc_u32 s31, s9, -1
	s_add_i32 s54, 0, 0x10000
	s_cmp_eq_u32 s53, 28
	s_cselect_b32 s35, s23, s31
	s_cselect_b32 s34, s28, s30
	s_cselect_b32 s31, s21, s52
	s_cselect_b32 s30, s29, s51
	s_add_i32 s56, 0, 0x14000
	v_add_u32_e32 v160, s54, v141
	v_add_u32_e32 v176, s56, v141
	ds_read_b128 v[148:151], v160
	ds_read_b128 v[152:155], v160 offset:1024
	ds_read_b128 v[156:159], v160 offset:2048
	ds_read_b128 v[160:163], v160 offset:3072
	ds_read_b128 v[164:167], v176
	ds_read_b128 v[168:171], v176 offset:1024
	ds_read_b128 v[172:175], v176 offset:2048
	ds_read_b128 v[176:179], v176 offset:3072
	v_lshl_add_u64 v[208:209], s[8:9], 0, v[144:145]
	s_add_i32 m0, s41, 0xc000
	ds_read_b128 v[180:183], v238
	ds_read_b128 v[184:187], v238 offset:1024
	ds_read_b128 v[188:191], v238 offset:2048
	ds_read_b128 v[192:195], v238 offset:3072
	ds_read_b128 v[196:199], v238 offset:4096
	ds_read_b128 v[200:203], v238 offset:5120
	ds_read_b128 v[204:207], v238 offset:6144
	ds_read_b128 v[216:219], v238 offset:7168
	global_load_lds_dwordx4 v[208:209], off
	v_lshl_add_u64 v[208:209], s[8:9], 0, v[146:147]
	s_add_i32 m0, s41, 0xe000
	s_nop 0
	global_load_lds_dwordx4 v[208:209], off
	s_waitcnt vmcnt(8)
	s_waitcnt lgkmcnt(0)
	s_barrier
	s_setprio 1
	v_mfma_f32_16x16x32_bf16 v[126:129], v[148:151], v[180:183], v[126:129]
	v_mfma_f32_16x16x32_bf16 v[122:125], v[156:159], v[180:183], v[122:125]
	v_mfma_f32_16x16x32_bf16 v[110:113], v[148:151], v[188:191], v[110:113]
	v_mfma_f32_16x16x32_bf16 v[106:109], v[156:159], v[188:191], v[106:109]
	v_mfma_f32_16x16x32_bf16 v[94:97], v[148:151], v[196:199], v[94:97]
	v_mfma_f32_16x16x32_bf16 v[90:93], v[156:159], v[196:199], v[90:93]
	v_mfma_f32_16x16x32_bf16 v[78:81], v[148:151], v[204:207], v[78:81]
	v_mfma_f32_16x16x32_bf16 v[74:77], v[156:159], v[204:207], v[74:77]
	v_mfma_f32_16x16x32_bf16 v[126:129], v[152:155], v[184:187], v[126:129]
	v_mfma_f32_16x16x32_bf16 v[122:125], v[160:163], v[184:187], v[122:125]
	v_mfma_f32_16x16x32_bf16 v[110:113], v[152:155], v[192:195], v[110:113]
	v_mfma_f32_16x16x32_bf16 v[106:109], v[160:163], v[192:195], v[106:109]
	v_mfma_f32_16x16x32_bf16 v[94:97], v[152:155], v[200:203], v[94:97]
	v_mfma_f32_16x16x32_bf16 v[90:93], v[160:163], v[200:203], v[90:93]
	v_mfma_f32_16x16x32_bf16 v[78:81], v[152:155], v[216:219], v[78:81]
	v_mfma_f32_16x16x32_bf16 v[74:77], v[160:163], v[216:219], v[74:77]
	v_mfma_f32_16x16x32_bf16 v[118:121], v[164:167], v[180:183], v[118:121]
	v_mfma_f32_16x16x32_bf16 v[114:117], v[172:175], v[180:183], v[114:117]
	v_mfma_f32_16x16x32_bf16 v[102:105], v[164:167], v[188:191], v[102:105]
	v_mfma_f32_16x16x32_bf16 v[98:101], v[172:175], v[188:191], v[98:101]
	v_mfma_f32_16x16x32_bf16 v[86:89], v[164:167], v[196:199], v[86:89]
	v_mfma_f32_16x16x32_bf16 v[82:85], v[172:175], v[196:199], v[82:85]
	v_mfma_f32_16x16x32_bf16 v[70:73], v[164:167], v[204:207], v[70:73]
	v_mfma_f32_16x16x32_bf16 v[66:69], v[172:175], v[204:207], v[66:69]
	v_mfma_f32_16x16x32_bf16 v[118:121], v[168:171], v[184:187], v[118:121]
	v_mfma_f32_16x16x32_bf16 v[114:117], v[176:179], v[184:187], v[114:117]
	v_mfma_f32_16x16x32_bf16 v[102:105], v[168:171], v[192:195], v[102:105]
	v_mfma_f32_16x16x32_bf16 v[98:101], v[176:179], v[192:195], v[98:101]
	v_mfma_f32_16x16x32_bf16 v[86:89], v[168:171], v[200:203], v[86:89]
	v_mfma_f32_16x16x32_bf16 v[82:85], v[176:179], v[200:203], v[82:85]
	v_mfma_f32_16x16x32_bf16 v[70:73], v[168:171], v[216:219], v[70:73]
	v_mfma_f32_16x16x32_bf16 v[66:69], v[176:179], v[216:219], v[66:69]
	s_setprio 0
	s_barrier
	s_add_i32 s54, s54, s40
	v_lshl_add_u64 v[208:209], s[30:31], 0, v[134:135]
	s_mov_b32 m0, s54
	ds_read_b128 v[180:183], v238 offset:16384
	ds_read_b128 v[184:187], v238 offset:17408
	ds_read_b128 v[188:191], v238 offset:18432
	ds_read_b128 v[192:195], v238 offset:19456
	ds_read_b128 v[196:199], v238 offset:20480
	ds_read_b128 v[200:203], v238 offset:21504
	ds_read_b128 v[204:207], v238 offset:22528
	ds_read_b128 v[216:219], v238 offset:23552
	global_load_lds_dwordx4 v[208:209], off
	s_add_i32 m0, s54, 0x2000
	s_add_u32 s54, s30, 0x80000
	v_lshl_add_u64 v[212:213], s[30:31], 0, v[130:131]
	s_addc_u32 s55, s31, 0
	s_add_i32 s56, s56, s40
	global_load_lds_dwordx4 v[212:213], off
	v_lshl_add_u64 v[214:215], s[54:55], 0, v[134:135]
	s_mov_b32 m0, s56
	v_lshl_add_u64 v[220:221], s[34:35], 0, v[132:133]
	global_load_lds_dwordx4 v[214:215], off
	v_lshl_add_u64 v[214:215], s[54:55], 0, v[130:131]
	s_add_i32 m0, s56, 0x2000
	s_nop 0
	global_load_lds_dwordx4 v[214:215], off
	v_lshl_add_u64 v[214:215], s[34:35], 0, v[136:137]
	s_mov_b32 m0, s41
	s_nop 0
	global_load_lds_dwordx4 v[214:215], off
	s_mov_b32 m0, s42
	s_nop 0
	global_load_lds_dwordx4 v[220:221], off
	s_waitcnt vmcnt(8)
	s_waitcnt lgkmcnt(0)
	s_barrier
	s_setprio 1
	v_mfma_f32_16x16x32_bf16 v[62:65], v[148:151], v[180:183], v[62:65]
	v_mfma_f32_16x16x32_bf16 v[58:61], v[156:159], v[180:183], v[58:61]
	v_mfma_f32_16x16x32_bf16 v[46:49], v[148:151], v[188:191], v[46:49]
	v_mfma_f32_16x16x32_bf16 v[42:45], v[156:159], v[188:191], v[42:45]
	v_mfma_f32_16x16x32_bf16 v[30:33], v[148:151], v[196:199], v[30:33]
	v_mfma_f32_16x16x32_bf16 v[26:29], v[156:159], v[196:199], v[26:29]
	v_mfma_f32_16x16x32_bf16 v[14:17], v[148:151], v[204:207], v[14:17]
	v_mfma_f32_16x16x32_bf16 v[10:13], v[156:159], v[204:207], v[10:13]
	v_mfma_f32_16x16x32_bf16 v[62:65], v[152:155], v[184:187], v[62:65]
	v_mfma_f32_16x16x32_bf16 v[58:61], v[160:163], v[184:187], v[58:61]
	v_mfma_f32_16x16x32_bf16 v[46:49], v[152:155], v[192:195], v[46:49]
	v_mfma_f32_16x16x32_bf16 v[42:45], v[160:163], v[192:195], v[42:45]
	v_mfma_f32_16x16x32_bf16 v[30:33], v[152:155], v[200:203], v[30:33]
	v_mfma_f32_16x16x32_bf16 v[26:29], v[160:163], v[200:203], v[26:29]
	v_mfma_f32_16x16x32_bf16 v[14:17], v[152:155], v[216:219], v[14:17]
	v_mfma_f32_16x16x32_bf16 v[10:13], v[160:163], v[216:219], v[10:13]
	v_mfma_f32_16x16x32_bf16 v[54:57], v[164:167], v[180:183], v[54:57]
	v_mfma_f32_16x16x32_bf16 v[50:53], v[172:175], v[180:183], v[50:53]
	v_mfma_f32_16x16x32_bf16 v[38:41], v[164:167], v[188:191], v[38:41]
	v_mfma_f32_16x16x32_bf16 v[34:37], v[172:175], v[188:191], v[34:37]
	v_mfma_f32_16x16x32_bf16 v[22:25], v[164:167], v[196:199], v[22:25]
	v_mfma_f32_16x16x32_bf16 v[18:21], v[172:175], v[196:199], v[18:21]
	v_mfma_f32_16x16x32_bf16 v[6:9], v[164:167], v[204:207], v[6:9]
	v_mfma_f32_16x16x32_bf16 v[2:5], v[172:175], v[204:207], v[2:5]
	v_mfma_f32_16x16x32_bf16 v[54:57], v[168:171], v[184:187], v[54:57]
	v_mfma_f32_16x16x32_bf16 v[50:53], v[176:179], v[184:187], v[50:53]
	v_mfma_f32_16x16x32_bf16 v[38:41], v[168:171], v[192:195], v[38:41]
	v_mfma_f32_16x16x32_bf16 v[34:37], v[176:179], v[192:195], v[34:37]
	v_mfma_f32_16x16x32_bf16 v[22:25], v[168:171], v[200:203], v[22:25]
	v_mfma_f32_16x16x32_bf16 v[18:21], v[176:179], v[200:203], v[18:21]
	v_mfma_f32_16x16x32_bf16 v[6:9], v[168:171], v[216:219], v[6:9]
	v_mfma_f32_16x16x32_bf16 v[2:5], v[176:179], v[216:219], v[2:5]
	s_setprio 0
	s_barrier
	s_add_i32 s54, 0, 0x18000
	s_add_i32 s55, 0, 0x1c000
	v_add_u32_e32 v160, s54, v141
	v_add_u32_e32 v176, s55, v141
	ds_read_b128 v[148:151], v160
	ds_read_b128 v[152:155], v160 offset:1024
	ds_read_b128 v[156:159], v160 offset:2048
	ds_read_b128 v[160:163], v160 offset:3072
	ds_read_b128 v[164:167], v176
	ds_read_b128 v[168:171], v176 offset:1024
	ds_read_b128 v[172:175], v176 offset:2048
	ds_read_b128 v[176:179], v176 offset:3072
	s_add_u32 s34, s34, 0x80000
	s_addc_u32 s35, s35, 0
	s_mov_b32 m0, s43
	v_lshl_add_u64 v[222:223], s[34:35], 0, v[136:137]
	ds_read_b128 v[180:183], v238 offset:32768
	ds_read_b128 v[184:187], v238 offset:33792
	ds_read_b128 v[188:191], v238 offset:34816
	ds_read_b128 v[192:195], v238 offset:35840
	ds_read_b128 v[196:199], v238 offset:36864
	ds_read_b128 v[200:203], v238 offset:37888
	ds_read_b128 v[204:207], v238 offset:38912
	ds_read_b128 v[216:219], v238 offset:39936
	global_load_lds_dwordx4 v[222:223], off
	v_lshl_add_u64 v[222:223], s[34:35], 0, v[132:133]
	s_mov_b32 m0, s44
	s_nop 0
	global_load_lds_dwordx4 v[222:223], off
	s_waitcnt vmcnt(8)
	s_waitcnt lgkmcnt(0)
	s_barrier
	s_setprio 1
	v_mfma_f32_16x16x32_bf16 v[126:129], v[148:151], v[180:183], v[126:129]
	v_mfma_f32_16x16x32_bf16 v[122:125], v[156:159], v[180:183], v[122:125]
	v_mfma_f32_16x16x32_bf16 v[110:113], v[148:151], v[188:191], v[110:113]
	v_mfma_f32_16x16x32_bf16 v[106:109], v[156:159], v[188:191], v[106:109]
	v_mfma_f32_16x16x32_bf16 v[94:97], v[148:151], v[196:199], v[94:97]
	v_mfma_f32_16x16x32_bf16 v[90:93], v[156:159], v[196:199], v[90:93]
	v_mfma_f32_16x16x32_bf16 v[78:81], v[148:151], v[204:207], v[78:81]
	v_mfma_f32_16x16x32_bf16 v[74:77], v[156:159], v[204:207], v[74:77]
	v_mfma_f32_16x16x32_bf16 v[126:129], v[152:155], v[184:187], v[126:129]
	v_mfma_f32_16x16x32_bf16 v[122:125], v[160:163], v[184:187], v[122:125]
	v_mfma_f32_16x16x32_bf16 v[110:113], v[152:155], v[192:195], v[110:113]
	v_mfma_f32_16x16x32_bf16 v[106:109], v[160:163], v[192:195], v[106:109]
	v_mfma_f32_16x16x32_bf16 v[94:97], v[152:155], v[200:203], v[94:97]
	v_mfma_f32_16x16x32_bf16 v[90:93], v[160:163], v[200:203], v[90:93]
	v_mfma_f32_16x16x32_bf16 v[78:81], v[152:155], v[216:219], v[78:81]
	v_mfma_f32_16x16x32_bf16 v[74:77], v[160:163], v[216:219], v[74:77]
	v_mfma_f32_16x16x32_bf16 v[118:121], v[164:167], v[180:183], v[118:121]
	v_mfma_f32_16x16x32_bf16 v[114:117], v[172:175], v[180:183], v[114:117]
	v_mfma_f32_16x16x32_bf16 v[102:105], v[164:167], v[188:191], v[102:105]
	v_mfma_f32_16x16x32_bf16 v[98:101], v[172:175], v[188:191], v[98:101]
	v_mfma_f32_16x16x32_bf16 v[86:89], v[164:167], v[196:199], v[86:89]
	v_mfma_f32_16x16x32_bf16 v[82:85], v[172:175], v[196:199], v[82:85]
	v_mfma_f32_16x16x32_bf16 v[70:73], v[164:167], v[204:207], v[70:73]
	v_mfma_f32_16x16x32_bf16 v[66:69], v[172:175], v[204:207], v[66:69]
	v_mfma_f32_16x16x32_bf16 v[118:121], v[168:171], v[184:187], v[118:121]
	v_mfma_f32_16x16x32_bf16 v[114:117], v[176:179], v[184:187], v[114:117]
	v_mfma_f32_16x16x32_bf16 v[102:105], v[168:171], v[192:195], v[102:105]
	v_mfma_f32_16x16x32_bf16 v[98:101], v[176:179], v[192:195], v[98:101]
	v_mfma_f32_16x16x32_bf16 v[86:89], v[168:171], v[200:203], v[86:89]
	v_mfma_f32_16x16x32_bf16 v[82:85], v[176:179], v[200:203], v[82:85]
	v_mfma_f32_16x16x32_bf16 v[70:73], v[168:171], v[216:219], v[70:73]
	v_mfma_f32_16x16x32_bf16 v[66:69], v[176:179], v[216:219], v[66:69]
	s_setprio 0
	s_barrier
	s_add_i32 s34, s54, s40
	v_lshl_add_u64 v[208:209], v[208:209], 0, s[64:65]
	s_mov_b32 m0, s34
	ds_read_b128 v[180:183], v238 offset:49152
	ds_read_b128 v[184:187], v238 offset:50176
	ds_read_b128 v[188:191], v238 offset:51200
	ds_read_b128 v[192:195], v238 offset:52224
	ds_read_b128 v[196:199], v238 offset:53248
	ds_read_b128 v[200:203], v238 offset:54272
	ds_read_b128 v[204:207], v238 offset:55296
	ds_read_b128 v[216:219], v238 offset:56320
	global_load_lds_dwordx4 v[208:209], off
	s_add_i32 m0, s34, 0x2000
	s_add_u32 s30, s30, 0x80080
	v_lshl_add_u64 v[208:209], v[212:213], 0, s[64:65]
	s_addc_u32 s31, s31, 0
	s_add_i32 s34, s55, s40
	global_load_lds_dwordx4 v[208:209], off
	v_lshl_add_u64 v[208:209], s[30:31], 0, v[134:135]
	s_mov_b32 m0, s34
	s_nop 0
	global_load_lds_dwordx4 v[208:209], off
	v_lshl_add_u64 v[208:209], s[30:31], 0, v[130:131]
	s_add_i32 m0, s34, 0x2000
	s_nop 0
	global_load_lds_dwordx4 v[208:209], off
	v_lshl_add_u64 v[208:209], v[214:215], 0, s[64:65]
	s_mov_b32 m0, s46
	s_nop 0
	global_load_lds_dwordx4 v[208:209], off
	v_lshl_add_u64 v[208:209], v[220:221], 0, s[64:65]
	s_mov_b32 m0, s47
	s_nop 0
	global_load_lds_dwordx4 v[208:209], off
	s_waitcnt vmcnt(8)
	s_waitcnt lgkmcnt(0)
	s_barrier
	s_setprio 1
	v_mfma_f32_16x16x32_bf16 v[62:65], v[148:151], v[180:183], v[62:65]
	v_mfma_f32_16x16x32_bf16 v[58:61], v[156:159], v[180:183], v[58:61]
	v_mfma_f32_16x16x32_bf16 v[46:49], v[148:151], v[188:191], v[46:49]
	v_mfma_f32_16x16x32_bf16 v[42:45], v[156:159], v[188:191], v[42:45]
	v_mfma_f32_16x16x32_bf16 v[30:33], v[148:151], v[196:199], v[30:33]
	v_mfma_f32_16x16x32_bf16 v[26:29], v[156:159], v[196:199], v[26:29]
	v_mfma_f32_16x16x32_bf16 v[14:17], v[148:151], v[204:207], v[14:17]
	v_mfma_f32_16x16x32_bf16 v[10:13], v[156:159], v[204:207], v[10:13]
	v_mfma_f32_16x16x32_bf16 v[62:65], v[152:155], v[184:187], v[62:65]
	v_mfma_f32_16x16x32_bf16 v[58:61], v[160:163], v[184:187], v[58:61]
	v_mfma_f32_16x16x32_bf16 v[46:49], v[152:155], v[192:195], v[46:49]
	v_mfma_f32_16x16x32_bf16 v[42:45], v[160:163], v[192:195], v[42:45]
	v_mfma_f32_16x16x32_bf16 v[30:33], v[152:155], v[200:203], v[30:33]
	v_mfma_f32_16x16x32_bf16 v[26:29], v[160:163], v[200:203], v[26:29]
	v_mfma_f32_16x16x32_bf16 v[14:17], v[152:155], v[216:219], v[14:17]
	v_mfma_f32_16x16x32_bf16 v[10:13], v[160:163], v[216:219], v[10:13]
	v_mfma_f32_16x16x32_bf16 v[54:57], v[164:167], v[180:183], v[54:57]
	v_mfma_f32_16x16x32_bf16 v[50:53], v[172:175], v[180:183], v[50:53]
	v_mfma_f32_16x16x32_bf16 v[38:41], v[164:167], v[188:191], v[38:41]
	v_mfma_f32_16x16x32_bf16 v[34:37], v[172:175], v[188:191], v[34:37]
	v_mfma_f32_16x16x32_bf16 v[22:25], v[164:167], v[196:199], v[22:25]
	v_mfma_f32_16x16x32_bf16 v[18:21], v[172:175], v[196:199], v[18:21]
	v_mfma_f32_16x16x32_bf16 v[6:9], v[164:167], v[204:207], v[6:9]
	v_mfma_f32_16x16x32_bf16 v[2:5], v[172:175], v[204:207], v[2:5]
	v_mfma_f32_16x16x32_bf16 v[54:57], v[168:171], v[184:187], v[54:57]
	v_mfma_f32_16x16x32_bf16 v[50:53], v[176:179], v[184:187], v[50:53]
	v_mfma_f32_16x16x32_bf16 v[38:41], v[168:171], v[192:195], v[38:41]
	v_mfma_f32_16x16x32_bf16 v[34:37], v[176:179], v[192:195], v[34:37]
	v_mfma_f32_16x16x32_bf16 v[22:25], v[168:171], v[200:203], v[22:25]
	v_mfma_f32_16x16x32_bf16 v[18:21], v[176:179], v[200:203], v[18:21]
	v_mfma_f32_16x16x32_bf16 v[6:9], v[168:171], v[216:219], v[6:9]
	v_mfma_f32_16x16x32_bf16 v[2:5], v[176:179], v[216:219], v[2:5]
	s_setprio 0
	s_barrier
	s_add_i32 s53, s53, 2
	s_add_u32 s8, s8, 0x100
	s_addc_u32 s9, s9, 0
	s_add_u32 s51, s51, 0x100
	s_addc_u32 s52, s52, 0
	s_cmp_gt_u32 s53, 29
	s_cbranch_scc0 .LBB0_226
	s_and_b64 vcc, exec, s[18:19]
	s_cbranch_vccz .LBB0_229
	s_barrier

.LBB0_451:
	s_and_b32 s9, s38, 0x7c0
	s_and_b32 s8, s37, 0x7e0
	s_waitcnt vmcnt(5) lgkmcnt(1)
	v_or_b32_e32 v3, s8, v44
	v_add_u32_e32 v2, s9, v45
	v_lshlrev_b32_e32 v210, 2, v3
	v_ashrrev_i32_e32 v3, 31, v2
	s_waitcnt lgkmcnt(0)
	v_lshl_add_u64 v[4:5], s[12:13], 0, v[210:211]
	v_lshlrev_b64 v[2:3], 13, v[2:3]
	v_lshl_add_u64 v[2:3], v[4:5], 0, v[2:3]
	v_add_co_u32_e32 v4, vcc, 0x4000, v2
	global_load_dword v6, v[2:3], off nt
	s_nop 0
	v_addc_co_u32_e32 v5, vcc, 0, v3, vcc
	global_load_dword v7, v[4:5], off nt
	v_add_co_u32_e32 v4, vcc, 0x8000, v2
	s_mov_b32 s20, 0x10000
	s_nop 0
	v_addc_co_u32_e32 v5, vcc, 0, v3, vcc
	global_load_dword v8, v[4:5], off nt
	v_add_co_u32_e32 v4, vcc, 0xc000, v2
	s_lshl_b32 s74, s9, 1
	s_nop 0
	v_addc_co_u32_e32 v5, vcc, 0, v3, vcc
	global_load_dword v9, v[4:5], off nt
	v_add_co_u32_e32 v4, vcc, s20, v2
	s_mov_b32 s20, 0x14000
	s_nop 0
	v_addc_co_u32_e32 v5, vcc, 0, v3, vcc
	global_load_dword v10, v[4:5], off nt
	v_add_co_u32_e32 v4, vcc, s20, v2
	s_mov_b32 s20, 0x18000
	s_nop 0
	v_addc_co_u32_e32 v5, vcc, 0, v3, vcc
	global_load_dword v11, v[4:5], off nt
	v_add_co_u32_e32 v4, vcc, s20, v2
	s_mov_b32 s20, 0x1c000
	s_nop 0
	v_addc_co_u32_e32 v5, vcc, 0, v3, vcc
	global_load_dword v12, v[4:5], off nt
	v_add_co_u32_e32 v4, vcc, s20, v2
	s_mov_b32 s20, 0x20000
	s_nop 0
	v_addc_co_u32_e32 v5, vcc, 0, v3, vcc
	global_load_dword v13, v[4:5], off nt
	v_add_co_u32_e32 v4, vcc, s20, v2
	s_mov_b32 s20, 0x24000
	s_nop 0
	v_addc_co_u32_e32 v5, vcc, 0, v3, vcc
	global_load_dword v14, v[4:5], off nt
	v_add_co_u32_e32 v4, vcc, s20, v2
	s_mov_b32 s20, 0x28000
	s_nop 0
	v_addc_co_u32_e32 v5, vcc, 0, v3, vcc
	global_load_dword v15, v[4:5], off nt
	v_add_co_u32_e32 v4, vcc, s20, v2
	s_mov_b32 s20, 0x2c000
	s_nop 0
	v_addc_co_u32_e32 v5, vcc, 0, v3, vcc
	global_load_dword v16, v[4:5], off nt
	v_add_co_u32_e32 v4, vcc, s20, v2
	s_mov_b32 s20, 0x30000
	s_nop 0
	v_addc_co_u32_e32 v5, vcc, 0, v3, vcc
	global_load_dword v17, v[4:5], off nt
	v_add_co_u32_e32 v4, vcc, s20, v2
	s_mov_b32 s20, 0x34000
	s_nop 0
	v_addc_co_u32_e32 v5, vcc, 0, v3, vcc
	global_load_dword v18, v[4:5], off nt
	v_add_co_u32_e32 v4, vcc, s20, v2
	s_mov_b32 s20, 0x38000
	s_nop 0
	v_addc_co_u32_e32 v5, vcc, 0, v3, vcc
	global_load_dword v19, v[4:5], off nt
	v_add_co_u32_e32 v4, vcc, s20, v2
	s_mov_b32 s20, 0x3c000
	s_nop 0
	v_addc_co_u32_e32 v5, vcc, 0, v3, vcc
	global_load_dword v20, v[4:5], off nt
	v_add_co_u32_e32 v4, vcc, s20, v2
	s_mov_b32 s20, 0x40000
	s_nop 0
	v_addc_co_u32_e32 v5, vcc, 0, v3, vcc
	global_load_dword v21, v[4:5], off nt
	v_add_co_u32_e32 v4, vcc, s20, v2
	s_mov_b32 s20, 0x44000
	s_nop 0
	v_addc_co_u32_e32 v5, vcc, 0, v3, vcc
	global_load_dword v34, v[4:5], off nt
	v_add_co_u32_e32 v4, vcc, s20, v2
	s_mov_b32 s20, 0x48000
	s_nop 0
	v_addc_co_u32_e32 v5, vcc, 0, v3, vcc
	global_load_dword v35, v[4:5], off nt
	v_add_co_u32_e32 v4, vcc, s20, v2
	s_mov_b32 s20, 0x4c000
	s_nop 0
	v_addc_co_u32_e32 v5, vcc, 0, v3, vcc
	global_load_dword v36, v[4:5], off nt
	v_add_co_u32_e32 v4, vcc, s20, v2
	s_mov_b32 s20, 0x50000
	s_nop 0
	v_addc_co_u32_e32 v5, vcc, 0, v3, vcc
	global_load_dword v37, v[4:5], off nt
	v_add_co_u32_e32 v4, vcc, s20, v2
	s_mov_b32 s20, 0x54000
	s_nop 0
	v_addc_co_u32_e32 v5, vcc, 0, v3, vcc
	global_load_dword v38, v[4:5], off nt
	v_add_co_u32_e32 v4, vcc, s20, v2
	s_mov_b32 s20, 0x58000
	s_nop 0
	v_addc_co_u32_e32 v5, vcc, 0, v3, vcc
	global_load_dword v39, v[4:5], off nt
	v_add_co_u32_e32 v4, vcc, s20, v2
	s_mov_b32 s20, 0x5c000
	s_nop 0
	v_addc_co_u32_e32 v5, vcc, 0, v3, vcc
	global_load_dword v40, v[4:5], off nt
	v_add_co_u32_e32 v4, vcc, s20, v2
	s_mov_b32 s20, 0x60000
	s_nop 0
	v_addc_co_u32_e32 v5, vcc, 0, v3, vcc
	global_load_dword v41, v[4:5], off nt
	v_add_co_u32_e32 v4, vcc, s20, v2
	s_mov_b32 s20, 0x64000
	s_nop 0
	v_addc_co_u32_e32 v5, vcc, 0, v3, vcc
	global_load_dword v42, v[4:5], off nt
	v_add_co_u32_e32 v4, vcc, s20, v2
	s_mov_b32 s20, 0x68000
	s_nop 0
	v_addc_co_u32_e32 v5, vcc, 0, v3, vcc
	global_load_dword v43, v[4:5], off nt
	v_add_co_u32_e32 v4, vcc, s20, v2
	s_mov_b32 s20, 0x6c000
	s_nop 0
	v_addc_co_u32_e32 v5, vcc, 0, v3, vcc
	global_load_dword v54, v[4:5], off nt
	v_add_co_u32_e32 v4, vcc, s20, v2
	s_mov_b32 s20, 0x70000
	s_nop 0
	v_addc_co_u32_e32 v5, vcc, 0, v3, vcc
	global_load_dword v55, v[4:5], off nt
	v_add_co_u32_e32 v4, vcc, s20, v2
	s_mov_b32 s20, 0x74000
	s_nop 0
	v_addc_co_u32_e32 v5, vcc, 0, v3, vcc
	global_load_dword v56, v[4:5], off nt
	v_add_co_u32_e32 v4, vcc, s20, v2
	s_mov_b32 s20, 0x78000
	s_nop 0
	v_addc_co_u32_e32 v5, vcc, 0, v3, vcc
	global_load_dword v57, v[4:5], off nt
	v_add_co_u32_e32 v4, vcc, s20, v2
	s_mov_b32 s20, 0x7c000
	s_nop 0
	v_addc_co_u32_e32 v5, vcc, 0, v3, vcc
	v_add_co_u32_e32 v2, vcc, s20, v2
	global_load_dword v4, v[4:5], off nt
	s_nop 0
	v_addc_co_u32_e32 v3, vcc, 0, v3, vcc
	global_load_dword v2, v[2:3], off nt
	v_add_u32_e32 v3, 0x400, v46
	s_waitcnt vmcnt(30)
	ds_write2_b32 v46, v6, v7 offset1:66
	s_waitcnt vmcnt(28)
	ds_write2_b32 v46, v8, v9 offset0:132 offset1:198
	s_waitcnt vmcnt(26)
	ds_write2_b32 v3, v10, v11 offset0:8 offset1:74
	s_waitcnt vmcnt(24)
	ds_write2_b32 v3, v12, v13 offset0:140 offset1:206
	v_add_u32_e32 v3, 0x800, v46
	s_waitcnt vmcnt(22)
	ds_write2_b32 v3, v14, v15 offset0:16 offset1:82
	s_waitcnt vmcnt(20)
	ds_write2_b32 v3, v16, v17 offset0:148 offset1:214
	v_add_u32_e32 v3, 0xc00, v46
	s_waitcnt vmcnt(18)
	ds_write2_b32 v3, v18, v19 offset0:24 offset1:90
	s_waitcnt vmcnt(16)
	ds_write2_b32 v3, v20, v21 offset0:156 offset1:222
	v_add_u32_e32 v3, 0x1000, v46
	s_waitcnt vmcnt(14)
	ds_write2_b32 v3, v34, v35 offset0:32 offset1:98
	s_waitcnt vmcnt(12)
	ds_write2_b32 v3, v36, v37 offset0:164 offset1:230
	v_add_u32_e32 v3, 0x1400, v46
	s_waitcnt vmcnt(10)
	ds_write2_b32 v3, v38, v39 offset0:40 offset1:106
	s_waitcnt vmcnt(8)
	ds_write2_b32 v3, v40, v41 offset0:172 offset1:238
	v_add_u32_e32 v3, 0x1800, v46
	s_waitcnt vmcnt(6)
	ds_write2_b32 v3, v42, v43 offset0:48 offset1:114
	s_waitcnt vmcnt(4)
	ds_write2_b32 v3, v54, v55 offset0:180 offset1:246
	v_add_u32_e32 v3, 0x1c00, v46
	s_waitcnt vmcnt(2)
	ds_write2_b32 v3, v56, v57 offset0:56 offset1:122
	s_waitcnt vmcnt(0)
	ds_write2_b32 v3, v4, v2 offset0:188 offset1:254
	s_waitcnt lgkmcnt(0)
	v_mov_b32 v2, 0
	ds_read2_b32 v[8:9], v47 offset0:33 offset1:41
	ds_read2_b32 v[10:11], v47 offset1:8
	ds_read2_b32 v[12:13], v47 offset0:66 offset1:74
	ds_read2_b32 v[14:15], v47 offset0:99 offset1:107
	ds_read2_b32 v[16:17], v47 offset0:132 offset1:140
	ds_read2_b32 v[18:19], v47 offset0:165 offset1:173
	ds_read2_b32 v[20:21], v47 offset0:198 offset1:206
	ds_read2_b32 v[34:35], v47 offset0:231 offset1:239
	v_add_u32_e32 v36, s8, v22
	v_ashrrev_i32_e32 v37, 31, v36
	v_lshl_add_u64 v[6:7], v[24:25], 0, s[74:75]
	v_lshlrev_b64 v[36:37], 12, v[36:37]
	s_waitcnt lgkmcnt(6)
	v_cvt_pk_bf16_f32 v2, v10, v8
	v_lshl_add_u64 v[36:37], v[6:7], 0, v[36:37]
	v_add_u32_e32 v8, s8, v48
	s_waitcnt lgkmcnt(4)
	v_cvt_pk_bf16_f32 v3, v12, v14
	s_waitcnt lgkmcnt(2)
	v_cvt_pk_bf16_f32 v4, v16, v18
	s_waitcnt lgkmcnt(0)
	v_cvt_pk_bf16_f32 v5, v20, v34
	global_store_dwordx4 v[36:37], v[2:5], off
	v_add_u32_e32 v36, s8, v49
	v_ashrrev_i32_e32 v37, 31, v36
	v_cvt_pk_bf16_f32 v2, v11, v9
	v_ashrrev_i32_e32 v9, 31, v8
	v_lshlrev_b64 v[8:9], 12, v[8:9]
	v_lshl_add_u64 v[8:9], v[6:7], 0, v[8:9]
	v_cvt_pk_bf16_f32 v3, v13, v15
	v_cvt_pk_bf16_f32 v4, v17, v19
	v_cvt_pk_bf16_f32 v5, v21, v35
	global_store_dwordx4 v[8:9], v[2:5], off
	ds_read2_b32 v[8:9], v47 offset0:16 offset1:24
	ds_read2_b32 v[10:11], v47 offset0:49 offset1:57
	ds_read2_b32 v[12:13], v47 offset0:82 offset1:90
	ds_read2_b32 v[14:15], v47 offset0:115 offset1:123
	ds_read2_b32 v[16:17], v47 offset0:148 offset1:156
	ds_read2_b32 v[18:19], v47 offset0:181 offset1:189
	ds_read2_b32 v[20:21], v47 offset0:214 offset1:222
	ds_read2_b32 v[34:35], v47 offset0:247 offset1:255
	v_lshlrev_b64 v[36:37], 12, v[36:37]
	s_waitcnt lgkmcnt(6)
	v_cvt_pk_bf16_f32 v2, v8, v10
	v_lshl_add_u64 v[36:37], v[6:7], 0, v[36:37]
	v_add_u32_e32 v8, s8, v50
	s_waitcnt lgkmcnt(4)
	v_cvt_pk_bf16_f32 v3, v12, v14
	s_waitcnt lgkmcnt(2)
	v_cvt_pk_bf16_f32 v4, v16, v18
	s_waitcnt lgkmcnt(0)
	v_cvt_pk_bf16_f32 v5, v20, v34
	global_store_dwordx4 v[36:37], v[2:5], off
	s_nop 1
	v_cvt_pk_bf16_f32 v2, v9, v11
	v_ashrrev_i32_e32 v9, 31, v8
	v_lshlrev_b64 v[8:9], 12, v[8:9]
	v_lshl_add_u64 v[6:7], v[6:7], 0, v[8:9]
	v_cvt_pk_bf16_f32 v3, v13, v15
	v_cvt_pk_bf16_f32 v4, v17, v19
	v_cvt_pk_bf16_f32 v5, v21, v35
	global_store_dwordx4 v[6:7], v[2:5], off
	s_waitcnt lgkmcnt(0)
	s_add_i32 s8, s38, 0xfffff800
	s_cmpk_gt_u32 s8, 0x1fff
	s_cbranch_scc1 .LBB0_450
.LBB0_452:
	s_lshr_b32 s8, s8, 2
	s_and_b32 s20, s8, 0x7c0
	s_and_b32 s28, s37, 0x1fe0
	s_waitcnt vmcnt(5) lgkmcnt(1)
	v_or_b32_e32 v3, s28, v44
	v_add_u32_e32 v2, s20, v45
	v_lshlrev_b32_e32 v210, 2, v3
	v_ashrrev_i32_e32 v3, 31, v2
	s_waitcnt lgkmcnt(0)
	v_lshl_add_u64 v[4:5], s[0:1], 0, v[210:211]
	v_lshlrev_b64 v[2:3], 15, v[2:3]
	v_lshl_add_u64 v[2:3], v[4:5], 0, v[2:3]
	v_add_co_u32_e32 v4, vcc, 0x10000, v2
	global_load_dword v6, v[2:3], off nt
	s_nop 0
	v_addc_co_u32_e32 v5, vcc, 0, v3, vcc
	global_load_dword v7, v[4:5], off nt
	v_add_co_u32_e32 v4, vcc, 0x20000, v2
	s_nop 1
	v_addc_co_u32_e32 v5, vcc, 0, v3, vcc
	global_load_dword v8, v[4:5], off nt
	v_add_co_u32_e32 v4, vcc, 0x30000, v2
	s_nop 1
	v_addc_co_u32_e32 v5, vcc, 0, v3, vcc
	global_load_dword v9, v[4:5], off nt
	v_add_co_u32_e32 v4, vcc, 0x40000, v2
	s_nop 1
	v_addc_co_u32_e32 v5, vcc, 0, v3, vcc
	global_load_dword v10, v[4:5], off nt
	v_add_co_u32_e32 v4, vcc, 0x50000, v2
	s_nop 1
	v_addc_co_u32_e32 v5, vcc, 0, v3, vcc
	global_load_dword v11, v[4:5], off nt
	v_add_co_u32_e32 v4, vcc, 0x60000, v2
	s_nop 1
	v_addc_co_u32_e32 v5, vcc, 0, v3, vcc
	global_load_dword v12, v[4:5], off nt
	v_add_co_u32_e32 v4, vcc, 0x70000, v2
	s_nop 1
	v_addc_co_u32_e32 v5, vcc, 0, v3, vcc
	global_load_dword v13, v[4:5], off nt
	v_add_co_u32_e32 v4, vcc, 0x80000, v2
	s_nop 1
	v_addc_co_u32_e32 v5, vcc, 0, v3, vcc
	global_load_dword v14, v[4:5], off nt
	v_add_co_u32_e32 v4, vcc, 0x90000, v2
	s_nop 1
	v_addc_co_u32_e32 v5, vcc, 0, v3, vcc
	global_load_dword v15, v[4:5], off nt
	v_add_co_u32_e32 v4, vcc, 0xa0000, v2
	s_nop 1
	v_addc_co_u32_e32 v5, vcc, 0, v3, vcc
	global_load_dword v16, v[4:5], off nt
	v_add_co_u32_e32 v4, vcc, 0xb0000, v2
	s_nop 1
	v_addc_co_u32_e32 v5, vcc, 0, v3, vcc
	global_load_dword v17, v[4:5], off nt
	v_add_co_u32_e32 v4, vcc, 0xc0000, v2
	s_nop 1
	v_addc_co_u32_e32 v5, vcc, 0, v3, vcc
	global_load_dword v18, v[4:5], off nt
	v_add_co_u32_e32 v4, vcc, 0xd0000, v2
	s_nop 1
	v_addc_co_u32_e32 v5, vcc, 0, v3, vcc
	global_load_dword v19, v[4:5], off nt
	v_add_co_u32_e32 v4, vcc, 0xe0000, v2
	s_nop 1
	v_addc_co_u32_e32 v5, vcc, 0, v3, vcc
	global_load_dword v20, v[4:5], off nt
	v_add_co_u32_e32 v4, vcc, 0xf0000, v2
	s_nop 1
	v_addc_co_u32_e32 v5, vcc, 0, v3, vcc
	global_load_dword v21, v[4:5], off nt
	v_add_co_u32_e32 v4, vcc, 0x100000, v2
	s_nop 1
	v_addc_co_u32_e32 v5, vcc, 0, v3, vcc
	global_load_dword v34, v[4:5], off nt
	v_add_co_u32_e32 v4, vcc, 0x110000, v2
	s_nop 1
	v_addc_co_u32_e32 v5, vcc, 0, v3, vcc
	global_load_dword v35, v[4:5], off nt
	v_add_co_u32_e32 v4, vcc, 0x120000, v2
	s_nop 1
	v_addc_co_u32_e32 v5, vcc, 0, v3, vcc
	global_load_dword v36, v[4:5], off nt
	v_add_co_u32_e32 v4, vcc, 0x130000, v2
	s_nop 1
	v_addc_co_u32_e32 v5, vcc, 0, v3, vcc
	global_load_dword v37, v[4:5], off nt
	v_add_co_u32_e32 v4, vcc, 0x140000, v2
	s_nop 1
	v_addc_co_u32_e32 v5, vcc, 0, v3, vcc
	global_load_dword v38, v[4:5], off nt
	v_add_co_u32_e32 v4, vcc, 0x150000, v2
	s_nop 1
	v_addc_co_u32_e32 v5, vcc, 0, v3, vcc
	global_load_dword v39, v[4:5], off nt
	v_add_co_u32_e32 v4, vcc, 0x160000, v2
	s_nop 1
	v_addc_co_u32_e32 v5, vcc, 0, v3, vcc
	global_load_dword v40, v[4:5], off nt
	v_add_co_u32_e32 v4, vcc, 0x170000, v2
	s_nop 1
	v_addc_co_u32_e32 v5, vcc, 0, v3, vcc
	global_load_dword v41, v[4:5], off nt
	v_add_co_u32_e32 v4, vcc, 0x180000, v2
	s_nop 1
	v_addc_co_u32_e32 v5, vcc, 0, v3, vcc
	global_load_dword v42, v[4:5], off nt
	v_add_co_u32_e32 v4, vcc, 0x190000, v2
	s_nop 1
	v_addc_co_u32_e32 v5, vcc, 0, v3, vcc
	global_load_dword v43, v[4:5], off nt
	v_add_co_u32_e32 v4, vcc, 0x1a0000, v2
	s_nop 1
	v_addc_co_u32_e32 v5, vcc, 0, v3, vcc
	global_load_dword v54, v[4:5], off nt
	v_add_co_u32_e32 v4, vcc, 0x1b0000, v2
	s_nop 1
	v_addc_co_u32_e32 v5, vcc, 0, v3, vcc
	global_load_dword v55, v[4:5], off nt
	v_add_co_u32_e32 v4, vcc, 0x1c0000, v2
	s_nop 1
	v_addc_co_u32_e32 v5, vcc, 0, v3, vcc
	global_load_dword v56, v[4:5], off nt
	v_add_co_u32_e32 v4, vcc, 0x1d0000, v2
	s_nop 1
	v_addc_co_u32_e32 v5, vcc, 0, v3, vcc
	global_load_dword v57, v[4:5], off nt
	v_add_co_u32_e32 v4, vcc, 0x1e0000, v2
	s_nop 1
	v_addc_co_u32_e32 v5, vcc, 0, v3, vcc
	v_add_co_u32_e32 v2, vcc, 0x1f0000, v2
	global_load_dword v4, v[4:5], off nt
	s_nop 0
	v_addc_co_u32_e32 v3, vcc, 0, v3, vcc
	global_load_dword v2, v[2:3], off nt
	v_add_u32_e32 v3, 0x400, v46
	s_waitcnt vmcnt(30)
	ds_write2_b32 v46, v6, v7 offset1:66
	s_waitcnt vmcnt(28)
	ds_write2_b32 v46, v8, v9 offset0:132 offset1:198
	s_waitcnt vmcnt(26)
	ds_write2_b32 v3, v10, v11 offset0:8 offset1:74
	s_waitcnt vmcnt(24)
	ds_write2_b32 v3, v12, v13 offset0:140 offset1:206
	v_add_u32_e32 v3, 0x800, v46
	s_waitcnt vmcnt(22)
	ds_write2_b32 v3, v14, v15 offset0:16 offset1:82
	s_waitcnt vmcnt(20)
	ds_write2_b32 v3, v16, v17 offset0:148 offset1:214
	v_add_u32_e32 v3, 0xc00, v46
	s_waitcnt vmcnt(18)
	ds_write2_b32 v3, v18, v19 offset0:24 offset1:90
	s_waitcnt vmcnt(16)
	ds_write2_b32 v3, v20, v21 offset0:156 offset1:222
	v_add_u32_e32 v3, 0x1000, v46
	s_waitcnt vmcnt(14)
	ds_write2_b32 v3, v34, v35 offset0:32 offset1:98
	s_waitcnt vmcnt(12)
	ds_write2_b32 v3, v36, v37 offset0:164 offset1:230
	v_add_u32_e32 v3, 0x1400, v46
	s_waitcnt vmcnt(10)
	ds_write2_b32 v3, v38, v39 offset0:40 offset1:106
	s_waitcnt vmcnt(8)
	ds_write2_b32 v3, v40, v41 offset0:172 offset1:238
	v_add_u32_e32 v3, 0x1800, v46
	s_waitcnt vmcnt(6)
	ds_write2_b32 v3, v42, v43 offset0:48 offset1:114
	s_waitcnt vmcnt(4)
	ds_write2_b32 v3, v54, v55 offset0:180 offset1:246
	v_add_u32_e32 v3, 0x1c00, v46
	s_waitcnt vmcnt(2)
	ds_write2_b32 v3, v56, v57 offset0:56 offset1:122
	s_waitcnt vmcnt(0)
	ds_write2_b32 v3, v4, v2 offset0:188 offset1:254
	s_waitcnt lgkmcnt(0)
	s_and_b64 vcc, exec, s[18:19]
	v_mov_b32 v18, 0
	s_cbranch_vccz .LBB0_473
	s_lshl_b32 s74, s20, 2
	v_lshl_add_u64 v[6:7], v[26:27], 0, s[74:75]
	v_lshl_add_u64 v[2:3], v[28:29], 0, s[74:75]
	global_load_dwordx4 v[10:13], v[2:3], off offset:16
	global_load_dwordx4 v[14:17], v[2:3], off
	s_nop 0
	global_load_dwordx4 v[2:5], v[6:7], off offset:16
	s_nop 0
	global_load_dwordx4 v[6:9], v[6:7], off
	s_cbranch_execnz .LBB0_455

.LBB0_472:
	s_add_i32 s8, s38, 0xffffd800
	s_and_b32 s74, s8, 0xffffffc0
	s_add_i32 s8, s37, 0xfffb0000
	s_and_b32 s8, s8, 0x7e0
	s_waitcnt vmcnt(5) lgkmcnt(1)
	v_or_b32_e32 v3, s8, v44
	v_add_u32_e32 v2, s74, v45
	v_lshlrev_b32_e32 v210, 2, v3
	v_ashrrev_i32_e32 v3, 31, v2
	s_waitcnt lgkmcnt(0)
	v_lshl_add_u64 v[4:5], s[10:11], 0, v[210:211]
	v_lshlrev_b64 v[2:3], 13, v[2:3]
	v_lshl_add_u64 v[2:3], v[4:5], 0, v[2:3]
	v_add_co_u32_e32 v4, vcc, 0x4000, v2
	global_load_dword v6, v[2:3], off nt
	s_nop 0
	v_addc_co_u32_e32 v5, vcc, 0, v3, vcc
	global_load_dword v7, v[4:5], off nt
	v_add_co_u32_e32 v4, vcc, 0x8000, v2
	s_mov_b32 s9, 0x10000
	s_nop 0
	v_addc_co_u32_e32 v5, vcc, 0, v3, vcc
	global_load_dword v8, v[4:5], off nt
	v_add_co_u32_e32 v4, vcc, 0xc000, v2
	s_nop 1
	v_addc_co_u32_e32 v5, vcc, 0, v3, vcc
	global_load_dword v9, v[4:5], off nt
	v_add_co_u32_e32 v4, vcc, s9, v2
	s_mov_b32 s9, 0x14000
	s_nop 0
	v_addc_co_u32_e32 v5, vcc, 0, v3, vcc
	global_load_dword v10, v[4:5], off nt
	v_add_co_u32_e32 v4, vcc, s9, v2
	s_mov_b32 s9, 0x18000
	s_nop 0
	v_addc_co_u32_e32 v5, vcc, 0, v3, vcc
	global_load_dword v11, v[4:5], off nt
	v_add_co_u32_e32 v4, vcc, s9, v2
	s_mov_b32 s9, 0x1c000
	s_nop 0
	v_addc_co_u32_e32 v5, vcc, 0, v3, vcc
	global_load_dword v12, v[4:5], off nt
	v_add_co_u32_e32 v4, vcc, s9, v2
	s_mov_b32 s9, 0x20000
	s_nop 0
	v_addc_co_u32_e32 v5, vcc, 0, v3, vcc
	global_load_dword v13, v[4:5], off nt
	v_add_co_u32_e32 v4, vcc, s9, v2
	s_mov_b32 s9, 0x24000
	s_nop 0
	v_addc_co_u32_e32 v5, vcc, 0, v3, vcc
	global_load_dword v14, v[4:5], off nt
	v_add_co_u32_e32 v4, vcc, s9, v2
	s_mov_b32 s9, 0x28000
	s_nop 0
	v_addc_co_u32_e32 v5, vcc, 0, v3, vcc
	global_load_dword v15, v[4:5], off nt
	v_add_co_u32_e32 v4, vcc, s9, v2
	s_mov_b32 s9, 0x2c000
	s_nop 0
	v_addc_co_u32_e32 v5, vcc, 0, v3, vcc
	global_load_dword v16, v[4:5], off nt
	v_add_co_u32_e32 v4, vcc, s9, v2
	s_mov_b32 s9, 0x30000
	s_nop 0
	v_addc_co_u32_e32 v5, vcc, 0, v3, vcc
	global_load_dword v17, v[4:5], off nt
	v_add_co_u32_e32 v4, vcc, s9, v2
	s_mov_b32 s9, 0x34000
	s_nop 0
	v_addc_co_u32_e32 v5, vcc, 0, v3, vcc
	global_load_dword v18, v[4:5], off nt
	v_add_co_u32_e32 v4, vcc, s9, v2
	s_mov_b32 s9, 0x38000
	s_nop 0
	v_addc_co_u32_e32 v5, vcc, 0, v3, vcc
	global_load_dword v19, v[4:5], off nt
	v_add_co_u32_e32 v4, vcc, s9, v2
	s_mov_b32 s9, 0x3c000
	s_nop 0
	v_addc_co_u32_e32 v5, vcc, 0, v3, vcc
	global_load_dword v20, v[4:5], off nt
	v_add_co_u32_e32 v4, vcc, s9, v2
	s_mov_b32 s9, 0x40000
	s_nop 0
	v_addc_co_u32_e32 v5, vcc, 0, v3, vcc
	global_load_dword v21, v[4:5], off nt
	v_add_co_u32_e32 v4, vcc, s9, v2
	s_mov_b32 s9, 0x44000
	s_nop 0
	v_addc_co_u32_e32 v5, vcc, 0, v3, vcc
	global_load_dword v34, v[4:5], off nt
	v_add_co_u32_e32 v4, vcc, s9, v2
	s_mov_b32 s9, 0x48000
	s_nop 0
	v_addc_co_u32_e32 v5, vcc, 0, v3, vcc
	global_load_dword v35, v[4:5], off nt
	v_add_co_u32_e32 v4, vcc, s9, v2
	s_mov_b32 s9, 0x4c000
	s_nop 0
	v_addc_co_u32_e32 v5, vcc, 0, v3, vcc
	global_load_dword v36, v[4:5], off nt
	v_add_co_u32_e32 v4, vcc, s9, v2
	s_mov_b32 s9, 0x50000
	s_nop 0
	v_addc_co_u32_e32 v5, vcc, 0, v3, vcc
	global_load_dword v37, v[4:5], off nt
	v_add_co_u32_e32 v4, vcc, s9, v2
	s_mov_b32 s9, 0x54000
	s_nop 0
	v_addc_co_u32_e32 v5, vcc, 0, v3, vcc
	global_load_dword v38, v[4:5], off nt
	v_add_co_u32_e32 v4, vcc, s9, v2
	s_mov_b32 s9, 0x58000
	s_nop 0
	v_addc_co_u32_e32 v5, vcc, 0, v3, vcc
	global_load_dword v39, v[4:5], off nt
	v_add_co_u32_e32 v4, vcc, s9, v2
	s_mov_b32 s9, 0x5c000
	s_nop 0
	v_addc_co_u32_e32 v5, vcc, 0, v3, vcc
	global_load_dword v40, v[4:5], off nt
	v_add_co_u32_e32 v4, vcc, s9, v2
	s_mov_b32 s9, 0x60000
	s_nop 0
	v_addc_co_u32_e32 v5, vcc, 0, v3, vcc
	global_load_dword v41, v[4:5], off nt
	v_add_co_u32_e32 v4, vcc, s9, v2
	s_mov_b32 s9, 0x64000
	s_nop 0
	v_addc_co_u32_e32 v5, vcc, 0, v3, vcc
	global_load_dword v42, v[4:5], off nt
	v_add_co_u32_e32 v4, vcc, s9, v2
	s_mov_b32 s9, 0x68000
	s_nop 0
	v_addc_co_u32_e32 v5, vcc, 0, v3, vcc
	global_load_dword v43, v[4:5], off nt
	v_add_co_u32_e32 v4, vcc, s9, v2
	s_mov_b32 s9, 0x6c000
	s_nop 0
	v_addc_co_u32_e32 v5, vcc, 0, v3, vcc
	global_load_dword v54, v[4:5], off nt
	v_add_co_u32_e32 v4, vcc, s9, v2
	s_mov_b32 s9, 0x70000
	s_nop 0
	v_addc_co_u32_e32 v5, vcc, 0, v3, vcc
	global_load_dword v55, v[4:5], off nt
	v_add_co_u32_e32 v4, vcc, s9, v2
	s_mov_b32 s9, 0x74000
	s_nop 0
	v_addc_co_u32_e32 v5, vcc, 0, v3, vcc
	global_load_dword v56, v[4:5], off nt
	v_add_co_u32_e32 v4, vcc, s9, v2
	s_mov_b32 s9, 0x78000
	s_nop 0
	v_addc_co_u32_e32 v5, vcc, 0, v3, vcc
	global_load_dword v57, v[4:5], off nt
	v_add_co_u32_e32 v4, vcc, s9, v2
	s_mov_b32 s9, 0x7c000
	s_nop 0
	v_addc_co_u32_e32 v5, vcc, 0, v3, vcc
	v_add_co_u32_e32 v2, vcc, s9, v2
	global_load_dword v4, v[4:5], off nt
	s_nop 0
	v_addc_co_u32_e32 v3, vcc, 0, v3, vcc
	global_load_dword v2, v[2:3], off nt
	v_add_u32_e32 v3, 0x400, v46
	s_waitcnt vmcnt(30)
	ds_write2_b32 v46, v6, v7 offset1:66
	s_waitcnt vmcnt(28)
	ds_write2_b32 v46, v8, v9 offset0:132 offset1:198
	s_waitcnt vmcnt(26)
	ds_write2_b32 v3, v10, v11 offset0:8 offset1:74
	s_waitcnt vmcnt(24)
	ds_write2_b32 v3, v12, v13 offset0:140 offset1:206
	v_add_u32_e32 v3, 0x800, v46
	s_waitcnt vmcnt(22)
	ds_write2_b32 v3, v14, v15 offset0:16 offset1:82
	s_waitcnt vmcnt(20)
	ds_write2_b32 v3, v16, v17 offset0:148 offset1:214
	v_add_u32_e32 v3, 0xc00, v46
	s_waitcnt vmcnt(18)
	ds_write2_b32 v3, v18, v19 offset0:24 offset1:90
	s_waitcnt vmcnt(16)
	ds_write2_b32 v3, v20, v21 offset0:156 offset1:222
	v_add_u32_e32 v3, 0x1000, v46
	s_waitcnt vmcnt(14)
	ds_write2_b32 v3, v34, v35 offset0:32 offset1:98
	s_waitcnt vmcnt(12)
	ds_write2_b32 v3, v36, v37 offset0:164 offset1:230
	v_add_u32_e32 v3, 0x1400, v46
	s_waitcnt vmcnt(10)
	ds_write2_b32 v3, v38, v39 offset0:40 offset1:106
	s_waitcnt vmcnt(8)
	ds_write2_b32 v3, v40, v41 offset0:172 offset1:238
	v_add_u32_e32 v3, 0x1800, v46
	s_waitcnt vmcnt(6)
	ds_write2_b32 v3, v42, v43 offset0:48 offset1:114
	s_waitcnt vmcnt(4)
	ds_write2_b32 v3, v54, v55 offset0:180 offset1:246
	v_add_u32_e32 v3, 0x1c00, v46
	s_waitcnt vmcnt(2)
	ds_write2_b32 v3, v56, v57 offset0:56 offset1:122
	s_waitcnt vmcnt(0)
	ds_write2_b32 v3, v4, v2 offset0:188 offset1:254
	s_waitcnt lgkmcnt(0)
	v_mov_b32 v2, 0
	ds_read2_b32 v[8:9], v47 offset0:33 offset1:41
	ds_read2_b32 v[10:11], v47 offset1:8
	ds_read2_b32 v[12:13], v47 offset0:66 offset1:74
	ds_read2_b32 v[14:15], v47 offset0:99 offset1:107
	ds_read2_b32 v[16:17], v47 offset0:132 offset1:140
	ds_read2_b32 v[18:19], v47 offset0:165 offset1:173
	ds_read2_b32 v[20:21], v47 offset0:198 offset1:206
	ds_read2_b32 v[34:35], v47 offset0:231 offset1:239
	v_add_u32_e32 v36, s8, v22
	v_ashrrev_i32_e32 v37, 31, v36
	v_lshl_add_u64 v[6:7], s[74:75], 1, v[30:31]
	v_lshlrev_b64 v[36:37], 14, v[36:37]
	s_waitcnt lgkmcnt(6)
	v_cvt_pk_bf16_f32 v2, v10, v8
	v_lshl_add_u64 v[36:37], v[6:7], 0, v[36:37]
	v_add_u32_e32 v8, s8, v48
	s_waitcnt lgkmcnt(4)
	v_cvt_pk_bf16_f32 v3, v12, v14
	s_waitcnt lgkmcnt(2)
	v_cvt_pk_bf16_f32 v4, v16, v18
	s_waitcnt lgkmcnt(0)
	v_cvt_pk_bf16_f32 v5, v20, v34
	global_store_dwordx4 v[36:37], v[2:5], off
	v_add_u32_e32 v36, s8, v49
	v_ashrrev_i32_e32 v37, 31, v36
	v_cvt_pk_bf16_f32 v2, v11, v9
	v_ashrrev_i32_e32 v9, 31, v8
	v_lshlrev_b64 v[8:9], 14, v[8:9]
	v_lshl_add_u64 v[8:9], v[6:7], 0, v[8:9]
	v_cvt_pk_bf16_f32 v3, v13, v15
	v_cvt_pk_bf16_f32 v4, v17, v19
	v_cvt_pk_bf16_f32 v5, v21, v35
	global_store_dwordx4 v[8:9], v[2:5], off
	ds_read2_b32 v[8:9], v47 offset0:16 offset1:24
	ds_read2_b32 v[10:11], v47 offset0:49 offset1:57
	ds_read2_b32 v[12:13], v47 offset0:82 offset1:90
	ds_read2_b32 v[14:15], v47 offset0:115 offset1:123
	ds_read2_b32 v[16:17], v47 offset0:148 offset1:156
	ds_read2_b32 v[18:19], v47 offset0:181 offset1:189
	ds_read2_b32 v[20:21], v47 offset0:214 offset1:222
	ds_read2_b32 v[34:35], v47 offset0:247 offset1:255
	v_lshlrev_b64 v[36:37], 14, v[36:37]
	s_waitcnt lgkmcnt(6)
	v_cvt_pk_bf16_f32 v2, v8, v10
	v_lshl_add_u64 v[36:37], v[6:7], 0, v[36:37]
	v_add_u32_e32 v8, s8, v50
	s_waitcnt lgkmcnt(4)
	v_cvt_pk_bf16_f32 v3, v12, v14
	s_waitcnt lgkmcnt(2)
	v_cvt_pk_bf16_f32 v4, v16, v18
	s_waitcnt lgkmcnt(0)
	v_cvt_pk_bf16_f32 v5, v20, v34
	global_store_dwordx4 v[36:37], v[2:5], off
	s_nop 1
	v_cvt_pk_bf16_f32 v2, v9, v11
	v_ashrrev_i32_e32 v9, 31, v8
	v_lshlrev_b64 v[8:9], 14, v[8:9]
	v_lshl_add_u64 v[6:7], v[6:7], 0, v[8:9]
	v_cvt_pk_bf16_f32 v3, v13, v15
	v_cvt_pk_bf16_f32 v4, v17, v19
	v_cvt_pk_bf16_f32 v5, v21, v35
	global_store_dwordx4 v[6:7], v[2:5], off
	s_waitcnt lgkmcnt(0)
	s_branch .LBB0_447

.LBB0_479:
	s_cmpk_gt_u32 s26, 0xfff
	v_add_u32_e32 v45, 0x400, v42
	v_add_u32_e32 v44, 0x800, v42
	v_add_u32_e32 v43, 0xc00, v42
	v_add_u32_e32 v33, 0x1000, v42
	v_add_u32_e32 v32, 0x1400, v42
	v_add_u32_e32 v31, 0x1800, v42
	v_add_u32_e32 v30, 0x1c00, v42
	s_cbranch_scc1 .LBB0_489
	s_lshr_b32 s2, s26, 1
	s_and_b32 s3, s2, 0x7c0
	s_and_b32 s2, s18, 0xfe0
	v_or_b32_e32 v2, s2, v34
	v_add_u32_e32 v46, s3, v35
	v_lshlrev_b32_e32 v210, 2, v2
	s_waitcnt lgkmcnt(1)
	v_lshl_add_u64 v[2:3], s[0:1], 0, v[210:211]
	s_movk_i32 s6, 0x6000
	v_add_u32_e32 v6, 2, v46
	v_add_u32_e32 v8, 4, v46
	v_add_u32_e32 v10, 6, v46
	v_add_u32_e32 v12, 8, v46
	v_add_u32_e32 v14, 10, v46
	v_add_u32_e32 v16, 12, v46
	v_add_u32_e32 v28, 14, v46
	s_waitcnt lgkmcnt(0)
	v_mad_i64_i32 v[4:5], s[4:5], v46, s6, v[2:3]
	v_mad_i64_i32 v[6:7], s[4:5], v6, s6, v[2:3]
	v_mad_i64_i32 v[8:9], s[4:5], v8, s6, v[2:3]
	v_mad_i64_i32 v[10:11], s[4:5], v10, s6, v[2:3]
	v_mad_i64_i32 v[12:13], s[4:5], v12, s6, v[2:3]
	v_mad_i64_i32 v[14:15], s[4:5], v14, s6, v[2:3]
	v_mad_i64_i32 v[16:17], s[4:5], v16, s6, v[2:3]
	v_mad_i64_i32 v[28:29], s[4:5], v28, s6, v[2:3]
	global_load_dword v47, v[4:5], off nt
	global_load_dword v48, v[6:7], off nt
	global_load_dword v49, v[8:9], off nt
	global_load_dword v50, v[10:11], off nt
	global_load_dword v51, v[12:13], off nt
	global_load_dword v52, v[14:15], off nt
	global_load_dword v53, v[16:17], off nt
	global_load_dword v54, v[28:29], off nt
	v_add_u32_e32 v4, 16, v46
	v_add_u32_e32 v6, 18, v46
	v_add_u32_e32 v8, 20, v46
	v_add_u32_e32 v10, 22, v46
	v_add_u32_e32 v12, 24, v46
	v_add_u32_e32 v14, 26, v46
	v_add_u32_e32 v16, 28, v46
	v_add_u32_e32 v28, 30, v46
	v_mad_i64_i32 v[4:5], s[4:5], v4, s6, v[2:3]
	v_mad_i64_i32 v[6:7], s[4:5], v6, s6, v[2:3]
	v_mad_i64_i32 v[8:9], s[4:5], v8, s6, v[2:3]
	v_mad_i64_i32 v[10:11], s[4:5], v10, s6, v[2:3]
	v_mad_i64_i32 v[12:13], s[4:5], v12, s6, v[2:3]
	v_mad_i64_i32 v[14:15], s[4:5], v14, s6, v[2:3]
	v_mad_i64_i32 v[16:17], s[4:5], v16, s6, v[2:3]
	v_mad_i64_i32 v[28:29], s[4:5], v28, s6, v[2:3]
	global_load_dword v55, v[4:5], off nt
	global_load_dword v56, v[6:7], off nt
	global_load_dword v57, v[8:9], off nt
	global_load_dword v58, v[10:11], off nt
	global_load_dword v59, v[12:13], off nt
	global_load_dword v60, v[14:15], off nt
	global_load_dword v61, v[16:17], off nt
	global_load_dword v62, v[28:29], off nt
	v_add_u32_e32 v4, 32, v46
	v_add_u32_e32 v6, 34, v46
	v_add_u32_e32 v8, 36, v46
	v_add_u32_e32 v10, 38, v46
	v_add_u32_e32 v12, 40, v46
	v_add_u32_e32 v14, 42, v46
	v_add_u32_e32 v16, 44, v46
	v_add_u32_e32 v28, 46, v46
	v_mad_i64_i32 v[4:5], s[4:5], v4, s6, v[2:3]
	v_mad_i64_i32 v[6:7], s[4:5], v6, s6, v[2:3]
	v_mad_i64_i32 v[8:9], s[4:5], v8, s6, v[2:3]
	v_mad_i64_i32 v[10:11], s[4:5], v10, s6, v[2:3]
	v_mad_i64_i32 v[12:13], s[4:5], v12, s6, v[2:3]
	v_mad_i64_i32 v[14:15], s[4:5], v14, s6, v[2:3]
	v_mad_i64_i32 v[16:17], s[4:5], v16, s6, v[2:3]
	v_mad_i64_i32 v[28:29], s[4:5], v28, s6, v[2:3]
	global_load_dword v63, v[4:5], off nt
	global_load_dword v64, v[6:7], off nt
	global_load_dword v65, v[8:9], off nt
	global_load_dword v66, v[10:11], off nt
	global_load_dword v67, v[12:13], off nt
	global_load_dword v68, v[14:15], off nt
	global_load_dword v69, v[16:17], off nt
	s_nop 0
	global_load_dword v28, v[28:29], off nt
	v_add_u32_e32 v4, 48, v46
	v_add_u32_e32 v6, 50, v46
	v_add_u32_e32 v8, 52, v46
	v_add_u32_e32 v10, 54, v46
	v_add_u32_e32 v12, 56, v46
	v_add_u32_e32 v14, 58, v46
	v_add_u32_e32 v16, 60, v46
	v_add_u32_e32 v29, 62, v46
	v_mad_i64_i32 v[4:5], s[4:5], v4, s6, v[2:3]
	v_mad_i64_i32 v[6:7], s[4:5], v6, s6, v[2:3]
	v_mad_i64_i32 v[8:9], s[4:5], v8, s6, v[2:3]
	v_mad_i64_i32 v[10:11], s[4:5], v10, s6, v[2:3]
	v_mad_i64_i32 v[12:13], s[4:5], v12, s6, v[2:3]
	v_mad_i64_i32 v[14:15], s[4:5], v14, s6, v[2:3]
	v_mad_i64_i32 v[16:17], s[4:5], v16, s6, v[2:3]
	v_mad_i64_i32 v[2:3], s[4:5], v29, s6, v[2:3]
	global_load_dword v4, v[4:5], off nt
	s_nop 0
	global_load_dword v5, v[6:7], off nt
	s_nop 0
	global_load_dword v6, v[8:9], off nt
	global_load_dword v7, v[10:11], off nt
	s_nop 0
	global_load_dword v8, v[12:13], off nt
	global_load_dword v9, v[14:15], off nt
	global_load_dword v10, v[16:17], off nt
	s_nop 0
	global_load_dword v2, v[2:3], off nt
	s_waitcnt vmcnt(30)
	ds_write2_b32 v42, v47, v48 offset1:66
	s_waitcnt vmcnt(28)
	ds_write2_b32 v42, v49, v50 offset0:132 offset1:198
	s_waitcnt vmcnt(26)
	ds_write2_b32 v45, v51, v52 offset0:8 offset1:74
	s_waitcnt vmcnt(24)
	ds_write2_b32 v45, v53, v54 offset0:140 offset1:206
	s_waitcnt vmcnt(22)
	ds_write2_b32 v44, v55, v56 offset0:16 offset1:82
	s_waitcnt vmcnt(20)
	ds_write2_b32 v44, v57, v58 offset0:148 offset1:214
	s_waitcnt vmcnt(18)
	ds_write2_b32 v43, v59, v60 offset0:24 offset1:90
	s_waitcnt vmcnt(16)
	ds_write2_b32 v43, v61, v62 offset0:156 offset1:222
	s_waitcnt vmcnt(14)
	ds_write2_b32 v33, v63, v64 offset0:32 offset1:98
	s_waitcnt vmcnt(12)
	ds_write2_b32 v33, v65, v66 offset0:164 offset1:230
	s_waitcnt vmcnt(10)
	ds_write2_b32 v32, v67, v68 offset0:40 offset1:106
	s_waitcnt vmcnt(8)
	ds_write2_b32 v32, v69, v28 offset0:172 offset1:238
	s_waitcnt vmcnt(6)
	ds_write2_b32 v31, v4, v5 offset0:48 offset1:114
	s_waitcnt vmcnt(4)
	ds_write2_b32 v31, v6, v7 offset0:180 offset1:246
	s_waitcnt vmcnt(2)
	ds_write2_b32 v30, v8, v9 offset0:56 offset1:122
	s_waitcnt vmcnt(0)
	ds_write2_b32 v30, v10, v2 offset0:188 offset1:254
	s_waitcnt lgkmcnt(0)
	v_mov_b32 v2, 0
	s_lshl_b32 s74, s3, 2
	v_lshl_add_u64 v[2:3], v[20:21], 0, s[74:75]
	global_load_dwordx4 v[14:17], v[2:3], off
	global_load_dwordx4 v[10:13], v[2:3], off offset:16
	v_lshl_add_u64 v[2:3], v[18:19], 0, s[74:75]
	global_load_dwordx4 v[6:9], v[2:3], off
	s_nop 0
	global_load_dwordx4 v[2:5], v[2:3], off offset:16
	ds_read2_b32 v[46:47], v38 offset1:33
	ds_read2_b32 v[48:49], v38 offset0:66 offset1:99
	ds_read2_b32 v[54:55], v38 offset0:132 offset1:165
	ds_read2_b32 v[56:57], v38 offset0:198 offset1:231
	s_lshl_b32 s74, s3, 1
	s_lshl_b32 s3, s2, 2
	s_add_u32 s4, s10, s3
	s_addc_u32 s5, s11, 0
	v_lshl_add_u64 v[28:29], v[24:25], 0, s[74:75]
	s_add_u32 s6, s12, s3
	s_addc_u32 s7, s13, 0
	s_waitcnt vmcnt(3) lgkmcnt(3)
	v_mul_f32_e32 v50, v14, v46
	v_mul_f32_e32 v51, v15, v47
	v_cvt_pk_bf16_f32 v50, v50, v51
	s_waitcnt lgkmcnt(2)
	v_mul_f32_e32 v51, v16, v48
	v_mul_f32_e32 v52, v17, v49
	v_cvt_pk_bf16_f32 v51, v51, v52
	s_waitcnt vmcnt(2) lgkmcnt(1)
	v_mul_f32_e32 v52, v10, v54
	v_mul_f32_e32 v53, v11, v55
	v_cvt_pk_bf16_f32 v52, v52, v53
	s_waitcnt lgkmcnt(0)
	v_mul_f32_e32 v53, v12, v56
	v_mul_f32_e32 v58, v13, v57
	v_cvt_pk_bf16_f32 v53, v53, v58
	v_lshlrev_b32_e32 v58, 16, v50
	v_and_b32_e32 v59, 0xffff0000, v50
	s_waitcnt vmcnt(1)
	v_mul_f32_e32 v47, v7, v47
	v_add_f32_e32 v58, v58, v59
	v_lshlrev_b32_e32 v59, 16, v51
	v_and_b32_e32 v60, 0xffff0000, v51
	v_fmac_f32_e32 v47, v6, v46
	v_mul_f32_e32 v46, v9, v49
	v_add_f32_e32 v59, v59, v60
	v_fmac_f32_e32 v46, v8, v48
	v_add_f32_e32 v58, v58, v59
	v_lshlrev_b32_e32 v59, 16, v52
	v_and_b32_e32 v60, 0xffff0000, v52
	v_add_f32_e32 v46, v47, v46
	s_waitcnt vmcnt(0)
	v_mul_f32_e32 v47, v3, v55
	v_add_f32_e32 v59, v59, v60
	v_fmac_f32_e32 v47, v2, v54
	v_add_f32_e32 v58, v58, v59
	v_lshlrev_b32_e32 v59, 16, v53
	v_and_b32_e32 v60, 0xffff0000, v53
	v_add_f32_e32 v46, v46, v47
	v_mul_f32_e32 v47, v5, v57
	v_add_f32_e32 v59, v59, v60
	v_fmac_f32_e32 v47, v4, v56
	v_add_f32_e32 v58, v58, v59
	v_add_f32_e32 v46, v46, v47
	ds_bpermute_b32 v48, v1, v58
	ds_bpermute_b32 v47, v1, v46
	v_add_u32_e32 v54, s2, v22
	s_waitcnt lgkmcnt(1)
	v_add_f32_e32 v48, v58, v48
	s_waitcnt lgkmcnt(0)
	v_add_f32_e32 v55, v46, v47
	ds_bpermute_b32 v49, v36, v48
	ds_bpermute_b32 v56, v36, v55
	s_waitcnt lgkmcnt(1)
	v_add_f32_e32 v46, v48, v49
	s_waitcnt lgkmcnt(0)
	v_add_f32_e32 v48, v55, v56
	ds_bpermute_b32 v47, v37, v46
	ds_bpermute_b32 v49, v37, v48
	v_ashrrev_i32_e32 v55, 31, v54
	v_lshlrev_b64 v[54:55], 12, v[54:55]
	v_lshl_add_u64 v[54:55], v[28:29], 0, v[54:55]
	global_store_dwordx4 v[54:55], v[50:53], off
	s_and_saveexec_b64 s[8:9], vcc
	s_cbranch_execz .LBB0_482
	s_waitcnt lgkmcnt(1)
	v_add_f32_e32 v51, v46, v47
	v_lshlrev_b64 v[46:47], 2, v[22:23]
	s_waitcnt lgkmcnt(0)
	v_add_f32_e32 v50, v48, v49
	v_lshl_add_u64 v[48:49], s[4:5], 0, v[46:47]
	v_lshl_add_u64 v[46:47], s[6:7], 0, v[46:47]
	global_atomic_add_f32 v[48:49], v51, off
	global_atomic_add_f32 v[46:47], v50, off

.LBB0_489:
	s_cmpk_lt_i32 s26, 0x1000
	s_cbranch_scc1 .LBB0_478
	s_add_i32 s2, s26, 0xfffff000
	s_and_b32 s74, s2, 0xffffffc0
	s_add_i32 s2, s18, 0xfffe0000
	s_and_b32 s4, s2, 0x7e0
	v_or_b32_e32 v2, s4, v34
	v_lshlrev_b32_e32 v210, 2, v2
	v_add_u32_e32 v46, s74, v35
	s_waitcnt lgkmcnt(1)
	v_lshl_add_u64 v[2:3], s[0:1], 0, v[210:211]
	s_mov_b64 s[2:3], 0x4000
	v_lshl_add_u64 v[2:3], v[2:3], 0, s[2:3]
	s_movk_i32 s5, 0x6000
	v_add_u32_e32 v6, 2, v46
	v_add_u32_e32 v8, 4, v46
	v_add_u32_e32 v10, 6, v46
	v_add_u32_e32 v12, 8, v46
	v_add_u32_e32 v14, 10, v46
	v_add_u32_e32 v16, 12, v46
	v_add_u32_e32 v28, 14, v46
	s_waitcnt lgkmcnt(0)
	v_mad_i64_i32 v[4:5], s[2:3], v46, s5, v[2:3]
	v_mad_i64_i32 v[6:7], s[2:3], v6, s5, v[2:3]
	v_mad_i64_i32 v[8:9], s[2:3], v8, s5, v[2:3]
	v_mad_i64_i32 v[10:11], s[2:3], v10, s5, v[2:3]
	v_mad_i64_i32 v[12:13], s[2:3], v12, s5, v[2:3]
	v_mad_i64_i32 v[14:15], s[2:3], v14, s5, v[2:3]
	v_mad_i64_i32 v[16:17], s[2:3], v16, s5, v[2:3]
	v_mad_i64_i32 v[28:29], s[2:3], v28, s5, v[2:3]
	global_load_dword v47, v[4:5], off nt
	global_load_dword v48, v[6:7], off nt
	global_load_dword v49, v[8:9], off nt
	global_load_dword v50, v[10:11], off nt
	global_load_dword v51, v[12:13], off nt
	global_load_dword v52, v[14:15], off nt
	global_load_dword v53, v[16:17], off nt
	global_load_dword v54, v[28:29], off nt
	v_add_u32_e32 v4, 16, v46
	v_add_u32_e32 v6, 18, v46
	v_add_u32_e32 v8, 20, v46
	v_add_u32_e32 v10, 22, v46
	v_add_u32_e32 v12, 24, v46
	v_add_u32_e32 v14, 26, v46
	v_add_u32_e32 v16, 28, v46
	v_add_u32_e32 v28, 30, v46
	v_mad_i64_i32 v[4:5], s[2:3], v4, s5, v[2:3]
	v_mad_i64_i32 v[6:7], s[2:3], v6, s5, v[2:3]
	v_mad_i64_i32 v[8:9], s[2:3], v8, s5, v[2:3]
	v_mad_i64_i32 v[10:11], s[2:3], v10, s5, v[2:3]
	v_mad_i64_i32 v[12:13], s[2:3], v12, s5, v[2:3]
	v_mad_i64_i32 v[14:15], s[2:3], v14, s5, v[2:3]
	v_mad_i64_i32 v[16:17], s[2:3], v16, s5, v[2:3]
	v_mad_i64_i32 v[28:29], s[2:3], v28, s5, v[2:3]
	global_load_dword v55, v[4:5], off nt
	global_load_dword v56, v[6:7], off nt
	global_load_dword v57, v[8:9], off nt
	global_load_dword v58, v[10:11], off nt
	global_load_dword v59, v[12:13], off nt
	global_load_dword v60, v[14:15], off nt
	global_load_dword v61, v[16:17], off nt
	global_load_dword v62, v[28:29], off nt
	v_add_u32_e32 v4, 32, v46
	v_add_u32_e32 v6, 34, v46
	v_add_u32_e32 v8, 36, v46
	v_add_u32_e32 v10, 38, v46
	v_add_u32_e32 v12, 40, v46
	v_add_u32_e32 v14, 42, v46
	v_add_u32_e32 v16, 44, v46
	v_add_u32_e32 v28, 46, v46
	v_mad_i64_i32 v[4:5], s[2:3], v4, s5, v[2:3]
	v_mad_i64_i32 v[6:7], s[2:3], v6, s5, v[2:3]
	v_mad_i64_i32 v[8:9], s[2:3], v8, s5, v[2:3]
	v_mad_i64_i32 v[10:11], s[2:3], v10, s5, v[2:3]
	v_mad_i64_i32 v[12:13], s[2:3], v12, s5, v[2:3]
	v_mad_i64_i32 v[14:15], s[2:3], v14, s5, v[2:3]
	v_mad_i64_i32 v[16:17], s[2:3], v16, s5, v[2:3]
	v_mad_i64_i32 v[28:29], s[2:3], v28, s5, v[2:3]
	global_load_dword v63, v[4:5], off nt
	global_load_dword v64, v[6:7], off nt
	global_load_dword v65, v[8:9], off nt
	global_load_dword v66, v[10:11], off nt
	global_load_dword v67, v[12:13], off nt
	global_load_dword v68, v[14:15], off nt
	global_load_dword v69, v[16:17], off nt
	s_nop 0
	global_load_dword v28, v[28:29], off nt
	v_add_u32_e32 v4, 48, v46
	v_add_u32_e32 v6, 50, v46
	v_add_u32_e32 v8, 52, v46
	v_add_u32_e32 v10, 54, v46
	v_add_u32_e32 v12, 56, v46
	v_add_u32_e32 v14, 58, v46
	v_add_u32_e32 v16, 60, v46
	v_add_u32_e32 v29, 62, v46
	v_mad_i64_i32 v[4:5], s[2:3], v4, s5, v[2:3]
	v_mad_i64_i32 v[6:7], s[2:3], v6, s5, v[2:3]
	v_mad_i64_i32 v[8:9], s[2:3], v8, s5, v[2:3]
	v_mad_i64_i32 v[10:11], s[2:3], v10, s5, v[2:3]
	v_mad_i64_i32 v[12:13], s[2:3], v12, s5, v[2:3]
	v_mad_i64_i32 v[14:15], s[2:3], v14, s5, v[2:3]
	v_mad_i64_i32 v[16:17], s[2:3], v16, s5, v[2:3]
	v_mad_i64_i32 v[2:3], s[2:3], v29, s5, v[2:3]
	global_load_dword v4, v[4:5], off nt
	s_nop 0
	global_load_dword v5, v[6:7], off nt
	s_nop 0
	global_load_dword v6, v[8:9], off nt
	global_load_dword v7, v[10:11], off nt
	s_nop 0
	global_load_dword v8, v[12:13], off nt
	global_load_dword v9, v[14:15], off nt
	global_load_dword v10, v[16:17], off nt
	s_nop 0
	global_load_dword v2, v[2:3], off nt
	s_waitcnt vmcnt(30)
	ds_write2_b32 v42, v47, v48 offset1:66
	s_waitcnt vmcnt(28)
	ds_write2_b32 v42, v49, v50 offset0:132 offset1:198
	s_waitcnt vmcnt(26)
	ds_write2_b32 v45, v51, v52 offset0:8 offset1:74
	s_waitcnt vmcnt(24)
	ds_write2_b32 v45, v53, v54 offset0:140 offset1:206
	s_waitcnt vmcnt(22)
	ds_write2_b32 v44, v55, v56 offset0:16 offset1:82
	s_waitcnt vmcnt(20)
	ds_write2_b32 v44, v57, v58 offset0:148 offset1:214
	s_waitcnt vmcnt(18)
	ds_write2_b32 v43, v59, v60 offset0:24 offset1:90
	s_waitcnt vmcnt(16)
	ds_write2_b32 v43, v61, v62 offset0:156 offset1:222
	s_waitcnt vmcnt(14)
	ds_write2_b32 v33, v63, v64 offset0:32 offset1:98
	s_waitcnt vmcnt(12)
	ds_write2_b32 v33, v65, v66 offset0:164 offset1:230
	s_waitcnt vmcnt(10)
	ds_write2_b32 v32, v67, v68 offset0:40 offset1:106
	s_waitcnt vmcnt(8)
	ds_write2_b32 v32, v69, v28 offset0:172 offset1:238
	s_waitcnt vmcnt(6)
	ds_write2_b32 v31, v4, v5 offset0:48 offset1:114
	s_waitcnt vmcnt(4)
	ds_write2_b32 v31, v6, v7 offset0:180 offset1:246
	s_waitcnt vmcnt(2)
	ds_write2_b32 v30, v8, v9 offset0:56 offset1:122
	s_waitcnt vmcnt(0)
	ds_write2_b32 v30, v10, v2 offset0:188 offset1:254
	s_waitcnt lgkmcnt(0)
	v_mov_b32 v2, 0
	s_lshl_b64 s[2:3], s[74:75], 2
	v_lshl_add_u64 v[2:3], v[20:21], 0, s[2:3]
	global_load_dwordx4 v[14:17], v[2:3], off
	global_load_dwordx4 v[10:13], v[2:3], off offset:16
	v_lshl_add_u64 v[2:3], v[18:19], 0, s[2:3]
	global_load_dwordx4 v[6:9], v[2:3], off
	s_nop 0
	global_load_dwordx4 v[2:5], v[2:3], off offset:16
	ds_read2_b32 v[44:45], v38 offset1:33
	ds_read2_b32 v[46:47], v38 offset0:66 offset1:99
	ds_read2_b32 v[48:49], v38 offset0:132 offset1:165
	ds_read2_b32 v[50:51], v38 offset0:198 offset1:231
	v_lshl_add_u64 v[28:29], s[74:75], 1, v[26:27]
	s_lshl_b32 s5, s4, 2
	s_add_u32 s2, s14, s5
	s_addc_u32 s3, s15, 0
	s_add_u32 s6, s16, s5
	s_addc_u32 s7, s17, 0
	s_waitcnt vmcnt(3) lgkmcnt(3)
	v_mul_f32_e32 v30, v14, v44
	v_mul_f32_e32 v31, v15, v45
	v_cvt_pk_bf16_f32 v30, v30, v31
	s_waitcnt lgkmcnt(2)
	v_mul_f32_e32 v31, v16, v46
	v_mul_f32_e32 v32, v17, v47
	v_cvt_pk_bf16_f32 v31, v31, v32
	s_waitcnt vmcnt(2) lgkmcnt(1)
	v_mul_f32_e32 v32, v10, v48
	v_mul_f32_e32 v33, v11, v49
	v_cvt_pk_bf16_f32 v32, v32, v33
	s_waitcnt lgkmcnt(0)
	v_mul_f32_e32 v33, v12, v50
	v_mul_f32_e32 v43, v13, v51
	v_cvt_pk_bf16_f32 v33, v33, v43
	v_lshlrev_b32_e32 v43, 16, v30
	v_and_b32_e32 v52, 0xffff0000, v30
	s_waitcnt vmcnt(1)
	v_mul_f32_e32 v45, v7, v45
	v_add_f32_e32 v43, v43, v52
	v_lshlrev_b32_e32 v52, 16, v31
	v_and_b32_e32 v53, 0xffff0000, v31
	v_fmac_f32_e32 v45, v6, v44
	v_mul_f32_e32 v44, v9, v47
	v_add_f32_e32 v52, v52, v53
	v_fmac_f32_e32 v44, v8, v46
	v_add_f32_e32 v43, v43, v52
	v_lshlrev_b32_e32 v52, 16, v32
	v_and_b32_e32 v53, 0xffff0000, v32
	v_add_f32_e32 v44, v45, v44
	s_waitcnt vmcnt(0)
	v_mul_f32_e32 v45, v3, v49
	v_add_f32_e32 v52, v52, v53
	v_fmac_f32_e32 v45, v2, v48
	v_add_f32_e32 v43, v43, v52
	v_lshlrev_b32_e32 v52, 16, v33
	v_and_b32_e32 v53, 0xffff0000, v33
	v_add_f32_e32 v44, v44, v45
	v_mul_f32_e32 v45, v5, v51
	v_add_f32_e32 v52, v52, v53
	v_fmac_f32_e32 v45, v4, v50
	v_add_f32_e32 v43, v43, v52
	v_add_f32_e32 v47, v44, v45
	ds_bpermute_b32 v46, v1, v43
	ds_bpermute_b32 v48, v1, v47
	v_add_u32_e32 v44, s4, v22
	v_ashrrev_i32_e32 v45, 31, v44
	v_lshlrev_b64 v[44:45], 12, v[44:45]
	s_waitcnt lgkmcnt(1)
	v_add_f32_e32 v43, v43, v46
	s_waitcnt lgkmcnt(0)
	v_add_f32_e32 v47, v47, v48
	ds_bpermute_b32 v46, v36, v43
	ds_bpermute_b32 v50, v36, v47
	v_lshl_add_u64 v[48:49], v[28:29], 0, v[44:45]
	global_store_dwordx4 v[48:49], v[30:33], off
	s_waitcnt lgkmcnt(1)
	v_add_f32_e32 v43, v43, v46
	s_waitcnt lgkmcnt(0)
	v_add_f32_e32 v45, v47, v50
	ds_bpermute_b32 v44, v37, v43
	ds_bpermute_b32 v46, v37, v45
	v_lshlrev_b64 v[32:33], 2, v[22:23]
	v_lshl_add_u64 v[30:31], s[2:3], 0, v[32:33]
	v_lshl_add_u64 v[32:33], s[6:7], 0, v[32:33]
	s_and_saveexec_b64 s[2:3], vcc
	s_cbranch_execz .LBB0_492
	s_waitcnt lgkmcnt(1)
	v_add_f32_e32 v43, v43, v44
	s_waitcnt lgkmcnt(0)
	v_add_f32_e32 v45, v45, v46
	global_atomic_add_f32 v[30:31], v43, off
	global_atomic_add_f32 v[32:33], v45, off

.LBB0_754:
	s_and_b32 s9, s37, 0x7c0
	s_and_b32 s8, s36, 0x7e0
	s_waitcnt vmcnt(5) lgkmcnt(1)
	v_or_b32_e32 v3, s8, v1
	v_add_u32_e32 v2, s9, v44
	v_lshlrev_b32_e32 v210, 2, v3
	v_ashrrev_i32_e32 v3, 31, v2
	s_waitcnt lgkmcnt(0)
	v_lshl_add_u64 v[4:5], s[16:17], 0, v[210:211]
	v_lshlrev_b64 v[2:3], 13, v[2:3]
	v_lshl_add_u64 v[2:3], v[4:5], 0, v[2:3]
	v_add_co_u32_e32 v4, vcc, 0x4000, v2
	global_load_dword v6, v[2:3], off nt
	s_nop 0
	v_addc_co_u32_e32 v5, vcc, 0, v3, vcc
	global_load_dword v7, v[4:5], off nt
	v_add_co_u32_e32 v4, vcc, 0x8000, v2
	s_mov_b32 s20, 0x10000
	s_nop 0
	v_addc_co_u32_e32 v5, vcc, 0, v3, vcc
	global_load_dword v8, v[4:5], off nt
	v_add_co_u32_e32 v4, vcc, 0xc000, v2
	s_lshl_b32 s74, s9, 1
	s_nop 0
	v_addc_co_u32_e32 v5, vcc, 0, v3, vcc
	global_load_dword v9, v[4:5], off nt
	v_add_co_u32_e32 v4, vcc, s20, v2
	s_mov_b32 s20, 0x14000
	s_nop 0
	v_addc_co_u32_e32 v5, vcc, 0, v3, vcc
	global_load_dword v10, v[4:5], off nt
	v_add_co_u32_e32 v4, vcc, s20, v2
	s_mov_b32 s20, 0x18000
	s_nop 0
	v_addc_co_u32_e32 v5, vcc, 0, v3, vcc
	global_load_dword v11, v[4:5], off nt
	v_add_co_u32_e32 v4, vcc, s20, v2
	s_mov_b32 s20, 0x1c000
	s_nop 0
	v_addc_co_u32_e32 v5, vcc, 0, v3, vcc
	global_load_dword v12, v[4:5], off nt
	v_add_co_u32_e32 v4, vcc, s20, v2
	s_mov_b32 s20, 0x20000
	s_nop 0
	v_addc_co_u32_e32 v5, vcc, 0, v3, vcc
	global_load_dword v13, v[4:5], off nt
	v_add_co_u32_e32 v4, vcc, s20, v2
	s_mov_b32 s20, 0x24000
	s_nop 0
	v_addc_co_u32_e32 v5, vcc, 0, v3, vcc
	global_load_dword v14, v[4:5], off nt
	v_add_co_u32_e32 v4, vcc, s20, v2
	s_mov_b32 s20, 0x28000
	s_nop 0
	v_addc_co_u32_e32 v5, vcc, 0, v3, vcc
	global_load_dword v15, v[4:5], off nt
	v_add_co_u32_e32 v4, vcc, s20, v2
	s_mov_b32 s20, 0x2c000
	s_nop 0
	v_addc_co_u32_e32 v5, vcc, 0, v3, vcc
	global_load_dword v16, v[4:5], off nt
	v_add_co_u32_e32 v4, vcc, s20, v2
	s_mov_b32 s20, 0x30000
	s_nop 0
	v_addc_co_u32_e32 v5, vcc, 0, v3, vcc
	global_load_dword v17, v[4:5], off nt
	v_add_co_u32_e32 v4, vcc, s20, v2
	s_mov_b32 s20, 0x34000
	s_nop 0
	v_addc_co_u32_e32 v5, vcc, 0, v3, vcc
	global_load_dword v18, v[4:5], off nt
	v_add_co_u32_e32 v4, vcc, s20, v2
	s_mov_b32 s20, 0x38000
	s_nop 0
	v_addc_co_u32_e32 v5, vcc, 0, v3, vcc
	global_load_dword v19, v[4:5], off nt
	v_add_co_u32_e32 v4, vcc, s20, v2
	s_mov_b32 s20, 0x3c000
	s_nop 0
	v_addc_co_u32_e32 v5, vcc, 0, v3, vcc
	global_load_dword v20, v[4:5], off nt
	v_add_co_u32_e32 v4, vcc, s20, v2
	s_mov_b32 s20, 0x40000
	s_nop 0
	v_addc_co_u32_e32 v5, vcc, 0, v3, vcc
	global_load_dword v21, v[4:5], off nt
	v_add_co_u32_e32 v4, vcc, s20, v2
	s_mov_b32 s20, 0x44000
	s_nop 0
	v_addc_co_u32_e32 v5, vcc, 0, v3, vcc
	global_load_dword v34, v[4:5], off nt
	v_add_co_u32_e32 v4, vcc, s20, v2
	s_mov_b32 s20, 0x48000
	s_nop 0
	v_addc_co_u32_e32 v5, vcc, 0, v3, vcc
	global_load_dword v35, v[4:5], off nt
	v_add_co_u32_e32 v4, vcc, s20, v2
	s_mov_b32 s20, 0x4c000
	s_nop 0
	v_addc_co_u32_e32 v5, vcc, 0, v3, vcc
	global_load_dword v36, v[4:5], off nt
	v_add_co_u32_e32 v4, vcc, s20, v2
	s_mov_b32 s20, 0x50000
	s_nop 0
	v_addc_co_u32_e32 v5, vcc, 0, v3, vcc
	global_load_dword v37, v[4:5], off nt
	v_add_co_u32_e32 v4, vcc, s20, v2
	s_mov_b32 s20, 0x54000
	s_nop 0
	v_addc_co_u32_e32 v5, vcc, 0, v3, vcc
	global_load_dword v38, v[4:5], off nt
	v_add_co_u32_e32 v4, vcc, s20, v2
	s_mov_b32 s20, 0x58000
	s_nop 0
	v_addc_co_u32_e32 v5, vcc, 0, v3, vcc
	global_load_dword v39, v[4:5], off nt
	v_add_co_u32_e32 v4, vcc, s20, v2
	s_mov_b32 s20, 0x5c000
	s_nop 0
	v_addc_co_u32_e32 v5, vcc, 0, v3, vcc
	global_load_dword v40, v[4:5], off nt
	v_add_co_u32_e32 v4, vcc, s20, v2
	s_mov_b32 s20, 0x60000
	s_nop 0
	v_addc_co_u32_e32 v5, vcc, 0, v3, vcc
	global_load_dword v41, v[4:5], off nt
	v_add_co_u32_e32 v4, vcc, s20, v2
	s_mov_b32 s20, 0x64000
	s_nop 0
	v_addc_co_u32_e32 v5, vcc, 0, v3, vcc
	global_load_dword v42, v[4:5], off nt
	v_add_co_u32_e32 v4, vcc, s20, v2
	s_mov_b32 s20, 0x68000
	s_nop 0
	v_addc_co_u32_e32 v5, vcc, 0, v3, vcc
	global_load_dword v43, v[4:5], off nt
	v_add_co_u32_e32 v4, vcc, s20, v2
	s_mov_b32 s20, 0x6c000
	s_nop 0
	v_addc_co_u32_e32 v5, vcc, 0, v3, vcc
	global_load_dword v53, v[4:5], off nt
	v_add_co_u32_e32 v4, vcc, s20, v2
	s_mov_b32 s20, 0x70000
	s_nop 0
	v_addc_co_u32_e32 v5, vcc, 0, v3, vcc
	global_load_dword v54, v[4:5], off nt
	v_add_co_u32_e32 v4, vcc, s20, v2
	s_mov_b32 s20, 0x74000
	s_nop 0
	v_addc_co_u32_e32 v5, vcc, 0, v3, vcc
	global_load_dword v55, v[4:5], off nt
	v_add_co_u32_e32 v4, vcc, s20, v2
	s_mov_b32 s20, 0x78000
	s_nop 0
	v_addc_co_u32_e32 v5, vcc, 0, v3, vcc
	global_load_dword v56, v[4:5], off nt
	v_add_co_u32_e32 v4, vcc, s20, v2
	s_mov_b32 s20, 0x7c000
	s_nop 0
	v_addc_co_u32_e32 v5, vcc, 0, v3, vcc
	v_add_co_u32_e32 v2, vcc, s20, v2
	global_load_dword v4, v[4:5], off nt
	s_nop 0
	v_addc_co_u32_e32 v3, vcc, 0, v3, vcc
	global_load_dword v2, v[2:3], off nt
	v_add_u32_e32 v3, 0x400, v45
	s_waitcnt vmcnt(30)
	ds_write2_b32 v45, v6, v7 offset1:66
	s_waitcnt vmcnt(28)
	ds_write2_b32 v45, v8, v9 offset0:132 offset1:198
	s_waitcnt vmcnt(26)
	ds_write2_b32 v3, v10, v11 offset0:8 offset1:74
	s_waitcnt vmcnt(24)
	ds_write2_b32 v3, v12, v13 offset0:140 offset1:206
	v_add_u32_e32 v3, 0x800, v45
	s_waitcnt vmcnt(22)
	ds_write2_b32 v3, v14, v15 offset0:16 offset1:82
	s_waitcnt vmcnt(20)
	ds_write2_b32 v3, v16, v17 offset0:148 offset1:214
	v_add_u32_e32 v3, 0xc00, v45
	s_waitcnt vmcnt(18)
	ds_write2_b32 v3, v18, v19 offset0:24 offset1:90
	s_waitcnt vmcnt(16)
	ds_write2_b32 v3, v20, v21 offset0:156 offset1:222
	v_add_u32_e32 v3, 0x1000, v45
	s_waitcnt vmcnt(14)
	ds_write2_b32 v3, v34, v35 offset0:32 offset1:98
	s_waitcnt vmcnt(12)
	ds_write2_b32 v3, v36, v37 offset0:164 offset1:230
	v_add_u32_e32 v3, 0x1400, v45
	s_waitcnt vmcnt(10)
	ds_write2_b32 v3, v38, v39 offset0:40 offset1:106
	s_waitcnt vmcnt(8)
	ds_write2_b32 v3, v40, v41 offset0:172 offset1:238
	v_add_u32_e32 v3, 0x1800, v45
	s_waitcnt vmcnt(6)
	ds_write2_b32 v3, v42, v43 offset0:48 offset1:114
	s_waitcnt vmcnt(4)
	ds_write2_b32 v3, v53, v54 offset0:180 offset1:246
	v_add_u32_e32 v3, 0x1c00, v45
	s_waitcnt vmcnt(2)
	ds_write2_b32 v3, v55, v56 offset0:56 offset1:122
	s_waitcnt vmcnt(0)
	ds_write2_b32 v3, v4, v2 offset0:188 offset1:254
	s_waitcnt lgkmcnt(0)
	v_mov_b32 v2, 0
	ds_read2_b32 v[8:9], v46 offset0:33 offset1:41
	ds_read2_b32 v[10:11], v46 offset1:8
	ds_read2_b32 v[12:13], v46 offset0:66 offset1:74
	ds_read2_b32 v[14:15], v46 offset0:99 offset1:107
	ds_read2_b32 v[16:17], v46 offset0:132 offset1:140
	ds_read2_b32 v[18:19], v46 offset0:165 offset1:173
	ds_read2_b32 v[20:21], v46 offset0:198 offset1:206
	ds_read2_b32 v[34:35], v46 offset0:231 offset1:239
	v_add_u32_e32 v36, s8, v22
	v_ashrrev_i32_e32 v37, 31, v36
	v_lshl_add_u64 v[6:7], v[24:25], 0, s[74:75]
	v_lshlrev_b64 v[36:37], 12, v[36:37]
	s_waitcnt lgkmcnt(6)
	v_cvt_pk_bf16_f32 v2, v10, v8
	v_lshl_add_u64 v[36:37], v[6:7], 0, v[36:37]
	v_add_u32_e32 v8, s8, v47
	s_waitcnt lgkmcnt(4)
	v_cvt_pk_bf16_f32 v3, v12, v14
	s_waitcnt lgkmcnt(2)
	v_cvt_pk_bf16_f32 v4, v16, v18
	s_waitcnt lgkmcnt(0)
	v_cvt_pk_bf16_f32 v5, v20, v34
	global_store_dwordx4 v[36:37], v[2:5], off
	v_add_u32_e32 v36, s8, v48
	v_ashrrev_i32_e32 v37, 31, v36
	v_cvt_pk_bf16_f32 v2, v11, v9
	v_ashrrev_i32_e32 v9, 31, v8
	v_lshlrev_b64 v[8:9], 12, v[8:9]
	v_lshl_add_u64 v[8:9], v[6:7], 0, v[8:9]
	v_cvt_pk_bf16_f32 v3, v13, v15
	v_cvt_pk_bf16_f32 v4, v17, v19
	v_cvt_pk_bf16_f32 v5, v21, v35
	global_store_dwordx4 v[8:9], v[2:5], off
	ds_read2_b32 v[8:9], v46 offset0:16 offset1:24
	ds_read2_b32 v[10:11], v46 offset0:49 offset1:57
	ds_read2_b32 v[12:13], v46 offset0:82 offset1:90
	ds_read2_b32 v[14:15], v46 offset0:115 offset1:123
	ds_read2_b32 v[16:17], v46 offset0:148 offset1:156
	ds_read2_b32 v[18:19], v46 offset0:181 offset1:189
	ds_read2_b32 v[20:21], v46 offset0:214 offset1:222
	ds_read2_b32 v[34:35], v46 offset0:247 offset1:255
	v_lshlrev_b64 v[36:37], 12, v[36:37]
	s_waitcnt lgkmcnt(6)
	v_cvt_pk_bf16_f32 v2, v8, v10
	v_lshl_add_u64 v[36:37], v[6:7], 0, v[36:37]
	v_add_u32_e32 v8, s8, v49
	s_waitcnt lgkmcnt(4)
	v_cvt_pk_bf16_f32 v3, v12, v14
	s_waitcnt lgkmcnt(2)
	v_cvt_pk_bf16_f32 v4, v16, v18
	s_waitcnt lgkmcnt(0)
	v_cvt_pk_bf16_f32 v5, v20, v34
	global_store_dwordx4 v[36:37], v[2:5], off
	s_nop 1
	v_cvt_pk_bf16_f32 v2, v9, v11
	v_ashrrev_i32_e32 v9, 31, v8
	v_lshlrev_b64 v[8:9], 12, v[8:9]
	v_lshl_add_u64 v[6:7], v[6:7], 0, v[8:9]
	v_cvt_pk_bf16_f32 v3, v13, v15
	v_cvt_pk_bf16_f32 v4, v17, v19
	v_cvt_pk_bf16_f32 v5, v21, v35
	global_store_dwordx4 v[6:7], v[2:5], off
	s_waitcnt lgkmcnt(0)
	s_add_i32 s8, s37, 0xfffff800
	s_cmpk_gt_u32 s8, 0x1fff
	s_cbranch_scc1 .LBB0_753
.LBB0_755:
	s_lshr_b32 s8, s8, 2
	s_and_b32 s20, s8, 0x7c0
	s_and_b32 s28, s36, 0x1fe0
	s_waitcnt vmcnt(5) lgkmcnt(1)
	v_or_b32_e32 v3, s28, v1
	v_add_u32_e32 v2, s20, v44
	v_lshlrev_b32_e32 v210, 2, v3
	v_ashrrev_i32_e32 v3, 31, v2
	s_waitcnt lgkmcnt(0)
	v_lshl_add_u64 v[4:5], s[0:1], 0, v[210:211]
	v_lshlrev_b64 v[2:3], 15, v[2:3]
	v_lshl_add_u64 v[2:3], v[4:5], 0, v[2:3]
	v_add_co_u32_e32 v4, vcc, 0x10000, v2
	global_load_dword v6, v[2:3], off nt
	s_nop 0
	v_addc_co_u32_e32 v5, vcc, 0, v3, vcc
	global_load_dword v7, v[4:5], off nt
	v_add_co_u32_e32 v4, vcc, 0x20000, v2
	s_nop 1
	v_addc_co_u32_e32 v5, vcc, 0, v3, vcc
	global_load_dword v8, v[4:5], off nt
	v_add_co_u32_e32 v4, vcc, 0x30000, v2
	s_nop 1
	v_addc_co_u32_e32 v5, vcc, 0, v3, vcc
	global_load_dword v9, v[4:5], off nt
	v_add_co_u32_e32 v4, vcc, 0x40000, v2
	s_nop 1
	v_addc_co_u32_e32 v5, vcc, 0, v3, vcc
	global_load_dword v10, v[4:5], off nt
	v_add_co_u32_e32 v4, vcc, 0x50000, v2
	s_nop 1
	v_addc_co_u32_e32 v5, vcc, 0, v3, vcc
	global_load_dword v11, v[4:5], off nt
	v_add_co_u32_e32 v4, vcc, 0x60000, v2
	s_nop 1
	v_addc_co_u32_e32 v5, vcc, 0, v3, vcc
	global_load_dword v12, v[4:5], off nt
	v_add_co_u32_e32 v4, vcc, 0x70000, v2
	s_nop 1
	v_addc_co_u32_e32 v5, vcc, 0, v3, vcc
	global_load_dword v13, v[4:5], off nt
	v_add_co_u32_e32 v4, vcc, 0x80000, v2
	s_nop 1
	v_addc_co_u32_e32 v5, vcc, 0, v3, vcc
	global_load_dword v14, v[4:5], off nt
	v_add_co_u32_e32 v4, vcc, 0x90000, v2
	s_nop 1
	v_addc_co_u32_e32 v5, vcc, 0, v3, vcc
	global_load_dword v15, v[4:5], off nt
	v_add_co_u32_e32 v4, vcc, 0xa0000, v2
	s_nop 1
	v_addc_co_u32_e32 v5, vcc, 0, v3, vcc
	global_load_dword v16, v[4:5], off nt
	v_add_co_u32_e32 v4, vcc, 0xb0000, v2
	s_nop 1
	v_addc_co_u32_e32 v5, vcc, 0, v3, vcc
	global_load_dword v17, v[4:5], off nt
	v_add_co_u32_e32 v4, vcc, 0xc0000, v2
	s_nop 1
	v_addc_co_u32_e32 v5, vcc, 0, v3, vcc
	global_load_dword v18, v[4:5], off nt
	v_add_co_u32_e32 v4, vcc, 0xd0000, v2
	s_nop 1
	v_addc_co_u32_e32 v5, vcc, 0, v3, vcc
	global_load_dword v19, v[4:5], off nt
	v_add_co_u32_e32 v4, vcc, 0xe0000, v2
	s_nop 1
	v_addc_co_u32_e32 v5, vcc, 0, v3, vcc
	global_load_dword v20, v[4:5], off nt
	v_add_co_u32_e32 v4, vcc, 0xf0000, v2
	s_nop 1
	v_addc_co_u32_e32 v5, vcc, 0, v3, vcc
	global_load_dword v21, v[4:5], off nt
	v_add_co_u32_e32 v4, vcc, 0x100000, v2
	s_nop 1
	v_addc_co_u32_e32 v5, vcc, 0, v3, vcc
	global_load_dword v34, v[4:5], off nt
	v_add_co_u32_e32 v4, vcc, 0x110000, v2
	s_nop 1
	v_addc_co_u32_e32 v5, vcc, 0, v3, vcc
	global_load_dword v35, v[4:5], off nt
	v_add_co_u32_e32 v4, vcc, 0x120000, v2
	s_nop 1
	v_addc_co_u32_e32 v5, vcc, 0, v3, vcc
	global_load_dword v36, v[4:5], off nt
	v_add_co_u32_e32 v4, vcc, 0x130000, v2
	s_nop 1
	v_addc_co_u32_e32 v5, vcc, 0, v3, vcc
	global_load_dword v37, v[4:5], off nt
	v_add_co_u32_e32 v4, vcc, 0x140000, v2
	s_nop 1
	v_addc_co_u32_e32 v5, vcc, 0, v3, vcc
	global_load_dword v38, v[4:5], off nt
	v_add_co_u32_e32 v4, vcc, 0x150000, v2
	s_nop 1
	v_addc_co_u32_e32 v5, vcc, 0, v3, vcc
	global_load_dword v39, v[4:5], off nt
	v_add_co_u32_e32 v4, vcc, 0x160000, v2
	s_nop 1
	v_addc_co_u32_e32 v5, vcc, 0, v3, vcc
	global_load_dword v40, v[4:5], off nt
	v_add_co_u32_e32 v4, vcc, 0x170000, v2
	s_nop 1
	v_addc_co_u32_e32 v5, vcc, 0, v3, vcc
	global_load_dword v41, v[4:5], off nt
	v_add_co_u32_e32 v4, vcc, 0x180000, v2
	s_nop 1
	v_addc_co_u32_e32 v5, vcc, 0, v3, vcc
	global_load_dword v42, v[4:5], off nt
	v_add_co_u32_e32 v4, vcc, 0x190000, v2
	s_nop 1
	v_addc_co_u32_e32 v5, vcc, 0, v3, vcc
	global_load_dword v43, v[4:5], off nt
	v_add_co_u32_e32 v4, vcc, 0x1a0000, v2
	s_nop 1
	v_addc_co_u32_e32 v5, vcc, 0, v3, vcc
	global_load_dword v53, v[4:5], off nt
	v_add_co_u32_e32 v4, vcc, 0x1b0000, v2
	s_nop 1
	v_addc_co_u32_e32 v5, vcc, 0, v3, vcc
	global_load_dword v54, v[4:5], off nt
	v_add_co_u32_e32 v4, vcc, 0x1c0000, v2
	s_nop 1
	v_addc_co_u32_e32 v5, vcc, 0, v3, vcc
	global_load_dword v55, v[4:5], off nt
	v_add_co_u32_e32 v4, vcc, 0x1d0000, v2
	s_nop 1
	v_addc_co_u32_e32 v5, vcc, 0, v3, vcc
	global_load_dword v56, v[4:5], off nt
	v_add_co_u32_e32 v4, vcc, 0x1e0000, v2
	s_nop 1
	v_addc_co_u32_e32 v5, vcc, 0, v3, vcc
	v_add_co_u32_e32 v2, vcc, 0x1f0000, v2
	global_load_dword v4, v[4:5], off nt
	s_nop 0
	v_addc_co_u32_e32 v3, vcc, 0, v3, vcc
	global_load_dword v2, v[2:3], off nt
	v_add_u32_e32 v3, 0x400, v45
	s_waitcnt vmcnt(30)
	ds_write2_b32 v45, v6, v7 offset1:66
	s_waitcnt vmcnt(28)
	ds_write2_b32 v45, v8, v9 offset0:132 offset1:198
	s_waitcnt vmcnt(26)
	ds_write2_b32 v3, v10, v11 offset0:8 offset1:74
	s_waitcnt vmcnt(24)
	ds_write2_b32 v3, v12, v13 offset0:140 offset1:206
	v_add_u32_e32 v3, 0x800, v45
	s_waitcnt vmcnt(22)
	ds_write2_b32 v3, v14, v15 offset0:16 offset1:82
	s_waitcnt vmcnt(20)
	ds_write2_b32 v3, v16, v17 offset0:148 offset1:214
	v_add_u32_e32 v3, 0xc00, v45
	s_waitcnt vmcnt(18)
	ds_write2_b32 v3, v18, v19 offset0:24 offset1:90
	s_waitcnt vmcnt(16)
	ds_write2_b32 v3, v20, v21 offset0:156 offset1:222
	v_add_u32_e32 v3, 0x1000, v45
	s_waitcnt vmcnt(14)
	ds_write2_b32 v3, v34, v35 offset0:32 offset1:98
	s_waitcnt vmcnt(12)
	ds_write2_b32 v3, v36, v37 offset0:164 offset1:230
	v_add_u32_e32 v3, 0x1400, v45
	s_waitcnt vmcnt(10)
	ds_write2_b32 v3, v38, v39 offset0:40 offset1:106
	s_waitcnt vmcnt(8)
	ds_write2_b32 v3, v40, v41 offset0:172 offset1:238
	v_add_u32_e32 v3, 0x1800, v45
	s_waitcnt vmcnt(6)
	ds_write2_b32 v3, v42, v43 offset0:48 offset1:114
	s_waitcnt vmcnt(4)
	ds_write2_b32 v3, v53, v54 offset0:180 offset1:246
	v_add_u32_e32 v3, 0x1c00, v45
	s_waitcnt vmcnt(2)
	ds_write2_b32 v3, v55, v56 offset0:56 offset1:122
	s_waitcnt vmcnt(0)
	ds_write2_b32 v3, v4, v2 offset0:188 offset1:254
	s_waitcnt lgkmcnt(0)
	s_and_b64 vcc, exec, s[18:19]
	v_mov_b32 v18, 0
	s_cbranch_vccz .LBB0_776
	s_lshl_b32 s74, s20, 2
	v_lshl_add_u64 v[6:7], v[26:27], 0, s[74:75]
	v_lshl_add_u64 v[2:3], v[28:29], 0, s[74:75]
	global_load_dwordx4 v[10:13], v[2:3], off offset:16
	global_load_dwordx4 v[14:17], v[2:3], off
	s_nop 0
	global_load_dwordx4 v[2:5], v[6:7], off offset:16
	s_nop 0
	global_load_dwordx4 v[6:9], v[6:7], off
	s_cbranch_execnz .LBB0_758

.LBB0_775:
	s_add_i32 s8, s37, 0xffffd800
	s_and_b32 s74, s8, 0xffffffc0
	s_add_i32 s8, s36, 0xfffb0000
	s_and_b32 s8, s8, 0x7e0
	s_waitcnt vmcnt(5) lgkmcnt(1)
	v_or_b32_e32 v3, s8, v1
	v_add_u32_e32 v2, s74, v44
	v_lshlrev_b32_e32 v210, 2, v3
	v_ashrrev_i32_e32 v3, 31, v2
	s_waitcnt lgkmcnt(0)
	v_lshl_add_u64 v[4:5], s[10:11], 0, v[210:211]
	v_lshlrev_b64 v[2:3], 13, v[2:3]
	v_lshl_add_u64 v[2:3], v[4:5], 0, v[2:3]
	v_add_co_u32_e32 v4, vcc, 0x4000, v2
	global_load_dword v6, v[2:3], off nt
	s_nop 0
	v_addc_co_u32_e32 v5, vcc, 0, v3, vcc
	global_load_dword v7, v[4:5], off nt
	v_add_co_u32_e32 v4, vcc, 0x8000, v2
	s_mov_b32 s9, 0x10000
	s_nop 0
	v_addc_co_u32_e32 v5, vcc, 0, v3, vcc
	global_load_dword v8, v[4:5], off nt
	v_add_co_u32_e32 v4, vcc, 0xc000, v2
	s_nop 1
	v_addc_co_u32_e32 v5, vcc, 0, v3, vcc
	global_load_dword v9, v[4:5], off nt
	v_add_co_u32_e32 v4, vcc, s9, v2
	s_mov_b32 s9, 0x14000
	s_nop 0
	v_addc_co_u32_e32 v5, vcc, 0, v3, vcc
	global_load_dword v10, v[4:5], off nt
	v_add_co_u32_e32 v4, vcc, s9, v2
	s_mov_b32 s9, 0x18000
	s_nop 0
	v_addc_co_u32_e32 v5, vcc, 0, v3, vcc
	global_load_dword v11, v[4:5], off nt
	v_add_co_u32_e32 v4, vcc, s9, v2
	s_mov_b32 s9, 0x1c000
	s_nop 0
	v_addc_co_u32_e32 v5, vcc, 0, v3, vcc
	global_load_dword v12, v[4:5], off nt
	v_add_co_u32_e32 v4, vcc, s9, v2
	s_mov_b32 s9, 0x20000
	s_nop 0
	v_addc_co_u32_e32 v5, vcc, 0, v3, vcc
	global_load_dword v13, v[4:5], off nt
	v_add_co_u32_e32 v4, vcc, s9, v2
	s_mov_b32 s9, 0x24000
	s_nop 0
	v_addc_co_u32_e32 v5, vcc, 0, v3, vcc
	global_load_dword v14, v[4:5], off nt
	v_add_co_u32_e32 v4, vcc, s9, v2
	s_mov_b32 s9, 0x28000
	s_nop 0
	v_addc_co_u32_e32 v5, vcc, 0, v3, vcc
	global_load_dword v15, v[4:5], off nt
	v_add_co_u32_e32 v4, vcc, s9, v2
	s_mov_b32 s9, 0x2c000
	s_nop 0
	v_addc_co_u32_e32 v5, vcc, 0, v3, vcc
	global_load_dword v16, v[4:5], off nt
	v_add_co_u32_e32 v4, vcc, s9, v2
	s_mov_b32 s9, 0x30000
	s_nop 0
	v_addc_co_u32_e32 v5, vcc, 0, v3, vcc
	global_load_dword v17, v[4:5], off nt
	v_add_co_u32_e32 v4, vcc, s9, v2
	s_mov_b32 s9, 0x34000
	s_nop 0
	v_addc_co_u32_e32 v5, vcc, 0, v3, vcc
	global_load_dword v18, v[4:5], off nt
	v_add_co_u32_e32 v4, vcc, s9, v2
	s_mov_b32 s9, 0x38000
	s_nop 0
	v_addc_co_u32_e32 v5, vcc, 0, v3, vcc
	global_load_dword v19, v[4:5], off nt
	v_add_co_u32_e32 v4, vcc, s9, v2
	s_mov_b32 s9, 0x3c000
	s_nop 0
	v_addc_co_u32_e32 v5, vcc, 0, v3, vcc
	global_load_dword v20, v[4:5], off nt
	v_add_co_u32_e32 v4, vcc, s9, v2
	s_mov_b32 s9, 0x40000
	s_nop 0
	v_addc_co_u32_e32 v5, vcc, 0, v3, vcc
	global_load_dword v21, v[4:5], off nt
	v_add_co_u32_e32 v4, vcc, s9, v2
	s_mov_b32 s9, 0x44000
	s_nop 0
	v_addc_co_u32_e32 v5, vcc, 0, v3, vcc
	global_load_dword v34, v[4:5], off nt
	v_add_co_u32_e32 v4, vcc, s9, v2
	s_mov_b32 s9, 0x48000
	s_nop 0
	v_addc_co_u32_e32 v5, vcc, 0, v3, vcc
	global_load_dword v35, v[4:5], off nt
	v_add_co_u32_e32 v4, vcc, s9, v2
	s_mov_b32 s9, 0x4c000
	s_nop 0
	v_addc_co_u32_e32 v5, vcc, 0, v3, vcc
	global_load_dword v36, v[4:5], off nt
	v_add_co_u32_e32 v4, vcc, s9, v2
	s_mov_b32 s9, 0x50000
	s_nop 0
	v_addc_co_u32_e32 v5, vcc, 0, v3, vcc
	global_load_dword v37, v[4:5], off nt
	v_add_co_u32_e32 v4, vcc, s9, v2
	s_mov_b32 s9, 0x54000
	s_nop 0
	v_addc_co_u32_e32 v5, vcc, 0, v3, vcc
	global_load_dword v38, v[4:5], off nt
	v_add_co_u32_e32 v4, vcc, s9, v2
	s_mov_b32 s9, 0x58000
	s_nop 0
	v_addc_co_u32_e32 v5, vcc, 0, v3, vcc
	global_load_dword v39, v[4:5], off nt
	v_add_co_u32_e32 v4, vcc, s9, v2
	s_mov_b32 s9, 0x5c000
	s_nop 0
	v_addc_co_u32_e32 v5, vcc, 0, v3, vcc
	global_load_dword v40, v[4:5], off nt
	v_add_co_u32_e32 v4, vcc, s9, v2
	s_mov_b32 s9, 0x60000
	s_nop 0
	v_addc_co_u32_e32 v5, vcc, 0, v3, vcc
	global_load_dword v41, v[4:5], off nt
	v_add_co_u32_e32 v4, vcc, s9, v2
	s_mov_b32 s9, 0x64000
	s_nop 0
	v_addc_co_u32_e32 v5, vcc, 0, v3, vcc
	global_load_dword v42, v[4:5], off nt
	v_add_co_u32_e32 v4, vcc, s9, v2
	s_mov_b32 s9, 0x68000
	s_nop 0
	v_addc_co_u32_e32 v5, vcc, 0, v3, vcc
	global_load_dword v43, v[4:5], off nt
	v_add_co_u32_e32 v4, vcc, s9, v2
	s_mov_b32 s9, 0x6c000
	s_nop 0
	v_addc_co_u32_e32 v5, vcc, 0, v3, vcc
	global_load_dword v53, v[4:5], off nt
	v_add_co_u32_e32 v4, vcc, s9, v2
	s_mov_b32 s9, 0x70000
	s_nop 0
	v_addc_co_u32_e32 v5, vcc, 0, v3, vcc
	global_load_dword v54, v[4:5], off nt
	v_add_co_u32_e32 v4, vcc, s9, v2
	s_mov_b32 s9, 0x74000
	s_nop 0
	v_addc_co_u32_e32 v5, vcc, 0, v3, vcc
	global_load_dword v55, v[4:5], off nt
	v_add_co_u32_e32 v4, vcc, s9, v2
	s_mov_b32 s9, 0x78000
	s_nop 0
	v_addc_co_u32_e32 v5, vcc, 0, v3, vcc
	global_load_dword v56, v[4:5], off nt
	v_add_co_u32_e32 v4, vcc, s9, v2
	s_mov_b32 s9, 0x7c000
	s_nop 0
	v_addc_co_u32_e32 v5, vcc, 0, v3, vcc
	v_add_co_u32_e32 v2, vcc, s9, v2
	global_load_dword v4, v[4:5], off nt
	s_nop 0
	v_addc_co_u32_e32 v3, vcc, 0, v3, vcc
	global_load_dword v2, v[2:3], off nt
	v_add_u32_e32 v3, 0x400, v45
	s_waitcnt vmcnt(30)
	ds_write2_b32 v45, v6, v7 offset1:66
	s_waitcnt vmcnt(28)
	ds_write2_b32 v45, v8, v9 offset0:132 offset1:198
	s_waitcnt vmcnt(26)
	ds_write2_b32 v3, v10, v11 offset0:8 offset1:74
	s_waitcnt vmcnt(24)
	ds_write2_b32 v3, v12, v13 offset0:140 offset1:206
	v_add_u32_e32 v3, 0x800, v45
	s_waitcnt vmcnt(22)
	ds_write2_b32 v3, v14, v15 offset0:16 offset1:82
	s_waitcnt vmcnt(20)
	ds_write2_b32 v3, v16, v17 offset0:148 offset1:214
	v_add_u32_e32 v3, 0xc00, v45
	s_waitcnt vmcnt(18)
	ds_write2_b32 v3, v18, v19 offset0:24 offset1:90
	s_waitcnt vmcnt(16)
	ds_write2_b32 v3, v20, v21 offset0:156 offset1:222
	v_add_u32_e32 v3, 0x1000, v45
	s_waitcnt vmcnt(14)
	ds_write2_b32 v3, v34, v35 offset0:32 offset1:98
	s_waitcnt vmcnt(12)
	ds_write2_b32 v3, v36, v37 offset0:164 offset1:230
	v_add_u32_e32 v3, 0x1400, v45
	s_waitcnt vmcnt(10)
	ds_write2_b32 v3, v38, v39 offset0:40 offset1:106
	s_waitcnt vmcnt(8)
	ds_write2_b32 v3, v40, v41 offset0:172 offset1:238
	v_add_u32_e32 v3, 0x1800, v45
	s_waitcnt vmcnt(6)
	ds_write2_b32 v3, v42, v43 offset0:48 offset1:114
	s_waitcnt vmcnt(4)
	ds_write2_b32 v3, v53, v54 offset0:180 offset1:246
	v_add_u32_e32 v3, 0x1c00, v45
	s_waitcnt vmcnt(2)
	ds_write2_b32 v3, v55, v56 offset0:56 offset1:122
	s_waitcnt vmcnt(0)
	ds_write2_b32 v3, v4, v2 offset0:188 offset1:254
	s_waitcnt lgkmcnt(0)
	v_mov_b32 v2, 0
	ds_read2_b32 v[8:9], v46 offset0:33 offset1:41
	ds_read2_b32 v[10:11], v46 offset1:8
	ds_read2_b32 v[12:13], v46 offset0:66 offset1:74
	ds_read2_b32 v[14:15], v46 offset0:99 offset1:107
	ds_read2_b32 v[16:17], v46 offset0:132 offset1:140
	ds_read2_b32 v[18:19], v46 offset0:165 offset1:173
	ds_read2_b32 v[20:21], v46 offset0:198 offset1:206
	ds_read2_b32 v[34:35], v46 offset0:231 offset1:239
	v_add_u32_e32 v36, s8, v22
	v_ashrrev_i32_e32 v37, 31, v36
	v_lshl_add_u64 v[6:7], s[74:75], 1, v[30:31]
	v_lshlrev_b64 v[36:37], 14, v[36:37]
	s_waitcnt lgkmcnt(6)
	v_cvt_pk_bf16_f32 v2, v10, v8
	v_lshl_add_u64 v[36:37], v[6:7], 0, v[36:37]
	v_add_u32_e32 v8, s8, v47
	s_waitcnt lgkmcnt(4)
	v_cvt_pk_bf16_f32 v3, v12, v14
	s_waitcnt lgkmcnt(2)
	v_cvt_pk_bf16_f32 v4, v16, v18
	s_waitcnt lgkmcnt(0)
	v_cvt_pk_bf16_f32 v5, v20, v34
	global_store_dwordx4 v[36:37], v[2:5], off
	v_add_u32_e32 v36, s8, v48
	v_ashrrev_i32_e32 v37, 31, v36
	v_cvt_pk_bf16_f32 v2, v11, v9
	v_ashrrev_i32_e32 v9, 31, v8
	v_lshlrev_b64 v[8:9], 14, v[8:9]
	v_lshl_add_u64 v[8:9], v[6:7], 0, v[8:9]
	v_cvt_pk_bf16_f32 v3, v13, v15
	v_cvt_pk_bf16_f32 v4, v17, v19
	v_cvt_pk_bf16_f32 v5, v21, v35
	global_store_dwordx4 v[8:9], v[2:5], off
	ds_read2_b32 v[8:9], v46 offset0:16 offset1:24
	ds_read2_b32 v[10:11], v46 offset0:49 offset1:57
	ds_read2_b32 v[12:13], v46 offset0:82 offset1:90
	ds_read2_b32 v[14:15], v46 offset0:115 offset1:123
	ds_read2_b32 v[16:17], v46 offset0:148 offset1:156
	ds_read2_b32 v[18:19], v46 offset0:181 offset1:189
	ds_read2_b32 v[20:21], v46 offset0:214 offset1:222
	ds_read2_b32 v[34:35], v46 offset0:247 offset1:255
	v_lshlrev_b64 v[36:37], 14, v[36:37]
	s_waitcnt lgkmcnt(6)
	v_cvt_pk_bf16_f32 v2, v8, v10
	v_lshl_add_u64 v[36:37], v[6:7], 0, v[36:37]
	v_add_u32_e32 v8, s8, v49
	s_waitcnt lgkmcnt(4)
	v_cvt_pk_bf16_f32 v3, v12, v14
	s_waitcnt lgkmcnt(2)
	v_cvt_pk_bf16_f32 v4, v16, v18
	s_waitcnt lgkmcnt(0)
	v_cvt_pk_bf16_f32 v5, v20, v34
	global_store_dwordx4 v[36:37], v[2:5], off
	s_nop 1
	v_cvt_pk_bf16_f32 v2, v9, v11
	v_ashrrev_i32_e32 v9, 31, v8
	v_lshlrev_b64 v[8:9], 14, v[8:9]
	v_lshl_add_u64 v[6:7], v[6:7], 0, v[8:9]
	v_cvt_pk_bf16_f32 v3, v13, v15
	v_cvt_pk_bf16_f32 v4, v17, v19
	v_cvt_pk_bf16_f32 v5, v21, v35
	global_store_dwordx4 v[6:7], v[2:5], off
	s_waitcnt lgkmcnt(0)
	s_branch .LBB0_750

.LBB0_781:
	s_cmpk_gt_u32 s21, 0x7ff
	s_movk_i32 s27, 0x6040
	s_cbranch_scc1 .LBB0_791
	s_and_b32 s4, s20, 0x7e0
	s_and_b32 s5, s21, 0x7c0
	v_or_b32_e32 v2, s4, v1
	v_add_u32_e32 v23, s5, v68
	v_lshlrev_b32_e32 v210, 2, v2
	s_waitcnt lgkmcnt(1)
	v_lshl_add_u64 v[2:3], s[0:1], 0, v[210:211]
	v_add_u32_e32 v6, 2, v23
	v_add_u32_e32 v8, 4, v23
	v_add_u32_e32 v10, 6, v23
	v_add_u32_e32 v12, 8, v23
	v_add_u32_e32 v14, 10, v23
	v_add_u32_e32 v16, 12, v23
	v_add_u32_e32 v25, 14, v23
	s_waitcnt lgkmcnt(0)
	v_mad_i64_i32 v[4:5], s[2:3], v23, s27, v[2:3]
	v_mad_i64_i32 v[6:7], s[2:3], v6, s27, v[2:3]
	v_mad_i64_i32 v[8:9], s[2:3], v8, s27, v[2:3]
	v_mad_i64_i32 v[10:11], s[2:3], v10, s27, v[2:3]
	v_mad_i64_i32 v[12:13], s[2:3], v12, s27, v[2:3]
	v_mad_i64_i32 v[14:15], s[2:3], v14, s27, v[2:3]
	v_mad_i64_i32 v[16:17], s[2:3], v16, s27, v[2:3]
	v_mad_i64_i32 v[62:63], s[2:3], v25, s27, v[2:3]
	global_load_dword v25, v[4:5], off nt
	global_load_dword v27, v[6:7], off nt
	global_load_dword v29, v[8:9], off nt
	global_load_dword v64, v[10:11], off nt
	global_load_dword v65, v[12:13], off nt
	global_load_dword v66, v[14:15], off nt
	global_load_dword v67, v[16:17], off nt
	global_load_dword v74, v[62:63], off nt
	v_add_u32_e32 v4, 16, v23
	v_add_u32_e32 v6, 18, v23
	v_add_u32_e32 v8, 20, v23
	v_add_u32_e32 v10, 22, v23
	v_add_u32_e32 v12, 24, v23
	v_add_u32_e32 v14, 26, v23
	v_add_u32_e32 v16, 28, v23
	v_add_u32_e32 v62, 30, v23
	v_mad_i64_i32 v[4:5], s[2:3], v4, s27, v[2:3]
	v_mad_i64_i32 v[6:7], s[2:3], v6, s27, v[2:3]
	v_mad_i64_i32 v[8:9], s[2:3], v8, s27, v[2:3]
	v_mad_i64_i32 v[10:11], s[2:3], v10, s27, v[2:3]
	v_mad_i64_i32 v[12:13], s[2:3], v12, s27, v[2:3]
	v_mad_i64_i32 v[14:15], s[2:3], v14, s27, v[2:3]
	v_mad_i64_i32 v[16:17], s[2:3], v16, s27, v[2:3]
	v_mad_i64_i32 v[62:63], s[2:3], v62, s27, v[2:3]
	global_load_dword v75, v[4:5], off nt
	global_load_dword v76, v[6:7], off nt
	global_load_dword v77, v[8:9], off nt
	global_load_dword v78, v[10:11], off nt
	global_load_dword v79, v[12:13], off nt
	global_load_dword v80, v[14:15], off nt
	global_load_dword v81, v[16:17], off nt
	global_load_dword v82, v[62:63], off nt
	v_add_u32_e32 v4, 32, v23
	v_add_u32_e32 v6, 34, v23
	v_add_u32_e32 v8, 36, v23
	v_add_u32_e32 v10, 38, v23
	v_add_u32_e32 v12, 40, v23
	v_add_u32_e32 v14, 42, v23
	v_add_u32_e32 v16, 44, v23
	v_add_u32_e32 v62, 46, v23
	v_mad_i64_i32 v[4:5], s[2:3], v4, s27, v[2:3]
	v_mad_i64_i32 v[6:7], s[2:3], v6, s27, v[2:3]
	v_mad_i64_i32 v[8:9], s[2:3], v8, s27, v[2:3]
	v_mad_i64_i32 v[10:11], s[2:3], v10, s27, v[2:3]
	v_mad_i64_i32 v[12:13], s[2:3], v12, s27, v[2:3]
	v_mad_i64_i32 v[14:15], s[2:3], v14, s27, v[2:3]
	v_mad_i64_i32 v[16:17], s[2:3], v16, s27, v[2:3]
	v_mad_i64_i32 v[62:63], s[2:3], v62, s27, v[2:3]
	global_load_dword v83, v[4:5], off nt
	global_load_dword v84, v[6:7], off nt
	global_load_dword v85, v[8:9], off nt
	global_load_dword v86, v[10:11], off nt
	global_load_dword v87, v[12:13], off nt
	global_load_dword v88, v[14:15], off nt
	global_load_dword v89, v[16:17], off nt
	s_nop 0
	global_load_dword v62, v[62:63], off nt
	v_add_u32_e32 v4, 48, v23
	v_add_u32_e32 v6, 50, v23
	v_add_u32_e32 v8, 52, v23
	v_add_u32_e32 v10, 54, v23
	v_add_u32_e32 v12, 56, v23
	v_add_u32_e32 v14, 58, v23
	v_add_u32_e32 v16, 60, v23
	v_add_u32_e32 v23, 62, v23
	v_mad_i64_i32 v[4:5], s[2:3], v4, s27, v[2:3]
	v_mad_i64_i32 v[6:7], s[2:3], v6, s27, v[2:3]
	v_mad_i64_i32 v[8:9], s[2:3], v8, s27, v[2:3]
	v_mad_i64_i32 v[10:11], s[2:3], v10, s27, v[2:3]
	v_mad_i64_i32 v[12:13], s[2:3], v12, s27, v[2:3]
	v_mad_i64_i32 v[14:15], s[2:3], v14, s27, v[2:3]
	v_mad_i64_i32 v[16:17], s[2:3], v16, s27, v[2:3]
	v_mad_i64_i32 v[2:3], s[2:3], v23, s27, v[2:3]
	global_load_dword v4, v[4:5], off nt
	s_nop 0
	global_load_dword v5, v[6:7], off nt
	s_nop 0
	global_load_dword v6, v[8:9], off nt
	global_load_dword v7, v[10:11], off nt
	s_nop 0
	global_load_dword v8, v[12:13], off nt
	global_load_dword v9, v[14:15], off nt
	global_load_dword v10, v[16:17], off nt
	s_nop 0
	global_load_dword v2, v[2:3], off nt
	v_add_u32_e32 v3, 0x400, v69
	s_waitcnt vmcnt(30)
	ds_write2_b32 v69, v25, v27 offset1:66
	s_waitcnt vmcnt(28)
	ds_write2_b32 v69, v29, v64 offset0:132 offset1:198
	s_waitcnt vmcnt(26)
	ds_write2_b32 v3, v65, v66 offset0:8 offset1:74
	s_waitcnt vmcnt(24)
	ds_write2_b32 v3, v67, v74 offset0:140 offset1:206
	v_add_u32_e32 v3, 0x800, v69
	s_waitcnt vmcnt(22)
	ds_write2_b32 v3, v75, v76 offset0:16 offset1:82
	s_waitcnt vmcnt(20)
	ds_write2_b32 v3, v77, v78 offset0:148 offset1:214
	v_add_u32_e32 v3, 0xc00, v69
	s_waitcnt vmcnt(18)
	ds_write2_b32 v3, v79, v80 offset0:24 offset1:90
	s_waitcnt vmcnt(16)
	ds_write2_b32 v3, v81, v82 offset0:156 offset1:222
	v_add_u32_e32 v3, 0x1000, v69
	s_waitcnt vmcnt(14)
	ds_write2_b32 v3, v83, v84 offset0:32 offset1:98
	s_waitcnt vmcnt(12)
	ds_write2_b32 v3, v85, v86 offset0:164 offset1:230
	v_add_u32_e32 v3, 0x1400, v69
	s_waitcnt vmcnt(10)
	ds_write2_b32 v3, v87, v88 offset0:40 offset1:106
	s_waitcnt vmcnt(8)
	ds_write2_b32 v3, v89, v62 offset0:172 offset1:238
	v_add_u32_e32 v3, 0x1800, v69
	s_waitcnt vmcnt(6)
	ds_write2_b32 v3, v4, v5 offset0:48 offset1:114
	s_waitcnt vmcnt(4)
	ds_write2_b32 v3, v6, v7 offset0:180 offset1:246
	v_add_u32_e32 v3, 0x1c00, v69
	s_waitcnt vmcnt(2)
	ds_write2_b32 v3, v8, v9 offset0:56 offset1:122
	s_waitcnt vmcnt(0)
	ds_write2_b32 v3, v10, v2 offset0:188 offset1:254
	s_waitcnt lgkmcnt(0)
	v_mov_b32 v2, 0
	s_lshl_b32 s2, s5, 2
	s_mov_b32 s3, s75
	v_lshl_add_u64 v[2:3], v[20:21], 0, s[2:3]
	global_load_dwordx4 v[14:17], v[2:3], off
	global_load_dwordx4 v[10:13], v[2:3], off offset:16
	v_lshl_add_u64 v[2:3], v[18:19], 0, s[2:3]
	global_load_dwordx4 v[6:9], v[2:3], off
	s_nop 0
	global_load_dwordx4 v[2:5], v[2:3], off offset:16
	ds_read2_b32 v[74:75], v73 offset1:33
	ds_read2_b32 v[76:77], v73 offset0:66 offset1:99
	ds_read2_b32 v[78:79], v73 offset0:132 offset1:165
	ds_read2_b32 v[80:81], v73 offset0:198 offset1:231
	s_lshl_b32 s2, s5, 1
	s_lshl_b32 s5, s4, 2
	v_lshl_add_u64 v[62:63], v[58:59], 0, s[2:3]
	s_add_u32 s2, s8, s5
	s_addc_u32 s3, s9, 0
	s_add_u32 s22, s10, s5
	s_addc_u32 s23, s11, 0
	s_waitcnt vmcnt(3) lgkmcnt(3)
	v_mul_f32_e32 v23, v14, v74
	v_mul_f32_e32 v25, v15, v75
	v_cvt_pk_bf16_f32 v64, v23, v25
	s_waitcnt lgkmcnt(2)
	v_mul_f32_e32 v23, v16, v76
	v_mul_f32_e32 v25, v17, v77
	v_cvt_pk_bf16_f32 v65, v23, v25
	s_waitcnt vmcnt(2) lgkmcnt(1)
	v_mul_f32_e32 v23, v10, v78
	v_mul_f32_e32 v25, v11, v79
	v_cvt_pk_bf16_f32 v66, v23, v25
	s_waitcnt lgkmcnt(0)
	v_mul_f32_e32 v23, v12, v80
	v_mul_f32_e32 v25, v13, v81
	v_cvt_pk_bf16_f32 v67, v23, v25
	v_lshlrev_b32_e32 v23, 16, v64
	v_and_b32_e32 v25, 0xffff0000, v64
	v_add_f32_e32 v23, v23, v25
	v_lshlrev_b32_e32 v25, 16, v65
	v_and_b32_e32 v27, 0xffff0000, v65
	v_add_f32_e32 v25, v25, v27
	v_add_f32_e32 v23, v23, v25
	v_lshlrev_b32_e32 v25, 16, v66
	v_and_b32_e32 v27, 0xffff0000, v66
	v_add_f32_e32 v25, v25, v27
	v_add_f32_e32 v23, v23, v25
	v_lshlrev_b32_e32 v25, 16, v67
	v_and_b32_e32 v27, 0xffff0000, v67
	v_add_f32_e32 v25, v25, v27
	v_add_f32_e32 v23, v23, v25
	s_waitcnt vmcnt(1)
	v_mul_f32_e32 v25, v7, v75
	v_mul_f32_e32 v27, v9, v77
	v_fmac_f32_e32 v25, v6, v74
	v_fmac_f32_e32 v27, v8, v76
	v_add_f32_e32 v25, v25, v27
	s_waitcnt vmcnt(0)
	v_mul_f32_e32 v27, v3, v79
	v_fmac_f32_e32 v27, v2, v78
	v_add_f32_e32 v25, v25, v27
	v_mul_f32_e32 v27, v5, v81
	v_fmac_f32_e32 v27, v4, v80
	v_add_f32_e32 v25, v25, v27
	ds_bpermute_b32 v29, v70, v23
	ds_bpermute_b32 v27, v70, v25
	v_add_u32_e32 v74, s4, v22
	v_ashrrev_i32_e32 v75, 31, v74
	v_lshlrev_b64 v[74:75], 12, v[74:75]
	s_waitcnt lgkmcnt(1)
	v_add_f32_e32 v23, v23, v29
	s_waitcnt lgkmcnt(0)
	v_add_f32_e32 v27, v25, v27
	ds_bpermute_b32 v29, v71, v23
	ds_bpermute_b32 v76, v71, v27
	v_lshl_add_u64 v[74:75], v[62:63], 0, v[74:75]
	global_store_dwordx4 v[74:75], v[64:67], off
	s_waitcnt lgkmcnt(1)
	v_add_f32_e32 v23, v23, v29
	s_waitcnt lgkmcnt(0)
	v_add_f32_e32 v27, v27, v76
	ds_bpermute_b32 v25, v72, v23
	ds_bpermute_b32 v29, v72, v27
	v_lshl_add_u64 v[64:65], s[2:3], 0, v[34:35]
	v_lshl_add_u64 v[66:67], s[22:23], 0, v[34:35]
	s_and_saveexec_b64 s[2:3], vcc
	s_cbranch_execz .LBB0_784
	s_waitcnt lgkmcnt(1)
	v_add_f32_e32 v23, v23, v25
	s_waitcnt lgkmcnt(0)
	v_add_f32_e32 v27, v27, v29
	global_atomic_add_f32 v[64:65], v23, off
	global_atomic_add_f32 v[66:67], v27, off

.LBB0_791:
	s_and_b32 s2, s21, 0xfffff800
	s_cmpk_lg_i32 s2, 0x800
	s_cbranch_scc1 .LBB0_801
	s_and_b32 s22, s20, 0x7e0
	v_or_b32_e32 v2, s22, v1
	s_and_b32 s5, s21, 0x7c0
	v_lshlrev_b32_e32 v210, 2, v2
	v_add_u32_e32 v23, s5, v68
	s_waitcnt lgkmcnt(1)
	v_lshl_add_u64 v[2:3], s[0:1], 0, v[210:211]
	s_mov_b64 s[2:3], 0x4000
	v_lshl_add_u64 v[2:3], v[2:3], 0, s[2:3]
	v_add_u32_e32 v6, 2, v23
	v_add_u32_e32 v8, 4, v23
	v_add_u32_e32 v10, 6, v23
	v_add_u32_e32 v12, 8, v23
	v_add_u32_e32 v14, 10, v23
	v_add_u32_e32 v16, 12, v23
	v_add_u32_e32 v25, 14, v23
	s_waitcnt lgkmcnt(0)
	v_mad_i64_i32 v[4:5], s[2:3], v23, s27, v[2:3]
	v_mad_i64_i32 v[6:7], s[2:3], v6, s27, v[2:3]
	v_mad_i64_i32 v[8:9], s[2:3], v8, s27, v[2:3]
	v_mad_i64_i32 v[10:11], s[2:3], v10, s27, v[2:3]
	v_mad_i64_i32 v[12:13], s[2:3], v12, s27, v[2:3]
	v_mad_i64_i32 v[14:15], s[2:3], v14, s27, v[2:3]
	v_mad_i64_i32 v[16:17], s[2:3], v16, s27, v[2:3]
	v_mad_i64_i32 v[62:63], s[2:3], v25, s27, v[2:3]
	global_load_dword v25, v[4:5], off nt
	global_load_dword v27, v[6:7], off nt
	global_load_dword v29, v[8:9], off nt
	global_load_dword v64, v[10:11], off nt
	global_load_dword v65, v[12:13], off nt
	global_load_dword v66, v[14:15], off nt
	global_load_dword v67, v[16:17], off nt
	global_load_dword v74, v[62:63], off nt
	v_add_u32_e32 v4, 16, v23
	v_add_u32_e32 v6, 18, v23
	v_add_u32_e32 v8, 20, v23
	v_add_u32_e32 v10, 22, v23
	v_add_u32_e32 v12, 24, v23
	v_add_u32_e32 v14, 26, v23
	v_add_u32_e32 v16, 28, v23
	v_add_u32_e32 v62, 30, v23
	v_mad_i64_i32 v[4:5], s[2:3], v4, s27, v[2:3]
	v_mad_i64_i32 v[6:7], s[2:3], v6, s27, v[2:3]
	v_mad_i64_i32 v[8:9], s[2:3], v8, s27, v[2:3]
	v_mad_i64_i32 v[10:11], s[2:3], v10, s27, v[2:3]
	v_mad_i64_i32 v[12:13], s[2:3], v12, s27, v[2:3]
	v_mad_i64_i32 v[14:15], s[2:3], v14, s27, v[2:3]
	v_mad_i64_i32 v[16:17], s[2:3], v16, s27, v[2:3]
	v_mad_i64_i32 v[62:63], s[2:3], v62, s27, v[2:3]
	global_load_dword v75, v[4:5], off nt
	global_load_dword v76, v[6:7], off nt
	global_load_dword v77, v[8:9], off nt
	global_load_dword v78, v[10:11], off nt
	global_load_dword v79, v[12:13], off nt
	global_load_dword v80, v[14:15], off nt
	global_load_dword v81, v[16:17], off nt
	global_load_dword v82, v[62:63], off nt
	v_add_u32_e32 v4, 32, v23
	v_add_u32_e32 v6, 34, v23
	v_add_u32_e32 v8, 36, v23
	v_add_u32_e32 v10, 38, v23
	v_add_u32_e32 v12, 40, v23
	v_add_u32_e32 v14, 42, v23
	v_add_u32_e32 v16, 44, v23
	v_add_u32_e32 v62, 46, v23
	v_mad_i64_i32 v[4:5], s[2:3], v4, s27, v[2:3]
	v_mad_i64_i32 v[6:7], s[2:3], v6, s27, v[2:3]
	v_mad_i64_i32 v[8:9], s[2:3], v8, s27, v[2:3]
	v_mad_i64_i32 v[10:11], s[2:3], v10, s27, v[2:3]
	v_mad_i64_i32 v[12:13], s[2:3], v12, s27, v[2:3]
	v_mad_i64_i32 v[14:15], s[2:3], v14, s27, v[2:3]
	v_mad_i64_i32 v[16:17], s[2:3], v16, s27, v[2:3]
	v_mad_i64_i32 v[62:63], s[2:3], v62, s27, v[2:3]
	global_load_dword v83, v[4:5], off nt
	global_load_dword v84, v[6:7], off nt
	global_load_dword v85, v[8:9], off nt
	global_load_dword v86, v[10:11], off nt
	global_load_dword v87, v[12:13], off nt
	global_load_dword v88, v[14:15], off nt
	global_load_dword v89, v[16:17], off nt
	s_nop 0
	global_load_dword v62, v[62:63], off nt
	v_add_u32_e32 v4, 48, v23
	v_add_u32_e32 v6, 50, v23
	v_add_u32_e32 v8, 52, v23
	v_add_u32_e32 v10, 54, v23
	v_add_u32_e32 v12, 56, v23
	v_add_u32_e32 v14, 58, v23
	v_add_u32_e32 v16, 60, v23
	v_add_u32_e32 v23, 62, v23
	v_mad_i64_i32 v[4:5], s[2:3], v4, s27, v[2:3]
	v_mad_i64_i32 v[6:7], s[2:3], v6, s27, v[2:3]
	v_mad_i64_i32 v[8:9], s[2:3], v8, s27, v[2:3]
	v_mad_i64_i32 v[10:11], s[2:3], v10, s27, v[2:3]
	v_mad_i64_i32 v[12:13], s[2:3], v12, s27, v[2:3]
	v_mad_i64_i32 v[14:15], s[2:3], v14, s27, v[2:3]
	v_mad_i64_i32 v[16:17], s[2:3], v16, s27, v[2:3]
	v_mad_i64_i32 v[2:3], s[2:3], v23, s27, v[2:3]
	global_load_dword v4, v[4:5], off nt
	s_nop 0
	global_load_dword v5, v[6:7], off nt
	s_nop 0
	global_load_dword v6, v[8:9], off nt
	global_load_dword v7, v[10:11], off nt
	s_nop 0
	global_load_dword v8, v[12:13], off nt
	global_load_dword v9, v[14:15], off nt
	global_load_dword v10, v[16:17], off nt
	s_nop 0
	global_load_dword v2, v[2:3], off nt
	v_add_u32_e32 v3, 0x400, v69
	s_waitcnt vmcnt(30)
	ds_write2_b32 v69, v25, v27 offset1:66
	s_waitcnt vmcnt(28)
	ds_write2_b32 v69, v29, v64 offset0:132 offset1:198
	s_waitcnt vmcnt(26)
	ds_write2_b32 v3, v65, v66 offset0:8 offset1:74
	s_waitcnt vmcnt(24)
	ds_write2_b32 v3, v67, v74 offset0:140 offset1:206
	v_add_u32_e32 v3, 0x800, v69
	s_waitcnt vmcnt(22)
	ds_write2_b32 v3, v75, v76 offset0:16 offset1:82
	s_waitcnt vmcnt(20)
	ds_write2_b32 v3, v77, v78 offset0:148 offset1:214
	v_add_u32_e32 v3, 0xc00, v69
	s_waitcnt vmcnt(18)
	ds_write2_b32 v3, v79, v80 offset0:24 offset1:90
	s_waitcnt vmcnt(16)
	ds_write2_b32 v3, v81, v82 offset0:156 offset1:222
	v_add_u32_e32 v3, 0x1000, v69
	s_waitcnt vmcnt(14)
	ds_write2_b32 v3, v83, v84 offset0:32 offset1:98
	s_waitcnt vmcnt(12)
	ds_write2_b32 v3, v85, v86 offset0:164 offset1:230
	v_add_u32_e32 v3, 0x1400, v69
	s_waitcnt vmcnt(10)
	ds_write2_b32 v3, v87, v88 offset0:40 offset1:106
	s_waitcnt vmcnt(8)
	ds_write2_b32 v3, v89, v62 offset0:172 offset1:238
	v_add_u32_e32 v3, 0x1800, v69
	s_waitcnt vmcnt(6)
	ds_write2_b32 v3, v4, v5 offset0:48 offset1:114
	s_waitcnt vmcnt(4)
	ds_write2_b32 v3, v6, v7 offset0:180 offset1:246
	v_add_u32_e32 v3, 0x1c00, v69
	s_waitcnt vmcnt(2)
	ds_write2_b32 v3, v8, v9 offset0:56 offset1:122
	s_waitcnt vmcnt(0)
	ds_write2_b32 v3, v10, v2 offset0:188 offset1:254
	s_waitcnt lgkmcnt(0)
	v_mov_b32 v2, 0
	s_lshl_b32 s2, s5, 2
	s_mov_b32 s3, s75
	v_lshl_add_u64 v[2:3], v[20:21], 0, s[2:3]
	global_load_dwordx4 v[14:17], v[2:3], off
	global_load_dwordx4 v[10:13], v[2:3], off offset:16
	v_lshl_add_u64 v[2:3], v[18:19], 0, s[2:3]
	global_load_dwordx4 v[6:9], v[2:3], off
	s_nop 0
	global_load_dwordx4 v[2:5], v[2:3], off offset:16
	ds_read2_b32 v[74:75], v73 offset1:33
	ds_read2_b32 v[76:77], v73 offset0:66 offset1:99
	ds_read2_b32 v[78:79], v73 offset0:132 offset1:165
	ds_read2_b32 v[80:81], v73 offset0:198 offset1:231
	s_or_b32 s4, s22, 0x800
	s_lshl_b32 s2, s5, 1
	s_lshl_b32 s5, s22, 2
	v_lshl_add_u64 v[62:63], v[58:59], 0, s[2:3]
	s_add_u32 s2, s12, s5
	s_addc_u32 s3, s13, 0
	s_add_u32 s22, s14, s5
	s_addc_u32 s23, s15, 0
	s_waitcnt vmcnt(3) lgkmcnt(3)
	v_mul_f32_e32 v23, v14, v74
	v_mul_f32_e32 v25, v15, v75
	v_cvt_pk_bf16_f32 v64, v23, v25
	s_waitcnt lgkmcnt(2)
	v_mul_f32_e32 v23, v16, v76
	v_mul_f32_e32 v25, v17, v77
	v_cvt_pk_bf16_f32 v65, v23, v25
	s_waitcnt vmcnt(2) lgkmcnt(1)
	v_mul_f32_e32 v23, v10, v78
	v_mul_f32_e32 v25, v11, v79
	v_cvt_pk_bf16_f32 v66, v23, v25
	s_waitcnt lgkmcnt(0)
	v_mul_f32_e32 v23, v12, v80
	v_mul_f32_e32 v25, v13, v81
	v_cvt_pk_bf16_f32 v67, v23, v25
	v_lshlrev_b32_e32 v23, 16, v64
	v_and_b32_e32 v25, 0xffff0000, v64
	v_add_f32_e32 v23, v23, v25
	v_lshlrev_b32_e32 v25, 16, v65
	v_and_b32_e32 v27, 0xffff0000, v65
	v_add_f32_e32 v25, v25, v27
	v_add_f32_e32 v23, v23, v25
	v_lshlrev_b32_e32 v25, 16, v66
	v_and_b32_e32 v27, 0xffff0000, v66
	v_add_f32_e32 v25, v25, v27
	v_add_f32_e32 v23, v23, v25
	v_lshlrev_b32_e32 v25, 16, v67
	v_and_b32_e32 v27, 0xffff0000, v67
	v_add_f32_e32 v25, v25, v27
	v_add_f32_e32 v23, v23, v25
	s_waitcnt vmcnt(1)
	v_mul_f32_e32 v25, v7, v75
	v_mul_f32_e32 v27, v9, v77
	v_fmac_f32_e32 v25, v6, v74
	v_fmac_f32_e32 v27, v8, v76
	v_add_f32_e32 v25, v25, v27
	s_waitcnt vmcnt(0)
	v_mul_f32_e32 v27, v3, v79
	v_fmac_f32_e32 v27, v2, v78
	v_add_f32_e32 v25, v25, v27
	v_mul_f32_e32 v27, v5, v81
	v_fmac_f32_e32 v27, v4, v80
	v_add_f32_e32 v25, v25, v27
	ds_bpermute_b32 v29, v70, v23
	ds_bpermute_b32 v27, v70, v25
	v_add_u32_e32 v74, s4, v22
	v_ashrrev_i32_e32 v75, 31, v74
	v_lshlrev_b64 v[74:75], 12, v[74:75]
	s_waitcnt lgkmcnt(1)
	v_add_f32_e32 v23, v23, v29
	s_waitcnt lgkmcnt(0)
	v_add_f32_e32 v27, v25, v27
	ds_bpermute_b32 v29, v71, v23
	ds_bpermute_b32 v76, v71, v27
	v_lshl_add_u64 v[74:75], v[62:63], 0, v[74:75]
	global_store_dwordx4 v[74:75], v[64:67], off
	s_waitcnt lgkmcnt(1)
	v_add_f32_e32 v23, v23, v29
	s_waitcnt lgkmcnt(0)
	v_add_f32_e32 v27, v27, v76
	ds_bpermute_b32 v25, v72, v23
	ds_bpermute_b32 v29, v72, v27
	v_lshl_add_u64 v[64:65], s[2:3], 0, v[34:35]
	v_lshl_add_u64 v[66:67], s[22:23], 0, v[34:35]
	s_and_saveexec_b64 s[2:3], vcc
	s_cbranch_execz .LBB0_794
	s_waitcnt lgkmcnt(1)
	v_add_f32_e32 v23, v23, v25
	s_waitcnt lgkmcnt(0)
	v_add_f32_e32 v27, v27, v29
	global_atomic_add_f32 v[64:65], v23, off
	global_atomic_add_f32 v[66:67], v27, off

.LBB0_875:
	s_cmpk_lt_i32 s21, 0x1020
	s_cbranch_scc1 .LBB0_780
	s_add_i32 s2, s21, 0xffffefe0
	s_and_b32 s4, s2, 0xffffffc0
	s_add_i32 s2, s20, 0xfffdfc00
	s_and_b32 s22, s2, 0x7e0
	v_or_b32_e32 v2, s22, v1
	v_lshlrev_b32_e32 v210, 2, v2
	v_add_u32_e32 v23, s4, v68
	s_waitcnt lgkmcnt(1)
	v_lshl_add_u64 v[2:3], s[0:1], 0, v[210:211]
	s_mov_b64 s[2:3], 0x2000
	v_lshl_add_u64 v[2:3], v[2:3], 0, s[2:3]
	v_add_u32_e32 v6, 2, v23
	v_add_u32_e32 v8, 4, v23
	v_add_u32_e32 v10, 6, v23
	v_add_u32_e32 v12, 8, v23
	v_add_u32_e32 v14, 10, v23
	v_add_u32_e32 v16, 12, v23
	v_add_u32_e32 v25, 14, v23
	s_waitcnt lgkmcnt(0)
	v_mad_i64_i32 v[4:5], s[2:3], v23, s27, v[2:3]
	v_mad_i64_i32 v[6:7], s[2:3], v6, s27, v[2:3]
	v_mad_i64_i32 v[8:9], s[2:3], v8, s27, v[2:3]
	v_mad_i64_i32 v[10:11], s[2:3], v10, s27, v[2:3]
	v_mad_i64_i32 v[12:13], s[2:3], v12, s27, v[2:3]
	v_mad_i64_i32 v[14:15], s[2:3], v14, s27, v[2:3]
	v_mad_i64_i32 v[16:17], s[2:3], v16, s27, v[2:3]
	v_mad_i64_i32 v[62:63], s[2:3], v25, s27, v[2:3]
	global_load_dword v25, v[4:5], off nt
	global_load_dword v27, v[6:7], off nt
	global_load_dword v29, v[8:9], off nt
	global_load_dword v64, v[10:11], off nt
	global_load_dword v65, v[12:13], off nt
	global_load_dword v66, v[14:15], off nt
	global_load_dword v67, v[16:17], off nt
	global_load_dword v74, v[62:63], off nt
	v_add_u32_e32 v4, 16, v23
	v_add_u32_e32 v6, 18, v23
	v_add_u32_e32 v8, 20, v23
	v_add_u32_e32 v10, 22, v23
	v_add_u32_e32 v12, 24, v23
	v_add_u32_e32 v14, 26, v23
	v_add_u32_e32 v16, 28, v23
	v_add_u32_e32 v62, 30, v23
	v_mad_i64_i32 v[4:5], s[2:3], v4, s27, v[2:3]
	v_mad_i64_i32 v[6:7], s[2:3], v6, s27, v[2:3]
	v_mad_i64_i32 v[8:9], s[2:3], v8, s27, v[2:3]
	v_mad_i64_i32 v[10:11], s[2:3], v10, s27, v[2:3]
	v_mad_i64_i32 v[12:13], s[2:3], v12, s27, v[2:3]
	v_mad_i64_i32 v[14:15], s[2:3], v14, s27, v[2:3]
	v_mad_i64_i32 v[16:17], s[2:3], v16, s27, v[2:3]
	v_mad_i64_i32 v[62:63], s[2:3], v62, s27, v[2:3]
	global_load_dword v75, v[4:5], off nt
	global_load_dword v76, v[6:7], off nt
	global_load_dword v77, v[8:9], off nt
	global_load_dword v78, v[10:11], off nt
	global_load_dword v79, v[12:13], off nt
	global_load_dword v80, v[14:15], off nt
	global_load_dword v81, v[16:17], off nt
	global_load_dword v82, v[62:63], off nt
	v_add_u32_e32 v4, 32, v23
	v_add_u32_e32 v6, 34, v23
	v_add_u32_e32 v8, 36, v23
	v_add_u32_e32 v10, 38, v23
	v_add_u32_e32 v12, 40, v23
	v_add_u32_e32 v14, 42, v23
	v_add_u32_e32 v16, 44, v23
	v_add_u32_e32 v62, 46, v23
	v_mad_i64_i32 v[4:5], s[2:3], v4, s27, v[2:3]
	v_mad_i64_i32 v[6:7], s[2:3], v6, s27, v[2:3]
	v_mad_i64_i32 v[8:9], s[2:3], v8, s27, v[2:3]
	v_mad_i64_i32 v[10:11], s[2:3], v10, s27, v[2:3]
	v_mad_i64_i32 v[12:13], s[2:3], v12, s27, v[2:3]
	v_mad_i64_i32 v[14:15], s[2:3], v14, s27, v[2:3]
	v_mad_i64_i32 v[16:17], s[2:3], v16, s27, v[2:3]
	v_mad_i64_i32 v[62:63], s[2:3], v62, s27, v[2:3]
	global_load_dword v83, v[4:5], off nt
	global_load_dword v84, v[6:7], off nt
	global_load_dword v85, v[8:9], off nt
	global_load_dword v86, v[10:11], off nt
	global_load_dword v87, v[12:13], off nt
	global_load_dword v88, v[14:15], off nt
	global_load_dword v89, v[16:17], off nt
	s_nop 0
	global_load_dword v62, v[62:63], off nt
	v_add_u32_e32 v4, 48, v23
	v_add_u32_e32 v6, 50, v23
	v_add_u32_e32 v8, 52, v23
	v_add_u32_e32 v10, 54, v23
	v_add_u32_e32 v12, 56, v23
	v_add_u32_e32 v14, 58, v23
	v_add_u32_e32 v16, 60, v23
	v_add_u32_e32 v23, 62, v23
	v_mad_i64_i32 v[4:5], s[2:3], v4, s27, v[2:3]
	v_mad_i64_i32 v[6:7], s[2:3], v6, s27, v[2:3]
	v_mad_i64_i32 v[8:9], s[2:3], v8, s27, v[2:3]
	v_mad_i64_i32 v[10:11], s[2:3], v10, s27, v[2:3]
	v_mad_i64_i32 v[12:13], s[2:3], v12, s27, v[2:3]
	v_mad_i64_i32 v[14:15], s[2:3], v14, s27, v[2:3]
	v_mad_i64_i32 v[16:17], s[2:3], v16, s27, v[2:3]
	v_mad_i64_i32 v[2:3], s[2:3], v23, s27, v[2:3]
	global_load_dword v4, v[4:5], off nt
	s_nop 0
	global_load_dword v5, v[6:7], off nt
	s_nop 0
	global_load_dword v6, v[8:9], off nt
	global_load_dword v7, v[10:11], off nt
	s_nop 0
	global_load_dword v8, v[12:13], off nt
	global_load_dword v9, v[14:15], off nt
	global_load_dword v10, v[16:17], off nt
	s_nop 0
	global_load_dword v2, v[2:3], off nt
	v_add_u32_e32 v3, 0x400, v69
	s_waitcnt vmcnt(30)
	ds_write2_b32 v69, v25, v27 offset1:66
	s_waitcnt vmcnt(28)
	ds_write2_b32 v69, v29, v64 offset0:132 offset1:198
	s_waitcnt vmcnt(26)
	ds_write2_b32 v3, v65, v66 offset0:8 offset1:74
	s_waitcnt vmcnt(24)
	ds_write2_b32 v3, v67, v74 offset0:140 offset1:206
	v_add_u32_e32 v3, 0x800, v69
	s_waitcnt vmcnt(22)
	ds_write2_b32 v3, v75, v76 offset0:16 offset1:82
	s_waitcnt vmcnt(20)
	ds_write2_b32 v3, v77, v78 offset0:148 offset1:214
	v_add_u32_e32 v3, 0xc00, v69
	s_waitcnt vmcnt(18)
	ds_write2_b32 v3, v79, v80 offset0:24 offset1:90
	s_waitcnt vmcnt(16)
	ds_write2_b32 v3, v81, v82 offset0:156 offset1:222
	v_add_u32_e32 v3, 0x1000, v69
	s_waitcnt vmcnt(14)
	ds_write2_b32 v3, v83, v84 offset0:32 offset1:98
	s_waitcnt vmcnt(12)
	ds_write2_b32 v3, v85, v86 offset0:164 offset1:230
	v_add_u32_e32 v3, 0x1400, v69
	s_waitcnt vmcnt(10)
	ds_write2_b32 v3, v87, v88 offset0:40 offset1:106
	s_waitcnt vmcnt(8)
	ds_write2_b32 v3, v89, v62 offset0:172 offset1:238
	v_add_u32_e32 v3, 0x1800, v69
	s_waitcnt vmcnt(6)
	ds_write2_b32 v3, v4, v5 offset0:48 offset1:114
	s_waitcnt vmcnt(4)
	ds_write2_b32 v3, v6, v7 offset0:180 offset1:246
	v_add_u32_e32 v3, 0x1c00, v69
	s_waitcnt vmcnt(2)
	ds_write2_b32 v3, v8, v9 offset0:56 offset1:122
	s_waitcnt vmcnt(0)
	ds_write2_b32 v3, v10, v2 offset0:188 offset1:254
	s_waitcnt lgkmcnt(0)
	s_mov_b32 s5, s75
	v_mov_b32 v2, 0
	s_lshl_b64 s[2:3], s[4:5], 2
	v_lshl_add_u64 v[2:3], v[20:21], 0, s[2:3]
	global_load_dwordx4 v[14:17], v[2:3], off
	global_load_dwordx4 v[10:13], v[2:3], off offset:16
	v_lshl_add_u64 v[2:3], v[18:19], 0, s[2:3]
	global_load_dwordx4 v[6:9], v[2:3], off
	s_nop 0
	global_load_dwordx4 v[2:5], v[2:3], off offset:16
	ds_read2_b32 v[74:75], v73 offset1:33
	ds_read2_b32 v[76:77], v73 offset0:66 offset1:99
	ds_read2_b32 v[78:79], v73 offset0:132 offset1:165
	ds_read2_b32 v[80:81], v73 offset0:198 offset1:231
	v_lshl_add_u64 v[62:63], s[4:5], 1, v[60:61]
	s_lshl_b32 s4, s22, 2
	s_add_u32 s2, s16, s4
	s_addc_u32 s3, s17, 0
	s_add_u32 s4, s18, s4
	s_addc_u32 s5, s19, 0
	s_waitcnt vmcnt(3) lgkmcnt(3)
	v_mul_f32_e32 v23, v14, v74
	v_mul_f32_e32 v25, v15, v75
	v_cvt_pk_bf16_f32 v64, v23, v25
	s_waitcnt lgkmcnt(2)
	v_mul_f32_e32 v23, v16, v76
	v_mul_f32_e32 v25, v17, v77
	v_cvt_pk_bf16_f32 v65, v23, v25
	s_waitcnt vmcnt(2) lgkmcnt(1)
	v_mul_f32_e32 v23, v10, v78
	v_mul_f32_e32 v25, v11, v79
	v_cvt_pk_bf16_f32 v66, v23, v25
	s_waitcnt lgkmcnt(0)
	v_mul_f32_e32 v23, v12, v80
	v_mul_f32_e32 v25, v13, v81
	v_cvt_pk_bf16_f32 v67, v23, v25
	v_lshlrev_b32_e32 v23, 16, v64
	v_and_b32_e32 v25, 0xffff0000, v64
	v_add_f32_e32 v23, v23, v25
	v_lshlrev_b32_e32 v25, 16, v65
	v_and_b32_e32 v27, 0xffff0000, v65
	v_add_f32_e32 v25, v25, v27
	v_add_f32_e32 v23, v23, v25
	v_lshlrev_b32_e32 v25, 16, v66
	v_and_b32_e32 v27, 0xffff0000, v66
	v_add_f32_e32 v25, v25, v27
	v_add_f32_e32 v23, v23, v25
	v_lshlrev_b32_e32 v25, 16, v67
	v_and_b32_e32 v27, 0xffff0000, v67
	v_add_f32_e32 v25, v25, v27
	v_add_f32_e32 v23, v23, v25
	s_waitcnt vmcnt(1)
	v_mul_f32_e32 v25, v7, v75
	v_mul_f32_e32 v27, v9, v77
	v_fmac_f32_e32 v25, v6, v74
	v_fmac_f32_e32 v27, v8, v76
	v_add_f32_e32 v25, v25, v27
	s_waitcnt vmcnt(0)
	v_mul_f32_e32 v27, v3, v79
	v_fmac_f32_e32 v27, v2, v78
	v_add_f32_e32 v25, v25, v27
	v_mul_f32_e32 v27, v5, v81
	v_fmac_f32_e32 v27, v4, v80
	v_add_f32_e32 v25, v25, v27
	ds_bpermute_b32 v29, v70, v23
	ds_bpermute_b32 v27, v70, v25
	v_add_u32_e32 v74, s22, v22
	v_ashrrev_i32_e32 v75, 31, v74
	v_lshlrev_b64 v[74:75], 12, v[74:75]
	s_waitcnt lgkmcnt(1)
	v_add_f32_e32 v23, v23, v29
	s_waitcnt lgkmcnt(0)
	v_add_f32_e32 v27, v25, v27
	ds_bpermute_b32 v29, v71, v23
	ds_bpermute_b32 v76, v71, v27
	v_lshl_add_u64 v[74:75], v[62:63], 0, v[74:75]
	global_store_dwordx4 v[74:75], v[64:67], off
	s_waitcnt lgkmcnt(1)
	v_add_f32_e32 v23, v23, v29
	s_waitcnt lgkmcnt(0)
	v_add_f32_e32 v27, v27, v76
	ds_bpermute_b32 v25, v72, v23
	ds_bpermute_b32 v29, v72, v27
	v_lshl_add_u64 v[64:65], s[2:3], 0, v[34:35]
	v_lshl_add_u64 v[66:67], s[4:5], 0, v[34:35]
	s_and_saveexec_b64 s[2:3], vcc
	s_cbranch_execz .LBB0_878
	s_waitcnt lgkmcnt(1)
	v_add_f32_e32 v23, v23, v25
	s_waitcnt lgkmcnt(0)
	v_add_f32_e32 v27, v27, v29
	global_atomic_add_f32 v[64:65], v23, off
	global_atomic_add_f32 v[66:67], v27, off

.LBB0_956:
	s_add_u32 s10, s34, 0x100
	s_addc_u32 s11, s35, 0
	s_add_i32 s63, 0, 0x10000
	s_cmp_eq_u32 s62, 28
	s_cselect_b32 s47, s2, s11
	s_cselect_b32 s46, s3, s10
	s_cselect_b32 s43, s31, s61
	s_cselect_b32 s42, s37, s60
	s_add_i32 s66, 0, 0x14000
	v_add_u32_e32 v78, s63, v251
	v_add_u32_e32 v94, s66, v251
	ds_read_b128 v[66:69], v78
	ds_read_b128 v[70:73], v78 offset:1024
	ds_read_b128 v[74:77], v78 offset:2048
	ds_read_b128 v[78:81], v78 offset:3072
	ds_read_b128 v[82:85], v94
	ds_read_b128 v[86:89], v94 offset:1024
	ds_read_b128 v[90:93], v94 offset:2048
	ds_read_b128 v[94:97], v94 offset:3072
	v_lshl_add_u64 v[194:195], s[34:35], 0, v[218:219]
	s_add_i32 m0, s51, 0xc000
	ds_read_b128 v[162:165], v244
	ds_read_b128 v[166:169], v244 offset:1024
	ds_read_b128 v[170:173], v244 offset:2048
	ds_read_b128 v[174:177], v244 offset:3072
	ds_read_b128 v[178:181], v244 offset:4096
	ds_read_b128 v[182:185], v244 offset:5120
	ds_read_b128 v[186:189], v244 offset:6144
	ds_read_b128 v[190:193], v244 offset:7168
	global_load_lds_dwordx4 v[194:195], off
	v_lshl_add_u64 v[194:195], s[34:35], 0, v[220:221]
	s_add_i32 m0, s51, 0xe000
	s_nop 0
	global_load_lds_dwordx4 v[194:195], off
	s_waitcnt vmcnt(8)
	s_waitcnt lgkmcnt(0)
	s_barrier
	s_setprio 1
	v_mfma_f32_16x16x32_bf16 v[158:161], v[66:69], v[162:165], v[158:161]
	v_mfma_f32_16x16x32_bf16 v[154:157], v[74:77], v[162:165], v[154:157]
	v_mfma_f32_16x16x32_bf16 v[142:145], v[66:69], v[170:173], v[142:145]
	v_mfma_f32_16x16x32_bf16 v[138:141], v[74:77], v[170:173], v[138:141]
	v_mfma_f32_16x16x32_bf16 v[126:129], v[66:69], v[178:181], v[126:129]
	v_mfma_f32_16x16x32_bf16 v[122:125], v[74:77], v[178:181], v[122:125]
	v_mfma_f32_16x16x32_bf16 v[110:113], v[66:69], v[186:189], v[110:113]
	v_mfma_f32_16x16x32_bf16 v[106:109], v[74:77], v[186:189], v[106:109]
	v_mfma_f32_16x16x32_bf16 v[158:161], v[70:73], v[166:169], v[158:161]
	v_mfma_f32_16x16x32_bf16 v[154:157], v[78:81], v[166:169], v[154:157]
	v_mfma_f32_16x16x32_bf16 v[142:145], v[70:73], v[174:177], v[142:145]
	v_mfma_f32_16x16x32_bf16 v[138:141], v[78:81], v[174:177], v[138:141]
	v_mfma_f32_16x16x32_bf16 v[126:129], v[70:73], v[182:185], v[126:129]
	v_mfma_f32_16x16x32_bf16 v[122:125], v[78:81], v[182:185], v[122:125]
	v_mfma_f32_16x16x32_bf16 v[110:113], v[70:73], v[190:193], v[110:113]
	v_mfma_f32_16x16x32_bf16 v[106:109], v[78:81], v[190:193], v[106:109]
	v_mfma_f32_16x16x32_bf16 v[150:153], v[82:85], v[162:165], v[150:153]
	v_mfma_f32_16x16x32_bf16 v[146:149], v[90:93], v[162:165], v[146:149]
	v_mfma_f32_16x16x32_bf16 v[134:137], v[82:85], v[170:173], v[134:137]
	v_mfma_f32_16x16x32_bf16 v[130:133], v[90:93], v[170:173], v[130:133]
	v_mfma_f32_16x16x32_bf16 v[118:121], v[82:85], v[178:181], v[118:121]
	v_mfma_f32_16x16x32_bf16 v[114:117], v[90:93], v[178:181], v[114:117]
	v_mfma_f32_16x16x32_bf16 v[102:105], v[82:85], v[186:189], v[102:105]
	v_mfma_f32_16x16x32_bf16 v[98:101], v[90:93], v[186:189], v[98:101]
	v_mfma_f32_16x16x32_bf16 v[150:153], v[86:89], v[166:169], v[150:153]
	v_mfma_f32_16x16x32_bf16 v[146:149], v[94:97], v[166:169], v[146:149]
	v_mfma_f32_16x16x32_bf16 v[134:137], v[86:89], v[174:177], v[134:137]
	v_mfma_f32_16x16x32_bf16 v[130:133], v[94:97], v[174:177], v[130:133]
	v_mfma_f32_16x16x32_bf16 v[118:121], v[86:89], v[182:185], v[118:121]
	v_mfma_f32_16x16x32_bf16 v[114:117], v[94:97], v[182:185], v[114:117]
	v_mfma_f32_16x16x32_bf16 v[102:105], v[86:89], v[190:193], v[102:105]
	v_mfma_f32_16x16x32_bf16 v[98:101], v[94:97], v[190:193], v[98:101]
	s_setprio 0
	s_barrier
	s_add_i32 s34, s63, s44
	v_lshl_add_u64 v[194:195], s[42:43], 0, v[210:211]
	s_mov_b32 m0, s34
	ds_read_b128 v[162:165], v244 offset:16384
	ds_read_b128 v[166:169], v244 offset:17408
	ds_read_b128 v[170:173], v244 offset:18432
	ds_read_b128 v[174:177], v244 offset:19456
	ds_read_b128 v[178:181], v244 offset:20480
	ds_read_b128 v[182:185], v244 offset:21504
	ds_read_b128 v[186:189], v244 offset:22528
	ds_read_b128 v[190:193], v244 offset:23552
	global_load_lds_dwordx4 v[194:195], off
	s_add_i32 m0, s34, 0x2000
	s_add_u32 s34, s42, 0x80000
	v_lshl_add_u64 v[196:197], s[42:43], 0, v[216:217]
	s_addc_u32 s35, s43, 0
	s_add_i32 s63, s66, s44
	global_load_lds_dwordx4 v[196:197], off
	v_lshl_add_u64 v[198:199], s[34:35], 0, v[210:211]
	s_mov_b32 m0, s63
	v_lshl_add_u64 v[200:201], s[46:47], 0, v[216:217]
	global_load_lds_dwordx4 v[198:199], off
	v_lshl_add_u64 v[198:199], s[34:35], 0, v[216:217]
	s_add_i32 m0, s63, 0x2000
	s_nop 0
	global_load_lds_dwordx4 v[198:199], off
	v_lshl_add_u64 v[198:199], s[46:47], 0, v[210:211]
	s_mov_b32 m0, s51
	s_nop 0
	global_load_lds_dwordx4 v[198:199], off
	s_mov_b32 m0, s52
	s_nop 0
	global_load_lds_dwordx4 v[200:201], off
	s_waitcnt vmcnt(8)
	s_waitcnt lgkmcnt(0)
	s_barrier
	s_setprio 1
	v_mfma_f32_16x16x32_bf16 v[62:65], v[66:69], v[162:165], v[62:65]
	v_mfma_f32_16x16x32_bf16 v[58:61], v[74:77], v[162:165], v[58:61]
	v_mfma_f32_16x16x32_bf16 v[46:49], v[66:69], v[170:173], v[46:49]
	v_mfma_f32_16x16x32_bf16 v[42:45], v[74:77], v[170:173], v[42:45]
	v_mfma_f32_16x16x32_bf16 v[30:33], v[66:69], v[178:181], v[30:33]
	v_mfma_f32_16x16x32_bf16 v[26:29], v[74:77], v[178:181], v[26:29]
	v_mfma_f32_16x16x32_bf16 v[14:17], v[66:69], v[186:189], v[14:17]
	v_mfma_f32_16x16x32_bf16 v[10:13], v[74:77], v[186:189], v[10:13]
	v_mfma_f32_16x16x32_bf16 v[62:65], v[70:73], v[166:169], v[62:65]
	v_mfma_f32_16x16x32_bf16 v[58:61], v[78:81], v[166:169], v[58:61]
	v_mfma_f32_16x16x32_bf16 v[46:49], v[70:73], v[174:177], v[46:49]
	v_mfma_f32_16x16x32_bf16 v[42:45], v[78:81], v[174:177], v[42:45]
	v_mfma_f32_16x16x32_bf16 v[30:33], v[70:73], v[182:185], v[30:33]
	v_mfma_f32_16x16x32_bf16 v[26:29], v[78:81], v[182:185], v[26:29]
	v_mfma_f32_16x16x32_bf16 v[14:17], v[70:73], v[190:193], v[14:17]
	v_mfma_f32_16x16x32_bf16 v[10:13], v[78:81], v[190:193], v[10:13]
	v_mfma_f32_16x16x32_bf16 v[54:57], v[82:85], v[162:165], v[54:57]
	v_mfma_f32_16x16x32_bf16 v[50:53], v[90:93], v[162:165], v[50:53]
	v_mfma_f32_16x16x32_bf16 v[38:41], v[82:85], v[170:173], v[38:41]
	v_mfma_f32_16x16x32_bf16 v[34:37], v[90:93], v[170:173], v[34:37]
	v_mfma_f32_16x16x32_bf16 v[22:25], v[82:85], v[178:181], v[22:25]
	v_mfma_f32_16x16x32_bf16 v[18:21], v[90:93], v[178:181], v[18:21]
	v_mfma_f32_16x16x32_bf16 v[6:9], v[82:85], v[186:189], v[6:9]
	v_mfma_f32_16x16x32_bf16 v[2:5], v[90:93], v[186:189], v[2:5]
	v_mfma_f32_16x16x32_bf16 v[54:57], v[86:89], v[166:169], v[54:57]
	v_mfma_f32_16x16x32_bf16 v[50:53], v[94:97], v[166:169], v[50:53]
	v_mfma_f32_16x16x32_bf16 v[38:41], v[86:89], v[174:177], v[38:41]
	v_mfma_f32_16x16x32_bf16 v[34:37], v[94:97], v[174:177], v[34:37]
	v_mfma_f32_16x16x32_bf16 v[22:25], v[86:89], v[182:185], v[22:25]
	v_mfma_f32_16x16x32_bf16 v[18:21], v[94:97], v[182:185], v[18:21]
	v_mfma_f32_16x16x32_bf16 v[6:9], v[86:89], v[190:193], v[6:9]
	v_mfma_f32_16x16x32_bf16 v[2:5], v[94:97], v[190:193], v[2:5]
	s_setprio 0
	s_barrier
	s_add_i32 s63, 0, 0x18000
	s_add_i32 s66, 0, 0x1c000
	v_add_u32_e32 v78, s63, v251
	v_add_u32_e32 v94, s66, v251
	ds_read_b128 v[66:69], v78
	ds_read_b128 v[70:73], v78 offset:1024
	ds_read_b128 v[74:77], v78 offset:2048
	ds_read_b128 v[78:81], v78 offset:3072
	ds_read_b128 v[82:85], v94
	ds_read_b128 v[86:89], v94 offset:1024
	ds_read_b128 v[90:93], v94 offset:2048
	ds_read_b128 v[94:97], v94 offset:3072
	s_add_u32 s34, s46, 0x80000
	s_addc_u32 s35, s47, 0
	s_mov_b32 m0, s53
	v_lshl_add_u64 v[202:203], s[34:35], 0, v[210:211]
	ds_read_b128 v[162:165], v244 offset:32768
	ds_read_b128 v[166:169], v244 offset:33792
	ds_read_b128 v[170:173], v244 offset:34816
	ds_read_b128 v[174:177], v244 offset:35840
	ds_read_b128 v[178:181], v244 offset:36864
	ds_read_b128 v[182:185], v244 offset:37888
	ds_read_b128 v[186:189], v244 offset:38912
	ds_read_b128 v[190:193], v244 offset:39936
	global_load_lds_dwordx4 v[202:203], off
	v_lshl_add_u64 v[202:203], s[34:35], 0, v[216:217]
	s_mov_b32 m0, s54
	s_nop 0
	global_load_lds_dwordx4 v[202:203], off
	s_waitcnt vmcnt(8)
	s_waitcnt lgkmcnt(0)
	s_barrier
	s_setprio 1
	v_mfma_f32_16x16x32_bf16 v[158:161], v[66:69], v[162:165], v[158:161]
	v_mfma_f32_16x16x32_bf16 v[154:157], v[74:77], v[162:165], v[154:157]
	v_mfma_f32_16x16x32_bf16 v[142:145], v[66:69], v[170:173], v[142:145]
	v_mfma_f32_16x16x32_bf16 v[138:141], v[74:77], v[170:173], v[138:141]
	v_mfma_f32_16x16x32_bf16 v[126:129], v[66:69], v[178:181], v[126:129]
	v_mfma_f32_16x16x32_bf16 v[122:125], v[74:77], v[178:181], v[122:125]
	v_mfma_f32_16x16x32_bf16 v[110:113], v[66:69], v[186:189], v[110:113]
	v_mfma_f32_16x16x32_bf16 v[106:109], v[74:77], v[186:189], v[106:109]
	v_mfma_f32_16x16x32_bf16 v[158:161], v[70:73], v[166:169], v[158:161]
	v_mfma_f32_16x16x32_bf16 v[154:157], v[78:81], v[166:169], v[154:157]
	v_mfma_f32_16x16x32_bf16 v[142:145], v[70:73], v[174:177], v[142:145]
	v_mfma_f32_16x16x32_bf16 v[138:141], v[78:81], v[174:177], v[138:141]
	v_mfma_f32_16x16x32_bf16 v[126:129], v[70:73], v[182:185], v[126:129]
	v_mfma_f32_16x16x32_bf16 v[122:125], v[78:81], v[182:185], v[122:125]
	v_mfma_f32_16x16x32_bf16 v[110:113], v[70:73], v[190:193], v[110:113]
	v_mfma_f32_16x16x32_bf16 v[106:109], v[78:81], v[190:193], v[106:109]
	v_mfma_f32_16x16x32_bf16 v[150:153], v[82:85], v[162:165], v[150:153]
	v_mfma_f32_16x16x32_bf16 v[146:149], v[90:93], v[162:165], v[146:149]
	v_mfma_f32_16x16x32_bf16 v[134:137], v[82:85], v[170:173], v[134:137]
	v_mfma_f32_16x16x32_bf16 v[130:133], v[90:93], v[170:173], v[130:133]
	v_mfma_f32_16x16x32_bf16 v[118:121], v[82:85], v[178:181], v[118:121]
	v_mfma_f32_16x16x32_bf16 v[114:117], v[90:93], v[178:181], v[114:117]
	v_mfma_f32_16x16x32_bf16 v[102:105], v[82:85], v[186:189], v[102:105]
	v_mfma_f32_16x16x32_bf16 v[98:101], v[90:93], v[186:189], v[98:101]
	v_mfma_f32_16x16x32_bf16 v[150:153], v[86:89], v[166:169], v[150:153]
	v_mfma_f32_16x16x32_bf16 v[146:149], v[94:97], v[166:169], v[146:149]
	v_mfma_f32_16x16x32_bf16 v[134:137], v[86:89], v[174:177], v[134:137]
	v_mfma_f32_16x16x32_bf16 v[130:133], v[94:97], v[174:177], v[130:133]
	v_mfma_f32_16x16x32_bf16 v[118:121], v[86:89], v[182:185], v[118:121]
	v_mfma_f32_16x16x32_bf16 v[114:117], v[94:97], v[182:185], v[114:117]
	v_mfma_f32_16x16x32_bf16 v[102:105], v[86:89], v[190:193], v[102:105]
	v_mfma_f32_16x16x32_bf16 v[98:101], v[94:97], v[190:193], v[98:101]
	s_setprio 0
	s_barrier
	s_add_i32 s34, s63, s44
	v_lshl_add_u64 v[194:195], v[194:195], 0, s[64:65]
	s_mov_b32 m0, s34
	ds_read_b128 v[162:165], v244 offset:49152
	ds_read_b128 v[166:169], v244 offset:50176
	ds_read_b128 v[170:173], v244 offset:51200
	ds_read_b128 v[174:177], v244 offset:52224
	ds_read_b128 v[178:181], v244 offset:53248
	ds_read_b128 v[182:185], v244 offset:54272
	ds_read_b128 v[186:189], v244 offset:55296
	ds_read_b128 v[190:193], v244 offset:56320
	global_load_lds_dwordx4 v[194:195], off
	s_add_i32 m0, s34, 0x2000
	s_add_u32 s34, s42, 0x80080
	v_lshl_add_u64 v[194:195], v[196:197], 0, s[64:65]
	s_addc_u32 s35, s43, 0
	s_add_i32 s42, s66, s44
	global_load_lds_dwordx4 v[194:195], off
	v_lshl_add_u64 v[194:195], s[34:35], 0, v[210:211]
	s_mov_b32 m0, s42
	s_nop 0
	global_load_lds_dwordx4 v[194:195], off
	v_lshl_add_u64 v[194:195], s[34:35], 0, v[216:217]
	s_add_i32 m0, s42, 0x2000
	s_nop 0
	global_load_lds_dwordx4 v[194:195], off
	v_lshl_add_u64 v[194:195], v[198:199], 0, s[64:65]
	s_mov_b32 m0, s55
	s_nop 0
	global_load_lds_dwordx4 v[194:195], off
	v_lshl_add_u64 v[194:195], v[200:201], 0, s[64:65]
	s_mov_b32 m0, s56
	s_nop 0
	global_load_lds_dwordx4 v[194:195], off
	s_waitcnt vmcnt(8)
	s_waitcnt lgkmcnt(0)
	s_barrier
	s_setprio 1
	v_mfma_f32_16x16x32_bf16 v[62:65], v[66:69], v[162:165], v[62:65]
	v_mfma_f32_16x16x32_bf16 v[58:61], v[74:77], v[162:165], v[58:61]
	v_mfma_f32_16x16x32_bf16 v[46:49], v[66:69], v[170:173], v[46:49]
	v_mfma_f32_16x16x32_bf16 v[42:45], v[74:77], v[170:173], v[42:45]
	v_mfma_f32_16x16x32_bf16 v[30:33], v[66:69], v[178:181], v[30:33]
	v_mfma_f32_16x16x32_bf16 v[26:29], v[74:77], v[178:181], v[26:29]
	v_mfma_f32_16x16x32_bf16 v[14:17], v[66:69], v[186:189], v[14:17]
	v_mfma_f32_16x16x32_bf16 v[10:13], v[74:77], v[186:189], v[10:13]
	v_mfma_f32_16x16x32_bf16 v[62:65], v[70:73], v[166:169], v[62:65]
	v_mfma_f32_16x16x32_bf16 v[58:61], v[78:81], v[166:169], v[58:61]
	v_mfma_f32_16x16x32_bf16 v[46:49], v[70:73], v[174:177], v[46:49]
	v_mfma_f32_16x16x32_bf16 v[42:45], v[78:81], v[174:177], v[42:45]
	v_mfma_f32_16x16x32_bf16 v[30:33], v[70:73], v[182:185], v[30:33]
	v_mfma_f32_16x16x32_bf16 v[26:29], v[78:81], v[182:185], v[26:29]
	v_mfma_f32_16x16x32_bf16 v[14:17], v[70:73], v[190:193], v[14:17]
	v_mfma_f32_16x16x32_bf16 v[10:13], v[78:81], v[190:193], v[10:13]
	v_mfma_f32_16x16x32_bf16 v[54:57], v[82:85], v[162:165], v[54:57]
	v_mfma_f32_16x16x32_bf16 v[50:53], v[90:93], v[162:165], v[50:53]
	v_mfma_f32_16x16x32_bf16 v[38:41], v[82:85], v[170:173], v[38:41]
	v_mfma_f32_16x16x32_bf16 v[34:37], v[90:93], v[170:173], v[34:37]
	v_mfma_f32_16x16x32_bf16 v[22:25], v[82:85], v[178:181], v[22:25]
	v_mfma_f32_16x16x32_bf16 v[18:21], v[90:93], v[178:181], v[18:21]
	v_mfma_f32_16x16x32_bf16 v[6:9], v[82:85], v[186:189], v[6:9]
	v_mfma_f32_16x16x32_bf16 v[2:5], v[90:93], v[186:189], v[2:5]
	v_mfma_f32_16x16x32_bf16 v[54:57], v[86:89], v[166:169], v[54:57]
	v_mfma_f32_16x16x32_bf16 v[50:53], v[94:97], v[166:169], v[50:53]
	v_mfma_f32_16x16x32_bf16 v[38:41], v[86:89], v[174:177], v[38:41]
	v_mfma_f32_16x16x32_bf16 v[34:37], v[94:97], v[174:177], v[34:37]
	v_mfma_f32_16x16x32_bf16 v[22:25], v[86:89], v[182:185], v[22:25]
	v_mfma_f32_16x16x32_bf16 v[18:21], v[94:97], v[182:185], v[18:21]
	v_mfma_f32_16x16x32_bf16 v[6:9], v[86:89], v[190:193], v[6:9]
	v_mfma_f32_16x16x32_bf16 v[2:5], v[94:97], v[190:193], v[2:5]
	s_setprio 0
	s_barrier
	s_add_i32 s62, s62, 2
	s_add_u32 s60, s60, 0x100
	s_addc_u32 s61, s61, 0
	s_cmp_gt_u32 s62, 29
	s_mov_b64 s[34:35], s[10:11]
	s_cbranch_scc0 .LBB0_956
	s_and_b64 vcc, exec, s[26:27]
	s_cbranch_vccz .LBB0_959
	s_barrier

.LBB0_1091:
	s_add_u32 s30, s26, 0xfff80080
	s_addc_u32 s31, s27, -1
	s_add_i32 s51, 0, 0x10000
	s_cmp_eq_u32 s50, 28
	s_cselect_b32 s35, s2, s31
	s_cselect_b32 s34, s3, s30
	s_cselect_b32 s31, s19, s49
	s_cselect_b32 s30, s21, s48
	s_add_i32 s54, 0, 0x14000
	v_add_u32_e32 v142, s51, v181
	v_add_u32_e32 v158, s54, v181
	ds_read_b128 v[130:133], v142
	ds_read_b128 v[134:137], v142 offset:1024
	ds_read_b128 v[138:141], v142 offset:2048
	ds_read_b128 v[142:145], v142 offset:3072
	ds_read_b128 v[146:149], v158
	ds_read_b128 v[150:153], v158 offset:1024
	ds_read_b128 v[154:157], v158 offset:2048
	ds_read_b128 v[158:161], v158 offset:3072
	v_lshl_add_u64 v[172:173], s[26:27], 0, v[168:169]
	s_add_i32 m0, s41, 0xc000
	ds_read_b128 v[176:179], v195
	ds_read_b128 v[182:185], v195 offset:1024
	ds_read_b128 v[190:193], v195 offset:2048
	ds_read_b128 v[196:199], v195 offset:3072
	ds_read_b128 v[200:203], v195 offset:4096
	ds_read_b128 v[204:207], v195 offset:5120
	ds_read_b128 v[216:219], v195 offset:6144
	ds_read_b128 v[220:223], v195 offset:7168
	global_load_lds_dwordx4 v[172:173], off
	v_lshl_add_u64 v[172:173], s[26:27], 0, v[170:171]
	s_add_i32 m0, s41, 0xe000
	s_nop 0
	global_load_lds_dwordx4 v[172:173], off
	s_waitcnt vmcnt(8)
	s_waitcnt lgkmcnt(0)
	s_barrier
	s_setprio 1
	v_mfma_f32_16x16x32_bf16 v[126:129], v[130:133], v[176:179], v[126:129]
	v_mfma_f32_16x16x32_bf16 v[122:125], v[138:141], v[176:179], v[122:125]
	v_mfma_f32_16x16x32_bf16 v[110:113], v[130:133], v[190:193], v[110:113]
	v_mfma_f32_16x16x32_bf16 v[106:109], v[138:141], v[190:193], v[106:109]
	v_mfma_f32_16x16x32_bf16 v[94:97], v[130:133], v[200:203], v[94:97]
	v_mfma_f32_16x16x32_bf16 v[90:93], v[138:141], v[200:203], v[90:93]
	v_mfma_f32_16x16x32_bf16 v[78:81], v[130:133], v[216:219], v[78:81]
	v_mfma_f32_16x16x32_bf16 v[74:77], v[138:141], v[216:219], v[74:77]
	v_mfma_f32_16x16x32_bf16 v[126:129], v[134:137], v[182:185], v[126:129]
	v_mfma_f32_16x16x32_bf16 v[122:125], v[142:145], v[182:185], v[122:125]
	v_mfma_f32_16x16x32_bf16 v[110:113], v[134:137], v[196:199], v[110:113]
	v_mfma_f32_16x16x32_bf16 v[106:109], v[142:145], v[196:199], v[106:109]
	v_mfma_f32_16x16x32_bf16 v[94:97], v[134:137], v[204:207], v[94:97]
	v_mfma_f32_16x16x32_bf16 v[90:93], v[142:145], v[204:207], v[90:93]
	v_mfma_f32_16x16x32_bf16 v[78:81], v[134:137], v[220:223], v[78:81]
	v_mfma_f32_16x16x32_bf16 v[74:77], v[142:145], v[220:223], v[74:77]
	v_mfma_f32_16x16x32_bf16 v[118:121], v[146:149], v[176:179], v[118:121]
	v_mfma_f32_16x16x32_bf16 v[114:117], v[154:157], v[176:179], v[114:117]
	v_mfma_f32_16x16x32_bf16 v[102:105], v[146:149], v[190:193], v[102:105]
	v_mfma_f32_16x16x32_bf16 v[98:101], v[154:157], v[190:193], v[98:101]
	v_mfma_f32_16x16x32_bf16 v[86:89], v[146:149], v[200:203], v[86:89]
	v_mfma_f32_16x16x32_bf16 v[82:85], v[154:157], v[200:203], v[82:85]
	v_mfma_f32_16x16x32_bf16 v[70:73], v[146:149], v[216:219], v[70:73]
	v_mfma_f32_16x16x32_bf16 v[66:69], v[154:157], v[216:219], v[66:69]
	v_mfma_f32_16x16x32_bf16 v[118:121], v[150:153], v[182:185], v[118:121]
	v_mfma_f32_16x16x32_bf16 v[114:117], v[158:161], v[182:185], v[114:117]
	v_mfma_f32_16x16x32_bf16 v[102:105], v[150:153], v[196:199], v[102:105]
	v_mfma_f32_16x16x32_bf16 v[98:101], v[158:161], v[196:199], v[98:101]
	v_mfma_f32_16x16x32_bf16 v[86:89], v[150:153], v[204:207], v[86:89]
	v_mfma_f32_16x16x32_bf16 v[82:85], v[158:161], v[204:207], v[82:85]
	v_mfma_f32_16x16x32_bf16 v[70:73], v[150:153], v[220:223], v[70:73]
	v_mfma_f32_16x16x32_bf16 v[66:69], v[158:161], v[220:223], v[66:69]
	s_setprio 0
	s_barrier
	s_add_i32 s51, s51, s40
	v_lshl_add_u64 v[172:173], s[30:31], 0, v[210:211]
	s_mov_b32 m0, s51
	ds_read_b128 v[176:179], v195 offset:16384
	ds_read_b128 v[182:185], v195 offset:17408
	ds_read_b128 v[190:193], v195 offset:18432
	ds_read_b128 v[196:199], v195 offset:19456
	ds_read_b128 v[200:203], v195 offset:20480
	ds_read_b128 v[204:207], v195 offset:21504
	ds_read_b128 v[216:219], v195 offset:22528
	ds_read_b128 v[220:223], v195 offset:23552
	global_load_lds_dwordx4 v[172:173], off
	s_add_i32 m0, s51, 0x2000
	s_add_u32 s52, s30, 0x80000
	v_lshl_add_u64 v[186:187], s[30:31], 0, v[162:163]
	s_addc_u32 s53, s31, 0
	s_add_i32 s51, s54, s40
	global_load_lds_dwordx4 v[186:187], off
	v_lshl_add_u64 v[208:209], s[52:53], 0, v[210:211]
	s_mov_b32 m0, s51
	v_lshl_add_u64 v[212:213], s[34:35], 0, v[164:165]
	global_load_lds_dwordx4 v[208:209], off
	v_lshl_add_u64 v[208:209], s[52:53], 0, v[162:163]
	s_add_i32 m0, s51, 0x2000
	s_nop 0
	global_load_lds_dwordx4 v[208:209], off
	v_lshl_add_u64 v[208:209], s[34:35], 0, v[166:167]
	s_mov_b32 m0, s41
	s_nop 0
	global_load_lds_dwordx4 v[208:209], off
	s_mov_b32 m0, s42
	s_nop 0
	global_load_lds_dwordx4 v[212:213], off
	s_waitcnt vmcnt(8)
	s_waitcnt lgkmcnt(0)
	s_barrier
	s_setprio 1
	v_mfma_f32_16x16x32_bf16 v[62:65], v[130:133], v[176:179], v[62:65]
	v_mfma_f32_16x16x32_bf16 v[58:61], v[138:141], v[176:179], v[58:61]
	v_mfma_f32_16x16x32_bf16 v[46:49], v[130:133], v[190:193], v[46:49]
	v_mfma_f32_16x16x32_bf16 v[42:45], v[138:141], v[190:193], v[42:45]
	v_mfma_f32_16x16x32_bf16 v[30:33], v[130:133], v[200:203], v[30:33]
	v_mfma_f32_16x16x32_bf16 v[26:29], v[138:141], v[200:203], v[26:29]
	v_mfma_f32_16x16x32_bf16 v[14:17], v[130:133], v[216:219], v[14:17]
	v_mfma_f32_16x16x32_bf16 v[10:13], v[138:141], v[216:219], v[10:13]
	v_mfma_f32_16x16x32_bf16 v[62:65], v[134:137], v[182:185], v[62:65]
	v_mfma_f32_16x16x32_bf16 v[58:61], v[142:145], v[182:185], v[58:61]
	v_mfma_f32_16x16x32_bf16 v[46:49], v[134:137], v[196:199], v[46:49]
	v_mfma_f32_16x16x32_bf16 v[42:45], v[142:145], v[196:199], v[42:45]
	v_mfma_f32_16x16x32_bf16 v[30:33], v[134:137], v[204:207], v[30:33]
	v_mfma_f32_16x16x32_bf16 v[26:29], v[142:145], v[204:207], v[26:29]
	v_mfma_f32_16x16x32_bf16 v[14:17], v[134:137], v[220:223], v[14:17]
	v_mfma_f32_16x16x32_bf16 v[10:13], v[142:145], v[220:223], v[10:13]
	v_mfma_f32_16x16x32_bf16 v[54:57], v[146:149], v[176:179], v[54:57]
	v_mfma_f32_16x16x32_bf16 v[50:53], v[154:157], v[176:179], v[50:53]
	v_mfma_f32_16x16x32_bf16 v[38:41], v[146:149], v[190:193], v[38:41]
	v_mfma_f32_16x16x32_bf16 v[34:37], v[154:157], v[190:193], v[34:37]
	v_mfma_f32_16x16x32_bf16 v[22:25], v[146:149], v[200:203], v[22:25]
	v_mfma_f32_16x16x32_bf16 v[18:21], v[154:157], v[200:203], v[18:21]
	v_mfma_f32_16x16x32_bf16 v[6:9], v[146:149], v[216:219], v[6:9]
	v_mfma_f32_16x16x32_bf16 v[2:5], v[154:157], v[216:219], v[2:5]
	v_mfma_f32_16x16x32_bf16 v[54:57], v[150:153], v[182:185], v[54:57]
	v_mfma_f32_16x16x32_bf16 v[50:53], v[158:161], v[182:185], v[50:53]
	v_mfma_f32_16x16x32_bf16 v[38:41], v[150:153], v[196:199], v[38:41]
	v_mfma_f32_16x16x32_bf16 v[34:37], v[158:161], v[196:199], v[34:37]
	v_mfma_f32_16x16x32_bf16 v[22:25], v[150:153], v[204:207], v[22:25]
	v_mfma_f32_16x16x32_bf16 v[18:21], v[158:161], v[204:207], v[18:21]
	v_mfma_f32_16x16x32_bf16 v[6:9], v[150:153], v[220:223], v[6:9]
	v_mfma_f32_16x16x32_bf16 v[2:5], v[158:161], v[220:223], v[2:5]
	s_setprio 0
	s_barrier
	s_add_i32 s51, 0, 0x18000
	s_add_i32 s52, 0, 0x1c000
	v_add_u32_e32 v142, s51, v181
	v_add_u32_e32 v158, s52, v181
	ds_read_b128 v[130:133], v142
	ds_read_b128 v[134:137], v142 offset:1024
	ds_read_b128 v[138:141], v142 offset:2048
	ds_read_b128 v[142:145], v142 offset:3072
	ds_read_b128 v[146:149], v158
	ds_read_b128 v[150:153], v158 offset:1024
	ds_read_b128 v[154:157], v158 offset:2048
	ds_read_b128 v[158:161], v158 offset:3072
	s_add_u32 s34, s34, 0x80000
	s_addc_u32 s35, s35, 0
	s_mov_b32 m0, s43
	v_lshl_add_u64 v[214:215], s[34:35], 0, v[166:167]
	ds_read_b128 v[176:179], v195 offset:32768
	ds_read_b128 v[182:185], v195 offset:33792
	ds_read_b128 v[190:193], v195 offset:34816
	ds_read_b128 v[196:199], v195 offset:35840
	ds_read_b128 v[200:203], v195 offset:36864
	ds_read_b128 v[204:207], v195 offset:37888
	ds_read_b128 v[216:219], v195 offset:38912
	ds_read_b128 v[220:223], v195 offset:39936
	global_load_lds_dwordx4 v[214:215], off
	v_lshl_add_u64 v[214:215], s[34:35], 0, v[164:165]
	s_mov_b32 m0, s44
	s_nop 0
	global_load_lds_dwordx4 v[214:215], off
	s_waitcnt vmcnt(8)
	s_waitcnt lgkmcnt(0)
	s_barrier
	s_setprio 1
	v_mfma_f32_16x16x32_bf16 v[126:129], v[130:133], v[176:179], v[126:129]
	v_mfma_f32_16x16x32_bf16 v[122:125], v[138:141], v[176:179], v[122:125]
	v_mfma_f32_16x16x32_bf16 v[110:113], v[130:133], v[190:193], v[110:113]
	v_mfma_f32_16x16x32_bf16 v[106:109], v[138:141], v[190:193], v[106:109]
	v_mfma_f32_16x16x32_bf16 v[94:97], v[130:133], v[200:203], v[94:97]
	v_mfma_f32_16x16x32_bf16 v[90:93], v[138:141], v[200:203], v[90:93]
	v_mfma_f32_16x16x32_bf16 v[78:81], v[130:133], v[216:219], v[78:81]
	v_mfma_f32_16x16x32_bf16 v[74:77], v[138:141], v[216:219], v[74:77]
	v_mfma_f32_16x16x32_bf16 v[126:129], v[134:137], v[182:185], v[126:129]
	v_mfma_f32_16x16x32_bf16 v[122:125], v[142:145], v[182:185], v[122:125]
	v_mfma_f32_16x16x32_bf16 v[110:113], v[134:137], v[196:199], v[110:113]
	v_mfma_f32_16x16x32_bf16 v[106:109], v[142:145], v[196:199], v[106:109]
	v_mfma_f32_16x16x32_bf16 v[94:97], v[134:137], v[204:207], v[94:97]
	v_mfma_f32_16x16x32_bf16 v[90:93], v[142:145], v[204:207], v[90:93]
	v_mfma_f32_16x16x32_bf16 v[78:81], v[134:137], v[220:223], v[78:81]
	v_mfma_f32_16x16x32_bf16 v[74:77], v[142:145], v[220:223], v[74:77]
	v_mfma_f32_16x16x32_bf16 v[118:121], v[146:149], v[176:179], v[118:121]
	v_mfma_f32_16x16x32_bf16 v[114:117], v[154:157], v[176:179], v[114:117]
	v_mfma_f32_16x16x32_bf16 v[102:105], v[146:149], v[190:193], v[102:105]
	v_mfma_f32_16x16x32_bf16 v[98:101], v[154:157], v[190:193], v[98:101]
	v_mfma_f32_16x16x32_bf16 v[86:89], v[146:149], v[200:203], v[86:89]
	v_mfma_f32_16x16x32_bf16 v[82:85], v[154:157], v[200:203], v[82:85]
	v_mfma_f32_16x16x32_bf16 v[70:73], v[146:149], v[216:219], v[70:73]
	v_mfma_f32_16x16x32_bf16 v[66:69], v[154:157], v[216:219], v[66:69]
	v_mfma_f32_16x16x32_bf16 v[118:121], v[150:153], v[182:185], v[118:121]
	v_mfma_f32_16x16x32_bf16 v[114:117], v[158:161], v[182:185], v[114:117]
	v_mfma_f32_16x16x32_bf16 v[102:105], v[150:153], v[196:199], v[102:105]
	v_mfma_f32_16x16x32_bf16 v[98:101], v[158:161], v[196:199], v[98:101]
	v_mfma_f32_16x16x32_bf16 v[86:89], v[150:153], v[204:207], v[86:89]
	v_mfma_f32_16x16x32_bf16 v[82:85], v[158:161], v[204:207], v[82:85]
	v_mfma_f32_16x16x32_bf16 v[70:73], v[150:153], v[220:223], v[70:73]
	v_mfma_f32_16x16x32_bf16 v[66:69], v[158:161], v[220:223], v[66:69]
	s_setprio 0
	s_barrier
	s_add_i32 s34, s51, s40
	v_lshl_add_u64 v[172:173], v[172:173], 0, s[64:65]
	s_mov_b32 m0, s34
	ds_read_b128 v[176:179], v195 offset:49152
	ds_read_b128 v[182:185], v195 offset:50176
	ds_read_b128 v[190:193], v195 offset:51200
	ds_read_b128 v[196:199], v195 offset:52224
	ds_read_b128 v[200:203], v195 offset:53248
	ds_read_b128 v[204:207], v195 offset:54272
	ds_read_b128 v[216:219], v195 offset:55296
	ds_read_b128 v[220:223], v195 offset:56320
	global_load_lds_dwordx4 v[172:173], off
	s_add_i32 m0, s34, 0x2000
	s_add_u32 s30, s30, 0x80080
	v_lshl_add_u64 v[172:173], v[186:187], 0, s[64:65]
	s_addc_u32 s31, s31, 0
	s_add_i32 s34, s52, s40
	global_load_lds_dwordx4 v[172:173], off
	v_lshl_add_u64 v[172:173], s[30:31], 0, v[210:211]
	s_mov_b32 m0, s34
	s_nop 0
	global_load_lds_dwordx4 v[172:173], off
	v_lshl_add_u64 v[172:173], s[30:31], 0, v[162:163]
	s_add_i32 m0, s34, 0x2000
	s_nop 0
	global_load_lds_dwordx4 v[172:173], off
	v_lshl_add_u64 v[172:173], v[208:209], 0, s[64:65]
	s_mov_b32 m0, s45
	s_nop 0
	global_load_lds_dwordx4 v[172:173], off
	v_lshl_add_u64 v[172:173], v[212:213], 0, s[64:65]
	s_mov_b32 m0, s46
	s_nop 0
	global_load_lds_dwordx4 v[172:173], off
	s_waitcnt vmcnt(8)
	s_waitcnt lgkmcnt(0)
	s_barrier
	s_setprio 1
	v_mfma_f32_16x16x32_bf16 v[62:65], v[130:133], v[176:179], v[62:65]
	v_mfma_f32_16x16x32_bf16 v[58:61], v[138:141], v[176:179], v[58:61]
	v_mfma_f32_16x16x32_bf16 v[46:49], v[130:133], v[190:193], v[46:49]
	v_mfma_f32_16x16x32_bf16 v[42:45], v[138:141], v[190:193], v[42:45]
	v_mfma_f32_16x16x32_bf16 v[30:33], v[130:133], v[200:203], v[30:33]
	v_mfma_f32_16x16x32_bf16 v[26:29], v[138:141], v[200:203], v[26:29]
	v_mfma_f32_16x16x32_bf16 v[14:17], v[130:133], v[216:219], v[14:17]
	v_mfma_f32_16x16x32_bf16 v[10:13], v[138:141], v[216:219], v[10:13]
	v_mfma_f32_16x16x32_bf16 v[62:65], v[134:137], v[182:185], v[62:65]
	v_mfma_f32_16x16x32_bf16 v[58:61], v[142:145], v[182:185], v[58:61]
	v_mfma_f32_16x16x32_bf16 v[46:49], v[134:137], v[196:199], v[46:49]
	v_mfma_f32_16x16x32_bf16 v[42:45], v[142:145], v[196:199], v[42:45]
	v_mfma_f32_16x16x32_bf16 v[30:33], v[134:137], v[204:207], v[30:33]
	v_mfma_f32_16x16x32_bf16 v[26:29], v[142:145], v[204:207], v[26:29]
	v_mfma_f32_16x16x32_bf16 v[14:17], v[134:137], v[220:223], v[14:17]
	v_mfma_f32_16x16x32_bf16 v[10:13], v[142:145], v[220:223], v[10:13]
	v_mfma_f32_16x16x32_bf16 v[54:57], v[146:149], v[176:179], v[54:57]
	v_mfma_f32_16x16x32_bf16 v[50:53], v[154:157], v[176:179], v[50:53]
	v_mfma_f32_16x16x32_bf16 v[38:41], v[146:149], v[190:193], v[38:41]
	v_mfma_f32_16x16x32_bf16 v[34:37], v[154:157], v[190:193], v[34:37]
	v_mfma_f32_16x16x32_bf16 v[22:25], v[146:149], v[200:203], v[22:25]
	v_mfma_f32_16x16x32_bf16 v[18:21], v[154:157], v[200:203], v[18:21]
	v_mfma_f32_16x16x32_bf16 v[6:9], v[146:149], v[216:219], v[6:9]
	v_mfma_f32_16x16x32_bf16 v[2:5], v[154:157], v[216:219], v[2:5]
	v_mfma_f32_16x16x32_bf16 v[54:57], v[150:153], v[182:185], v[54:57]
	v_mfma_f32_16x16x32_bf16 v[50:53], v[158:161], v[182:185], v[50:53]
	v_mfma_f32_16x16x32_bf16 v[38:41], v[150:153], v[196:199], v[38:41]
	v_mfma_f32_16x16x32_bf16 v[34:37], v[158:161], v[196:199], v[34:37]
	v_mfma_f32_16x16x32_bf16 v[22:25], v[150:153], v[204:207], v[22:25]
	v_mfma_f32_16x16x32_bf16 v[18:21], v[158:161], v[204:207], v[18:21]
	v_mfma_f32_16x16x32_bf16 v[6:9], v[150:153], v[220:223], v[6:9]
	v_mfma_f32_16x16x32_bf16 v[2:5], v[158:161], v[220:223], v[2:5]
	s_setprio 0
	s_barrier
	s_add_i32 s50, s50, 2
	s_add_u32 s26, s26, 0x100
	s_addc_u32 s27, s27, 0
	s_add_u32 s48, s48, 0x100
	s_addc_u32 s49, s49, 0
	s_cmp_gt_u32 s50, 29
	s_cbranch_scc0 .LBB0_1091
	v_readlane_b32 s50, v254, 38
	s_and_b64 vcc, exec, s[16:17]
	v_readlane_b32 s51, v254, 39
	s_cbranch_vccz .LBB0_1094
	s_barrier

.LBB0_1180:
	s_add_u32 s36, s34, 0x100
	s_addc_u32 s37, s35, 0
	s_add_i32 s57, 0, 0x10000
	s_cmpk_eq_i32 s56, 0x7c
	s_cselect_b32 s41, s2, s37
	s_cselect_b32 s40, s3, s36
	s_cselect_b32 s39, s23, s55
	s_cselect_b32 s38, s25, s54
	s_add_i32 s58, 0, 0x14000
	v_add_u32_e32 v78, s57, v233
	v_add_u32_e32 v98, s58, v233
	ds_read_b128 v[66:69], v78
	ds_read_b128 v[70:73], v78 offset:1024
	ds_read_b128 v[74:77], v78 offset:2048
	ds_read_b128 v[78:81], v78 offset:3072
	ds_read_b128 v[82:85], v98
	ds_read_b128 v[86:89], v98 offset:1024
	ds_read_b128 v[94:97], v98 offset:2048
	ds_read_b128 v[98:101], v98 offset:3072
	v_lshl_add_u64 v[200:201], s[34:35], 0, v[196:197]
	s_add_i32 m0, s47, 0xc000
	ds_read_b128 v[162:165], v235
	ds_read_b128 v[166:169], v235 offset:1024
	ds_read_b128 v[170:173], v235 offset:2048
	ds_read_b128 v[174:177], v235 offset:3072
	ds_read_b128 v[178:181], v235 offset:4096
	ds_read_b128 v[182:185], v235 offset:5120
	ds_read_b128 v[186:189], v235 offset:6144
	ds_read_b128 v[190:193], v235 offset:7168
	global_load_lds_dwordx4 v[200:201], off
	v_lshl_add_u64 v[200:201], s[34:35], 0, v[198:199]
	s_add_i32 m0, s47, 0xe000
	s_nop 0
	global_load_lds_dwordx4 v[200:201], off
	s_waitcnt vmcnt(8)
	s_waitcnt lgkmcnt(0)
	s_barrier
	s_setprio 1
	v_mfma_f32_16x16x32_bf16 v[158:161], v[66:69], v[162:165], v[158:161]
	v_mfma_f32_16x16x32_bf16 v[154:157], v[74:77], v[162:165], v[154:157]
	v_mfma_f32_16x16x32_bf16 v[142:145], v[66:69], v[170:173], v[142:145]
	v_mfma_f32_16x16x32_bf16 v[138:141], v[74:77], v[170:173], v[138:141]
	v_mfma_f32_16x16x32_bf16 v[126:129], v[66:69], v[178:181], v[126:129]
	v_mfma_f32_16x16x32_bf16 v[122:125], v[74:77], v[178:181], v[122:125]
	v_mfma_f32_16x16x32_bf16 v[110:113], v[66:69], v[186:189], v[110:113]
	v_mfma_f32_16x16x32_bf16 v[106:109], v[74:77], v[186:189], v[106:109]
	v_mfma_f32_16x16x32_bf16 v[158:161], v[70:73], v[166:169], v[158:161]
	v_mfma_f32_16x16x32_bf16 v[154:157], v[78:81], v[166:169], v[154:157]
	v_mfma_f32_16x16x32_bf16 v[142:145], v[70:73], v[174:177], v[142:145]
	v_mfma_f32_16x16x32_bf16 v[138:141], v[78:81], v[174:177], v[138:141]
	v_mfma_f32_16x16x32_bf16 v[126:129], v[70:73], v[182:185], v[126:129]
	v_mfma_f32_16x16x32_bf16 v[122:125], v[78:81], v[182:185], v[122:125]
	v_mfma_f32_16x16x32_bf16 v[110:113], v[70:73], v[190:193], v[110:113]
	v_mfma_f32_16x16x32_bf16 v[106:109], v[78:81], v[190:193], v[106:109]
	v_mfma_f32_16x16x32_bf16 v[150:153], v[82:85], v[162:165], v[150:153]
	v_mfma_f32_16x16x32_bf16 v[146:149], v[94:97], v[162:165], v[146:149]
	v_mfma_f32_16x16x32_bf16 v[134:137], v[82:85], v[170:173], v[134:137]
	v_mfma_f32_16x16x32_bf16 v[130:133], v[94:97], v[170:173], v[130:133]
	v_mfma_f32_16x16x32_bf16 v[118:121], v[82:85], v[178:181], v[118:121]
	v_mfma_f32_16x16x32_bf16 v[114:117], v[94:97], v[178:181], v[114:117]
	v_mfma_f32_16x16x32_bf16 v[102:105], v[82:85], v[186:189], v[102:105]
	v_mfma_f32_16x16x32_bf16 v[90:93], v[94:97], v[186:189], v[90:93]
	v_mfma_f32_16x16x32_bf16 v[150:153], v[86:89], v[166:169], v[150:153]
	v_mfma_f32_16x16x32_bf16 v[146:149], v[98:101], v[166:169], v[146:149]
	v_mfma_f32_16x16x32_bf16 v[134:137], v[86:89], v[174:177], v[134:137]
	v_mfma_f32_16x16x32_bf16 v[130:133], v[98:101], v[174:177], v[130:133]
	v_mfma_f32_16x16x32_bf16 v[118:121], v[86:89], v[182:185], v[118:121]
	v_mfma_f32_16x16x32_bf16 v[114:117], v[98:101], v[182:185], v[114:117]
	v_mfma_f32_16x16x32_bf16 v[102:105], v[86:89], v[190:193], v[102:105]
	v_mfma_f32_16x16x32_bf16 v[90:93], v[98:101], v[190:193], v[90:93]
	s_setprio 0
	s_barrier
	s_add_i32 s34, s57, s46
	v_lshl_add_u64 v[200:201], s[38:39], 0, v[210:211]
	s_mov_b32 m0, s34
	ds_read_b128 v[162:165], v235 offset:16384
	ds_read_b128 v[166:169], v235 offset:17408
	ds_read_b128 v[170:173], v235 offset:18432
	ds_read_b128 v[174:177], v235 offset:19456
	ds_read_b128 v[178:181], v235 offset:20480
	ds_read_b128 v[182:185], v235 offset:21504
	ds_read_b128 v[186:189], v235 offset:22528
	ds_read_b128 v[190:193], v235 offset:23552
	global_load_lds_dwordx4 v[200:201], off
	s_add_i32 m0, s34, 0x2000
	s_add_u32 s34, s38, 0x200000
	v_lshl_add_u64 v[202:203], s[38:39], 0, v[194:195]
	s_addc_u32 s35, s39, 0
	s_add_i32 s57, s58, s46
	global_load_lds_dwordx4 v[202:203], off
	v_lshl_add_u64 v[204:205], s[34:35], 0, v[210:211]
	s_mov_b32 m0, s57
	v_lshl_add_u64 v[206:207], s[40:41], 0, v[194:195]
	global_load_lds_dwordx4 v[204:205], off
	v_lshl_add_u64 v[204:205], s[34:35], 0, v[194:195]
	s_add_i32 m0, s57, 0x2000
	s_nop 0
	global_load_lds_dwordx4 v[204:205], off
	v_lshl_add_u64 v[204:205], s[40:41], 0, v[210:211]
	s_mov_b32 m0, s47
	s_nop 0
	global_load_lds_dwordx4 v[204:205], off
	s_mov_b32 m0, s48
	s_nop 0
	global_load_lds_dwordx4 v[206:207], off
	s_waitcnt vmcnt(8)
	s_waitcnt lgkmcnt(0)
	s_barrier
	s_setprio 1
	v_mfma_f32_16x16x32_bf16 v[62:65], v[66:69], v[162:165], v[62:65]
	v_mfma_f32_16x16x32_bf16 v[58:61], v[74:77], v[162:165], v[58:61]
	v_mfma_f32_16x16x32_bf16 v[46:49], v[66:69], v[170:173], v[46:49]
	v_mfma_f32_16x16x32_bf16 v[42:45], v[74:77], v[170:173], v[42:45]
	v_mfma_f32_16x16x32_bf16 v[30:33], v[66:69], v[178:181], v[30:33]
	v_mfma_f32_16x16x32_bf16 v[26:29], v[74:77], v[178:181], v[26:29]
	v_mfma_f32_16x16x32_bf16 v[14:17], v[66:69], v[186:189], v[14:17]
	v_mfma_f32_16x16x32_bf16 v[10:13], v[74:77], v[186:189], v[10:13]
	v_mfma_f32_16x16x32_bf16 v[62:65], v[70:73], v[166:169], v[62:65]
	v_mfma_f32_16x16x32_bf16 v[58:61], v[78:81], v[166:169], v[58:61]
	v_mfma_f32_16x16x32_bf16 v[46:49], v[70:73], v[174:177], v[46:49]
	v_mfma_f32_16x16x32_bf16 v[42:45], v[78:81], v[174:177], v[42:45]
	v_mfma_f32_16x16x32_bf16 v[30:33], v[70:73], v[182:185], v[30:33]
	v_mfma_f32_16x16x32_bf16 v[26:29], v[78:81], v[182:185], v[26:29]
	v_mfma_f32_16x16x32_bf16 v[14:17], v[70:73], v[190:193], v[14:17]
	v_mfma_f32_16x16x32_bf16 v[10:13], v[78:81], v[190:193], v[10:13]
	v_mfma_f32_16x16x32_bf16 v[54:57], v[82:85], v[162:165], v[54:57]
	v_mfma_f32_16x16x32_bf16 v[50:53], v[94:97], v[162:165], v[50:53]
	v_mfma_f32_16x16x32_bf16 v[38:41], v[82:85], v[170:173], v[38:41]
	v_mfma_f32_16x16x32_bf16 v[34:37], v[94:97], v[170:173], v[34:37]
	v_mfma_f32_16x16x32_bf16 v[22:25], v[82:85], v[178:181], v[22:25]
	v_mfma_f32_16x16x32_bf16 v[18:21], v[94:97], v[178:181], v[18:21]
	v_mfma_f32_16x16x32_bf16 v[6:9], v[82:85], v[186:189], v[6:9]
	v_mfma_f32_16x16x32_bf16 v[2:5], v[94:97], v[186:189], v[2:5]
	v_mfma_f32_16x16x32_bf16 v[54:57], v[86:89], v[166:169], v[54:57]
	v_mfma_f32_16x16x32_bf16 v[50:53], v[98:101], v[166:169], v[50:53]
	v_mfma_f32_16x16x32_bf16 v[38:41], v[86:89], v[174:177], v[38:41]
	v_mfma_f32_16x16x32_bf16 v[34:37], v[98:101], v[174:177], v[34:37]
	v_mfma_f32_16x16x32_bf16 v[22:25], v[86:89], v[182:185], v[22:25]
	v_mfma_f32_16x16x32_bf16 v[18:21], v[98:101], v[182:185], v[18:21]
	v_mfma_f32_16x16x32_bf16 v[6:9], v[86:89], v[190:193], v[6:9]
	v_mfma_f32_16x16x32_bf16 v[2:5], v[98:101], v[190:193], v[2:5]
	s_setprio 0
	s_barrier
	s_add_i32 s57, 0, 0x18000
	s_add_i32 s58, 0, 0x1c000
	v_add_u32_e32 v78, s57, v233
	v_add_u32_e32 v98, s58, v233
	ds_read_b128 v[66:69], v78
	ds_read_b128 v[70:73], v78 offset:1024
	ds_read_b128 v[74:77], v78 offset:2048
	ds_read_b128 v[78:81], v78 offset:3072
	ds_read_b128 v[82:85], v98
	ds_read_b128 v[86:89], v98 offset:1024
	ds_read_b128 v[94:97], v98 offset:2048
	ds_read_b128 v[98:101], v98 offset:3072
	s_add_u32 s34, s40, 0x200000
	s_addc_u32 s35, s41, 0
	s_mov_b32 m0, s49
	v_lshl_add_u64 v[208:209], s[34:35], 0, v[210:211]
	ds_read_b128 v[162:165], v235 offset:32768
	ds_read_b128 v[166:169], v235 offset:33792
	ds_read_b128 v[170:173], v235 offset:34816
	ds_read_b128 v[174:177], v235 offset:35840
	ds_read_b128 v[178:181], v235 offset:36864
	ds_read_b128 v[182:185], v235 offset:37888
	ds_read_b128 v[186:189], v235 offset:38912
	ds_read_b128 v[190:193], v235 offset:39936
	global_load_lds_dwordx4 v[208:209], off
	v_lshl_add_u64 v[208:209], s[34:35], 0, v[194:195]
	s_mov_b32 m0, s50
	s_nop 0
	global_load_lds_dwordx4 v[208:209], off
	s_waitcnt vmcnt(8)
	s_waitcnt lgkmcnt(0)
	s_barrier
	s_setprio 1
	v_mfma_f32_16x16x32_bf16 v[158:161], v[66:69], v[162:165], v[158:161]
	v_mfma_f32_16x16x32_bf16 v[154:157], v[74:77], v[162:165], v[154:157]
	v_mfma_f32_16x16x32_bf16 v[142:145], v[66:69], v[170:173], v[142:145]
	v_mfma_f32_16x16x32_bf16 v[138:141], v[74:77], v[170:173], v[138:141]
	v_mfma_f32_16x16x32_bf16 v[126:129], v[66:69], v[178:181], v[126:129]
	v_mfma_f32_16x16x32_bf16 v[122:125], v[74:77], v[178:181], v[122:125]
	v_mfma_f32_16x16x32_bf16 v[110:113], v[66:69], v[186:189], v[110:113]
	v_mfma_f32_16x16x32_bf16 v[106:109], v[74:77], v[186:189], v[106:109]
	v_mfma_f32_16x16x32_bf16 v[158:161], v[70:73], v[166:169], v[158:161]
	v_mfma_f32_16x16x32_bf16 v[154:157], v[78:81], v[166:169], v[154:157]
	v_mfma_f32_16x16x32_bf16 v[142:145], v[70:73], v[174:177], v[142:145]
	v_mfma_f32_16x16x32_bf16 v[138:141], v[78:81], v[174:177], v[138:141]
	v_mfma_f32_16x16x32_bf16 v[126:129], v[70:73], v[182:185], v[126:129]
	v_mfma_f32_16x16x32_bf16 v[122:125], v[78:81], v[182:185], v[122:125]
	v_mfma_f32_16x16x32_bf16 v[110:113], v[70:73], v[190:193], v[110:113]
	v_mfma_f32_16x16x32_bf16 v[106:109], v[78:81], v[190:193], v[106:109]
	v_mfma_f32_16x16x32_bf16 v[150:153], v[82:85], v[162:165], v[150:153]
	v_mfma_f32_16x16x32_bf16 v[146:149], v[94:97], v[162:165], v[146:149]
	v_mfma_f32_16x16x32_bf16 v[134:137], v[82:85], v[170:173], v[134:137]
	v_mfma_f32_16x16x32_bf16 v[130:133], v[94:97], v[170:173], v[130:133]
	v_mfma_f32_16x16x32_bf16 v[118:121], v[82:85], v[178:181], v[118:121]
	v_mfma_f32_16x16x32_bf16 v[114:117], v[94:97], v[178:181], v[114:117]
	v_mfma_f32_16x16x32_bf16 v[102:105], v[82:85], v[186:189], v[102:105]
	v_mfma_f32_16x16x32_bf16 v[90:93], v[94:97], v[186:189], v[90:93]
	v_mfma_f32_16x16x32_bf16 v[150:153], v[86:89], v[166:169], v[150:153]
	v_mfma_f32_16x16x32_bf16 v[146:149], v[98:101], v[166:169], v[146:149]
	v_mfma_f32_16x16x32_bf16 v[134:137], v[86:89], v[174:177], v[134:137]
	v_mfma_f32_16x16x32_bf16 v[130:133], v[98:101], v[174:177], v[130:133]
	v_mfma_f32_16x16x32_bf16 v[118:121], v[86:89], v[182:185], v[118:121]
	v_mfma_f32_16x16x32_bf16 v[114:117], v[98:101], v[182:185], v[114:117]
	v_mfma_f32_16x16x32_bf16 v[102:105], v[86:89], v[190:193], v[102:105]
	v_mfma_f32_16x16x32_bf16 v[90:93], v[98:101], v[190:193], v[90:93]
	s_setprio 0
	s_barrier
	s_add_i32 s34, s57, s46
	v_lshl_add_u64 v[200:201], v[200:201], 0, s[64:65]
	s_mov_b32 m0, s34
	ds_read_b128 v[162:165], v235 offset:49152
	ds_read_b128 v[166:169], v235 offset:50176
	ds_read_b128 v[170:173], v235 offset:51200
	ds_read_b128 v[174:177], v235 offset:52224
	ds_read_b128 v[178:181], v235 offset:53248
	ds_read_b128 v[182:185], v235 offset:54272
	ds_read_b128 v[186:189], v235 offset:55296
	ds_read_b128 v[190:193], v235 offset:56320
	global_load_lds_dwordx4 v[200:201], off
	s_add_i32 m0, s34, 0x2000
	s_add_u32 s34, s38, 0x200080
	v_lshl_add_u64 v[200:201], v[202:203], 0, s[64:65]
	s_addc_u32 s35, s39, 0
	s_add_i32 s38, s58, s46
	global_load_lds_dwordx4 v[200:201], off
	v_lshl_add_u64 v[200:201], s[34:35], 0, v[210:211]
	s_mov_b32 m0, s38
	s_nop 0
	global_load_lds_dwordx4 v[200:201], off
	v_lshl_add_u64 v[200:201], s[34:35], 0, v[194:195]
	s_add_i32 m0, s38, 0x2000
	s_nop 0
	global_load_lds_dwordx4 v[200:201], off
	v_lshl_add_u64 v[200:201], v[204:205], 0, s[64:65]
	s_mov_b32 m0, s51
	s_nop 0
	global_load_lds_dwordx4 v[200:201], off
	v_lshl_add_u64 v[200:201], v[206:207], 0, s[64:65]
	s_mov_b32 m0, s52
	s_nop 0
	global_load_lds_dwordx4 v[200:201], off
	s_waitcnt vmcnt(8)
	s_waitcnt lgkmcnt(0)
	s_barrier
	s_setprio 1
	v_mfma_f32_16x16x32_bf16 v[62:65], v[66:69], v[162:165], v[62:65]
	v_mfma_f32_16x16x32_bf16 v[58:61], v[74:77], v[162:165], v[58:61]
	v_mfma_f32_16x16x32_bf16 v[46:49], v[66:69], v[170:173], v[46:49]
	v_mfma_f32_16x16x32_bf16 v[42:45], v[74:77], v[170:173], v[42:45]
	v_mfma_f32_16x16x32_bf16 v[30:33], v[66:69], v[178:181], v[30:33]
	v_mfma_f32_16x16x32_bf16 v[26:29], v[74:77], v[178:181], v[26:29]
	v_mfma_f32_16x16x32_bf16 v[14:17], v[66:69], v[186:189], v[14:17]
	v_mfma_f32_16x16x32_bf16 v[10:13], v[74:77], v[186:189], v[10:13]
	v_mfma_f32_16x16x32_bf16 v[62:65], v[70:73], v[166:169], v[62:65]
	v_mfma_f32_16x16x32_bf16 v[58:61], v[78:81], v[166:169], v[58:61]
	v_mfma_f32_16x16x32_bf16 v[46:49], v[70:73], v[174:177], v[46:49]
	v_mfma_f32_16x16x32_bf16 v[42:45], v[78:81], v[174:177], v[42:45]
	v_mfma_f32_16x16x32_bf16 v[30:33], v[70:73], v[182:185], v[30:33]
	v_mfma_f32_16x16x32_bf16 v[26:29], v[78:81], v[182:185], v[26:29]
	v_mfma_f32_16x16x32_bf16 v[14:17], v[70:73], v[190:193], v[14:17]
	v_mfma_f32_16x16x32_bf16 v[10:13], v[78:81], v[190:193], v[10:13]
	v_mfma_f32_16x16x32_bf16 v[54:57], v[82:85], v[162:165], v[54:57]
	v_mfma_f32_16x16x32_bf16 v[50:53], v[94:97], v[162:165], v[50:53]
	v_mfma_f32_16x16x32_bf16 v[38:41], v[82:85], v[170:173], v[38:41]
	v_mfma_f32_16x16x32_bf16 v[34:37], v[94:97], v[170:173], v[34:37]
	v_mfma_f32_16x16x32_bf16 v[22:25], v[82:85], v[178:181], v[22:25]
	v_mfma_f32_16x16x32_bf16 v[18:21], v[94:97], v[178:181], v[18:21]
	v_mfma_f32_16x16x32_bf16 v[6:9], v[82:85], v[186:189], v[6:9]
	v_mfma_f32_16x16x32_bf16 v[2:5], v[94:97], v[186:189], v[2:5]
	v_mfma_f32_16x16x32_bf16 v[54:57], v[86:89], v[166:169], v[54:57]
	v_mfma_f32_16x16x32_bf16 v[50:53], v[98:101], v[166:169], v[50:53]
	v_mfma_f32_16x16x32_bf16 v[38:41], v[86:89], v[174:177], v[38:41]
	v_mfma_f32_16x16x32_bf16 v[34:37], v[98:101], v[174:177], v[34:37]
	v_mfma_f32_16x16x32_bf16 v[22:25], v[86:89], v[182:185], v[22:25]
	v_mfma_f32_16x16x32_bf16 v[18:21], v[98:101], v[182:185], v[18:21]
	v_mfma_f32_16x16x32_bf16 v[6:9], v[86:89], v[190:193], v[6:9]
	v_mfma_f32_16x16x32_bf16 v[2:5], v[98:101], v[190:193], v[2:5]
	s_setprio 0
	s_barrier
	s_add_i32 s56, s56, 2
	s_add_u32 s54, s54, 0x100
	s_addc_u32 s55, s55, 0
	s_cmpk_gt_u32 s56, 0x7d
	s_mov_b64 s[34:35], s[36:37]
	s_cbranch_scc0 .LBB0_1180
	s_and_b64 vcc, exec, s[20:21]
	s_cbranch_vccz .LBB0_1183
	s_barrier
